# v52 minus the s_setprio 0/1 pair between the two 16-MFMA blocks of each MMA segment
# speedup vs baseline: 1.0005x; 1.0005x over previous
; #define PG8_STAGE(bufoff, gbase, voff) do { _Pragma("unroll") for (int _i = 0; _i < 2; ++_i) \
;         __builtin_amdgcn_global_load_lds((const unsigned*)((const char*)(gbase) + (voff)[_i]), (PG8_LAS unsigned*)(lds + (bufoff) + ldsw + _i * 8192), 16, 0, 0); } while (0)
; #define PG8_LDA(dst, b, h) do { _Pragma("unroll") for (int m = 0; m < 4; ++m) _Pragma("unroll") for (int k = 0; k < 2; ++k) dst[m][k] = *(const PG8_LAS bf16x8*)(lds + PG8_SA(b, h) + aoff + m * 2048 + k * 1024); } while (0)
; #define PG8_LDB(dst, b, h) do { _Pragma("unroll") for (int n = 0; n < 2; ++n) _Pragma("unroll") for (int k = 0; k < 2; ++k) dst[n][k] = *(const PG8_LAS bf16x8*)(lds + PG8_SB(b, h) + boff + n * 2048 + k * 1024); } while (0)
; #define PG8_MMA(ai, bj, At, Bt) do { __builtin_amdgcn_s_setprio(1); _Pragma("unroll") for (int m = 0; m < 4; ++m) _Pragma("unroll") for (int n = 0; n < 2; ++n) _Pragma("unroll") for (int k = 0; k < 2; ++k) \
;         acc[ai][bj][m][n] = __builtin_amdgcn_mfma_f32_16x16x32_bf16(Bt[n][k], At[m][k], acc[ai][bj][m][n], 0, 0, 0); __builtin_amdgcn_s_setprio(0); } while (0)
; #define PG8_WAIT_V(n) asm volatile("s_waitcnt vmcnt(" #n ")" ::: "memory")
; #define PG8_WAIT_L(n) asm volatile("s_waitcnt lgkmcnt(" #n ")" ::: "memory")
; template <class Epi, class Sched, bool ALIGN_EPI = false, bool SP2 = false>
; __device__ __forceinline__ void gemm_phase(PG8_LAS unsigned char* lds, const Gemm g, const Sched& S, const Epi& E) {
;     ...
;             const bool last = (t == nt - 2);
;             const char* a1 = cA + (size_t)(t + 1) * kstep;
;             const char* a2 = last ? nA : cA + (size_t)(t + 2) * kstep; const char* b2 = last ? nB : cB + (size_t)(t + 2) * kstep;
;             const char* a3 = a2 + kstep; const char* b3 = b2 + kstep;
;             if (last && has_next) S.a_ready(nxt);
;             if constexpr (SP2) {
;             PG8_LDB(B0, 0, 0); PG8_LDB(B1, 0, 1); PG8_SCHED; PG8_LDA(At, 0, 0); PG8_STAGE(PG8_SA(1, 1), a1 + hstep, voffA);
;             PG8_WAIT_V(8); PG8_WAIT_L(0); PG8_BAR; PG8_MMA(0, 0, At, B0); PG8_MMA(0, 1, At, B1); PG8_BAR; PG8_SCHED;
;             PG8_LDA(At, 0, 1); PG8_STAGE(PG8_SB(0, 0), b2, voffB); PG8_STAGE(PG8_SB(0, 1), b2 + hstep, voffB); PG8_STAGE(PG8_SA(0, 0), a2, voffA);
;             PG8_WAIT_V(8); PG8_WAIT_L(0); PG8_BAR; PG8_MMA(1, 0, At, B0); PG8_MMA(1, 1, At, B1); PG8_BAR; PG8_SCHED;
.LBB0_139:
	ds_read_b128 v[2:5], v187
	ds_read_b128 v[6:9], v187 offset:1024
	ds_read_b128 v[138:141], v187 offset:2048
	ds_read_b128 v[142:145], v187 offset:3072
	ds_read_b128 v[146:149], v197
	ds_read_b128 v[150:153], v197 offset:1024
	ds_read_b128 v[154:157], v197 offset:2048
	ds_read_b128 v[158:161], v197 offset:3072
	s_add_u32 s14, s12, 0xfff00080
	s_addc_u32 s15, s13, -1
	s_cmp_eq_u32 s33, 60
	s_cselect_b32 s17, s2, s15
	s_cselect_b32 s16, s11, s14
	s_cselect_b32 s15, s26, s30
	s_cselect_b32 s14, s28, s29
	v_lshl_add_u64 v[162:163], s[12:13], 0, v[188:189]
	s_add_i32 m0, s27, 0xc000
	ds_read_b128 v[202:205], v199
	ds_read_b128 v[206:209], v199 offset:1024
	ds_read_b128 v[214:217], v199 offset:2048
	ds_read_b128 v[218:221], v199 offset:3072
	ds_read_b128 v[222:225], v199 offset:4096
	ds_read_b128 v[226:229], v199 offset:5120
	ds_read_b128 v[230:233], v199 offset:6144
	ds_read_b128 v[234:237], v199 offset:7168
	global_load_lds_dwordx4 v[162:163], off
	v_lshl_add_u64 v[162:163], s[12:13], 0, v[190:191]
	s_add_i32 m0, s27, 0xe000
	s_nop 0
	global_load_lds_dwordx4 v[162:163], off
	s_waitcnt vmcnt(8)
	s_waitcnt lgkmcnt(0)
	s_setprio 1
	s_barrier
	v_mfma_f32_16x16x32_bf16 v[134:137], v[2:5], v[202:205], v[134:137]
	v_mfma_f32_16x16x32_bf16 v[134:137], v[6:9], v[206:209], v[134:137]
	v_mfma_f32_16x16x32_bf16 v[118:121], v[6:9], v[218:221], v[118:121]
	v_mfma_f32_16x16x32_bf16 v[118:121], v[2:5], v[214:217], v[118:121]
	v_mfma_f32_16x16x32_bf16 v[102:105], v[2:5], v[222:225], v[102:105]
	v_mfma_f32_16x16x32_bf16 v[102:105], v[6:9], v[226:229], v[102:105]
	v_mfma_f32_16x16x32_bf16 v[86:89], v[6:9], v[234:237], v[86:89]
	v_mfma_f32_16x16x32_bf16 v[86:89], v[2:5], v[230:233], v[86:89]
	v_mfma_f32_16x16x32_bf16 v[82:85], v[138:141], v[230:233], v[82:85]
	v_mfma_f32_16x16x32_bf16 v[82:85], v[142:145], v[234:237], v[82:85]
	v_mfma_f32_16x16x32_bf16 v[130:133], v[142:145], v[206:209], v[130:133]
	v_mfma_f32_16x16x32_bf16 v[130:133], v[138:141], v[202:205], v[130:133]
	v_mfma_f32_16x16x32_bf16 v[114:117], v[138:141], v[214:217], v[114:117]
	v_mfma_f32_16x16x32_bf16 v[114:117], v[142:145], v[218:221], v[114:117]
	v_mfma_f32_16x16x32_bf16 v[98:101], v[142:145], v[226:229], v[98:101]
	v_mfma_f32_16x16x32_bf16 v[98:101], v[138:141], v[222:225], v[98:101]
	v_mfma_f32_16x16x32_bf16 v[94:97], v[146:149], v[222:225], v[94:97]
	v_mfma_f32_16x16x32_bf16 v[94:97], v[150:153], v[226:229], v[94:97]
	v_mfma_f32_16x16x32_bf16 v[126:129], v[150:153], v[206:209], v[126:129]
	v_mfma_f32_16x16x32_bf16 v[126:129], v[146:149], v[202:205], v[126:129]
	v_mfma_f32_16x16x32_bf16 v[110:113], v[146:149], v[214:217], v[110:113]
	v_mfma_f32_16x16x32_bf16 v[110:113], v[150:153], v[218:221], v[110:113]
	v_mfma_f32_16x16x32_bf16 v[78:81], v[150:153], v[234:237], v[78:81]
	v_mfma_f32_16x16x32_bf16 v[78:81], v[146:149], v[230:233], v[78:81]
	v_mfma_f32_16x16x32_bf16 v[74:77], v[154:157], v[230:233], v[74:77]
	v_mfma_f32_16x16x32_bf16 v[74:77], v[158:161], v[234:237], v[74:77]
	v_mfma_f32_16x16x32_bf16 v[122:125], v[158:161], v[206:209], v[122:125]
	v_mfma_f32_16x16x32_bf16 v[122:125], v[154:157], v[202:205], v[122:125]
	v_mfma_f32_16x16x32_bf16 v[106:109], v[154:157], v[214:217], v[106:109]
	v_mfma_f32_16x16x32_bf16 v[106:109], v[158:161], v[218:221], v[106:109]
	v_mfma_f32_16x16x32_bf16 v[90:93], v[158:161], v[226:229], v[90:93]
	v_mfma_f32_16x16x32_bf16 v[90:93], v[154:157], v[222:225], v[90:93]
	s_barrier
	s_setprio 0
	s_add_i32 s34, s41, s25
	v_lshl_add_u64 v[162:163], s[14:15], 0, v[168:169]
	s_mov_b32 m0, s34
	ds_read_b128 v[202:205], v199 offset:16384
	ds_read_b128 v[206:209], v199 offset:17408
	ds_read_b128 v[214:217], v199 offset:18432
	ds_read_b128 v[218:221], v199 offset:19456
	ds_read_b128 v[222:225], v199 offset:20480
	ds_read_b128 v[226:229], v199 offset:21504
	ds_read_b128 v[230:233], v199 offset:22528
	ds_read_b128 v[234:237], v199 offset:23552
	global_load_lds_dwordx4 v[162:163], off
	s_add_i32 m0, s34, 0x2000
	s_add_u32 s34, s14, 0x100000
	v_lshl_add_u64 v[210:211], s[14:15], 0, v[172:173]
	s_addc_u32 s35, s15, 0
	s_add_i32 s79, s92, s25
	global_load_lds_dwordx4 v[210:211], off
	v_lshl_add_u64 v[238:239], s[34:35], 0, v[168:169]
	s_mov_b32 m0, s79
	v_lshl_add_u64 v[240:241], s[16:17], 0, v[170:171]
	global_load_lds_dwordx4 v[238:239], off
	v_lshl_add_u64 v[238:239], s[34:35], 0, v[172:173]
	s_add_i32 m0, s79, 0x2000
	s_nop 0
	global_load_lds_dwordx4 v[238:239], off
	v_lshl_add_u64 v[238:239], s[16:17], 0, v[164:165]
	s_mov_b32 m0, s27
	s_nop 0
	global_load_lds_dwordx4 v[238:239], off
	s_mov_b32 m0, s39
	s_nop 0
	global_load_lds_dwordx4 v[240:241], off
	s_waitcnt vmcnt(8)
	s_waitcnt lgkmcnt(0)
	s_setprio 1
	s_barrier
; #define PG8_STAGE(bufoff, gbase, voff) do { _Pragma("unroll") for (int _i = 0; _i < 2; ++_i) \
;         __builtin_amdgcn_global_load_lds((const unsigned*)((const char*)(gbase) + (voff)[_i]), (PG8_LAS unsigned*)(lds + (bufoff) + ldsw + _i * 8192), 16, 0, 0); } while (0)
; #define PG8_LDA(dst, b, h) do { _Pragma("unroll") for (int m = 0; m < 4; ++m) _Pragma("unroll") for (int k = 0; k < 2; ++k) dst[m][k] = *(const PG8_LAS bf16x8*)(lds + PG8_SA(b, h) + aoff + m * 2048 + k * 1024); } while (0)
; #define PG8_LDB(dst, b, h) do { _Pragma("unroll") for (int n = 0; n < 2; ++n) _Pragma("unroll") for (int k = 0; k < 2; ++k) dst[n][k] = *(const PG8_LAS bf16x8*)(lds + PG8_SB(b, h) + boff + n * 2048 + k * 1024); } while (0)
; #define PG8_MMA(ai, bj, At, Bt) do { __builtin_amdgcn_s_setprio(1); _Pragma("unroll") for (int m = 0; m < 4; ++m) _Pragma("unroll") for (int n = 0; n < 2; ++n) _Pragma("unroll") for (int k = 0; k < 2; ++k) \
;         acc[ai][bj][m][n] = __builtin_amdgcn_mfma_f32_16x16x32_bf16(Bt[n][k], At[m][k], acc[ai][bj][m][n], 0, 0, 0); __builtin_amdgcn_s_setprio(0); } while (0)
; #define PG8_WAIT_V(n) asm volatile("s_waitcnt vmcnt(" #n ")" ::: "memory")
; #define PG8_WAIT_L(n) asm volatile("s_waitcnt lgkmcnt(" #n ")" ::: "memory")
; #define PG8_BAR __builtin_amdgcn_s_barrier()
; #define PG8_SCHED __builtin_amdgcn_sched_barrier(0)
; template <class Epi, class Sched, bool ALIGN_EPI = false, bool SP2 = false>
; __device__ __forceinline__ void gemm_phase(PG8_LAS unsigned char* lds, const Gemm g, const Sched& S, const Epi& E) {
;     ...
;             PG8_WAIT_V(8); PG8_WAIT_L(0); PG8_BAR; PG8_MMA(1, 0, At, B0); PG8_MMA(1, 1, At, B1); PG8_BAR; PG8_SCHED;
;             PG8_LDB(B0, 1, 0); PG8_LDB(B1, 1, 1); PG8_SCHED; PG8_LDA(At, 1, 0); PG8_STAGE(PG8_SA(0, 1), a2 + hstep, voffA);
;             PG8_WAIT_V(8); PG8_WAIT_L(0); PG8_BAR; PG8_MMA(0, 0, At, B0); PG8_MMA(0, 1, At, B1); PG8_BAR; PG8_SCHED;
	v_mfma_f32_16x16x32_bf16 v[70:73], v[6:9], v[206:209], v[70:73]
	v_mfma_f32_16x16x32_bf16 v[70:73], v[2:5], v[202:205], v[70:73]
	v_mfma_f32_16x16x32_bf16 v[54:57], v[2:5], v[214:217], v[54:57]
	v_mfma_f32_16x16x32_bf16 v[54:57], v[6:9], v[218:221], v[54:57]
	v_mfma_f32_16x16x32_bf16 v[38:41], v[6:9], v[226:229], v[38:41]
	v_mfma_f32_16x16x32_bf16 v[38:41], v[2:5], v[222:225], v[38:41]
	v_mfma_f32_16x16x32_bf16 v[2:5], v[2:5], v[230:233], v[22:25]
	v_mfma_f32_16x16x32_bf16 v[2:5], v[6:9], v[234:237], v[2:5]
	v_mfma_f32_16x16x32_bf16 v[6:9], v[142:145], v[234:237], v[18:21]
	v_mfma_f32_16x16x32_bf16 v[6:9], v[138:141], v[230:233], v[6:9]
	v_mfma_f32_16x16x32_bf16 v[66:69], v[138:141], v[202:205], v[66:69]
	v_mfma_f32_16x16x32_bf16 v[66:69], v[142:145], v[206:209], v[66:69]
	v_mfma_f32_16x16x32_bf16 v[50:53], v[142:145], v[218:221], v[50:53]
	v_mfma_f32_16x16x32_bf16 v[50:53], v[138:141], v[214:217], v[50:53]
	v_mfma_f32_16x16x32_bf16 v[34:37], v[138:141], v[222:225], v[34:37]
	v_mfma_f32_16x16x32_bf16 v[34:37], v[142:145], v[226:229], v[34:37]
	v_mfma_f32_16x16x32_bf16 v[18:21], v[150:153], v[226:229], v[30:33]
	v_mfma_f32_16x16x32_bf16 v[30:33], v[146:149], v[222:225], v[18:21]
	v_mfma_f32_16x16x32_bf16 v[14:17], v[146:149], v[230:233], v[14:17]
	v_mfma_f32_16x16x32_bf16 v[14:17], v[150:153], v[234:237], v[14:17]
	v_mfma_f32_16x16x32_bf16 v[18:21], v[150:153], v[206:209], v[62:65]
	v_mfma_f32_16x16x32_bf16 v[62:65], v[146:149], v[202:205], v[18:21]
	v_mfma_f32_16x16x32_bf16 v[18:21], v[146:149], v[214:217], v[46:49]
	v_mfma_f32_16x16x32_bf16 v[46:49], v[150:153], v[218:221], v[18:21]
	v_mfma_f32_16x16x32_bf16 v[18:21], v[158:161], v[218:221], v[42:45]
	v_mfma_f32_16x16x32_bf16 v[42:45], v[154:157], v[214:217], v[18:21]
	v_mfma_f32_16x16x32_bf16 v[18:21], v[154:157], v[222:225], v[26:29]
	v_mfma_f32_16x16x32_bf16 v[26:29], v[158:161], v[226:229], v[18:21]
	v_mfma_f32_16x16x32_bf16 v[10:13], v[158:161], v[234:237], v[10:13]
	v_mfma_f32_16x16x32_bf16 v[10:13], v[154:157], v[230:233], v[10:13]
	v_mfma_f32_16x16x32_bf16 v[18:21], v[154:157], v[202:205], v[58:61]
	v_mfma_f32_16x16x32_bf16 v[58:61], v[158:161], v[206:209], v[18:21]
	s_barrier
	s_setprio 0
	s_add_i32 s34, 0, 0x18000
	s_add_i32 s35, 0, 0x1c000
	v_add_u32_e32 v142, s34, v179
	v_add_u32_e32 v158, s35, v179
	ds_read_b128 v[18:21], v142
	ds_read_b128 v[22:25], v142 offset:1024
	ds_read_b128 v[138:141], v142 offset:2048
	ds_read_b128 v[142:145], v142 offset:3072
	ds_read_b128 v[146:149], v158
	ds_read_b128 v[150:153], v158 offset:1024
	ds_read_b128 v[154:157], v158 offset:2048
	ds_read_b128 v[158:161], v158 offset:3072
	s_add_u32 s16, s16, 0x100000
	s_addc_u32 s17, s17, 0
	s_mov_b32 m0, s71
	v_lshl_add_u64 v[242:243], s[16:17], 0, v[164:165]
	ds_read_b128 v[202:205], v199 offset:32768
	ds_read_b128 v[206:209], v199 offset:33792
	ds_read_b128 v[214:217], v199 offset:34816
	ds_read_b128 v[218:221], v199 offset:35840
	ds_read_b128 v[222:225], v199 offset:36864
	ds_read_b128 v[226:229], v199 offset:37888
	ds_read_b128 v[230:233], v199 offset:38912
	ds_read_b128 v[234:237], v199 offset:39936
	global_load_lds_dwordx4 v[242:243], off
	v_lshl_add_u64 v[242:243], s[16:17], 0, v[170:171]
	s_mov_b32 m0, s87
	s_nop 0
	global_load_lds_dwordx4 v[242:243], off
	s_waitcnt vmcnt(8)
	s_waitcnt lgkmcnt(0)
	s_setprio 1
	s_barrier
	v_mfma_f32_16x16x32_bf16 v[134:137], v[18:21], v[202:205], v[134:137]
	v_mfma_f32_16x16x32_bf16 v[134:137], v[22:25], v[206:209], v[134:137]
	v_mfma_f32_16x16x32_bf16 v[118:121], v[22:25], v[218:221], v[118:121]
	v_mfma_f32_16x16x32_bf16 v[118:121], v[18:21], v[214:217], v[118:121]
	v_mfma_f32_16x16x32_bf16 v[102:105], v[18:21], v[222:225], v[102:105]
	v_mfma_f32_16x16x32_bf16 v[102:105], v[22:25], v[226:229], v[102:105]
	v_mfma_f32_16x16x32_bf16 v[86:89], v[22:25], v[234:237], v[86:89]
	v_mfma_f32_16x16x32_bf16 v[86:89], v[18:21], v[230:233], v[86:89]
	v_mfma_f32_16x16x32_bf16 v[82:85], v[138:141], v[230:233], v[82:85]
	v_mfma_f32_16x16x32_bf16 v[82:85], v[142:145], v[234:237], v[82:85]
	v_mfma_f32_16x16x32_bf16 v[130:133], v[142:145], v[206:209], v[130:133]
	v_mfma_f32_16x16x32_bf16 v[130:133], v[138:141], v[202:205], v[130:133]
	v_mfma_f32_16x16x32_bf16 v[114:117], v[138:141], v[214:217], v[114:117]
	v_mfma_f32_16x16x32_bf16 v[114:117], v[142:145], v[218:221], v[114:117]
	v_mfma_f32_16x16x32_bf16 v[98:101], v[142:145], v[226:229], v[98:101]
	v_mfma_f32_16x16x32_bf16 v[98:101], v[138:141], v[222:225], v[98:101]
	v_mfma_f32_16x16x32_bf16 v[94:97], v[146:149], v[222:225], v[94:97]
	v_mfma_f32_16x16x32_bf16 v[94:97], v[150:153], v[226:229], v[94:97]
	v_mfma_f32_16x16x32_bf16 v[126:129], v[150:153], v[206:209], v[126:129]
	v_mfma_f32_16x16x32_bf16 v[126:129], v[146:149], v[202:205], v[126:129]
	v_mfma_f32_16x16x32_bf16 v[110:113], v[146:149], v[214:217], v[110:113]
	v_mfma_f32_16x16x32_bf16 v[110:113], v[150:153], v[218:221], v[110:113]
	v_mfma_f32_16x16x32_bf16 v[78:81], v[150:153], v[234:237], v[78:81]
	v_mfma_f32_16x16x32_bf16 v[78:81], v[146:149], v[230:233], v[78:81]
	v_mfma_f32_16x16x32_bf16 v[74:77], v[154:157], v[230:233], v[74:77]
	v_mfma_f32_16x16x32_bf16 v[74:77], v[158:161], v[234:237], v[74:77]
	v_mfma_f32_16x16x32_bf16 v[122:125], v[158:161], v[206:209], v[122:125]
	v_mfma_f32_16x16x32_bf16 v[122:125], v[154:157], v[202:205], v[122:125]
	v_mfma_f32_16x16x32_bf16 v[106:109], v[154:157], v[214:217], v[106:109]
	v_mfma_f32_16x16x32_bf16 v[106:109], v[158:161], v[218:221], v[106:109]
	v_mfma_f32_16x16x32_bf16 v[90:93], v[158:161], v[226:229], v[90:93]
	v_mfma_f32_16x16x32_bf16 v[90:93], v[154:157], v[222:225], v[90:93]
	s_barrier
; #define PG8_STAGE(bufoff, gbase, voff) do { _Pragma("unroll") for (int _i = 0; _i < 2; ++_i) \
;         __builtin_amdgcn_global_load_lds((const unsigned*)((const char*)(gbase) + (voff)[_i]), (PG8_LAS unsigned*)(lds + (bufoff) + ldsw + _i * 8192), 16, 0, 0); } while (0)
; #define PG8_LDA(dst, b, h) do { _Pragma("unroll") for (int m = 0; m < 4; ++m) _Pragma("unroll") for (int k = 0; k < 2; ++k) dst[m][k] = *(const PG8_LAS bf16x8*)(lds + PG8_SA(b, h) + aoff + m * 2048 + k * 1024); } while (0)
; #define PG8_MMA(ai, bj, At, Bt) do { __builtin_amdgcn_s_setprio(1); _Pragma("unroll") for (int m = 0; m < 4; ++m) _Pragma("unroll") for (int n = 0; n < 2; ++n) _Pragma("unroll") for (int k = 0; k < 2; ++k) \
;         acc[ai][bj][m][n] = __builtin_amdgcn_mfma_f32_16x16x32_bf16(Bt[n][k], At[m][k], acc[ai][bj][m][n], 0, 0, 0); __builtin_amdgcn_s_setprio(0); } while (0)
; #define PG8_WAIT_V(n) asm volatile("s_waitcnt vmcnt(" #n ")" ::: "memory")
; #define PG8_WAIT_L(n) asm volatile("s_waitcnt lgkmcnt(" #n ")" ::: "memory")
; #define PG8_BAR __builtin_amdgcn_s_barrier()
; #define PG8_SCHED __builtin_amdgcn_sched_barrier(0)
; template <class Epi, class Sched, bool ALIGN_EPI = false, bool SP2 = false>
; __device__ __forceinline__ void gemm_phase(PG8_LAS unsigned char* lds, const Gemm g, const Sched& S, const Epi& E) {
;     ...
;             PG8_LDA(At, 1, 1); PG8_STAGE(PG8_SB(1, 0), b3, voffB); PG8_STAGE(PG8_SB(1, 1), b3 + hstep, voffB); PG8_STAGE(PG8_SA(1, 0), a3, voffA);
;             PG8_WAIT_V(8); PG8_WAIT_L(0); PG8_BAR; PG8_MMA(1, 0, At, B0); PG8_MMA(1, 1, At, B1); PG8_BAR; PG8_SCHED;
;     ...
;         if constexpr (ALIGN_EPI) { if (wr == 0) PG8_BAR; }
	s_setprio 0
	s_add_i32 s16, s34, s25
	v_lshl_add_u64 v[162:163], v[162:163], 0, s[46:47]
	s_mov_b32 m0, s16
	ds_read_b128 v[202:205], v199 offset:49152
	ds_read_b128 v[206:209], v199 offset:50176
	ds_read_b128 v[214:217], v199 offset:51200
	ds_read_b128 v[218:221], v199 offset:52224
	ds_read_b128 v[222:225], v199 offset:53248
	ds_read_b128 v[226:229], v199 offset:54272
	ds_read_b128 v[230:233], v199 offset:55296
	ds_read_b128 v[234:237], v199 offset:56320
	global_load_lds_dwordx4 v[162:163], off
	s_add_i32 m0, s16, 0x2000
	s_add_u32 s14, s14, 0x100080
	v_lshl_add_u64 v[162:163], v[210:211], 0, s[46:47]
	s_addc_u32 s15, s15, 0
	s_add_i32 s16, s35, s25
	global_load_lds_dwordx4 v[162:163], off
	v_lshl_add_u64 v[162:163], s[14:15], 0, v[168:169]
	s_mov_b32 m0, s16
	s_nop 0
	global_load_lds_dwordx4 v[162:163], off
	v_lshl_add_u64 v[162:163], s[14:15], 0, v[172:173]
	s_add_i32 m0, s16, 0x2000
	s_nop 0
	global_load_lds_dwordx4 v[162:163], off
	v_lshl_add_u64 v[162:163], v[238:239], 0, s[46:47]
	s_mov_b32 m0, s95
	s_nop 0
	global_load_lds_dwordx4 v[162:163], off
	v_lshl_add_u64 v[162:163], v[240:241], 0, s[46:47]
	s_mov_b32 m0, s96
	s_nop 0
	global_load_lds_dwordx4 v[162:163], off
	s_waitcnt vmcnt(8)
	s_waitcnt lgkmcnt(0)
	s_setprio 1
	s_barrier
	v_mfma_f32_16x16x32_bf16 v[70:73], v[18:21], v[202:205], v[70:73]
	v_mfma_f32_16x16x32_bf16 v[70:73], v[22:25], v[206:209], v[70:73]
	v_mfma_f32_16x16x32_bf16 v[54:57], v[22:25], v[218:221], v[54:57]
	v_mfma_f32_16x16x32_bf16 v[54:57], v[18:21], v[214:217], v[54:57]
	v_mfma_f32_16x16x32_bf16 v[38:41], v[18:21], v[222:225], v[38:41]
	v_mfma_f32_16x16x32_bf16 v[38:41], v[22:25], v[226:229], v[38:41]
	v_mfma_f32_16x16x32_bf16 v[2:5], v[22:25], v[234:237], v[2:5]
	v_mfma_f32_16x16x32_bf16 v[22:25], v[18:21], v[230:233], v[2:5]
	v_mfma_f32_16x16x32_bf16 v[2:5], v[138:141], v[230:233], v[6:9]
	v_mfma_f32_16x16x32_bf16 v[18:21], v[142:145], v[234:237], v[2:5]
	v_mfma_f32_16x16x32_bf16 v[66:69], v[142:145], v[206:209], v[66:69]
	v_mfma_f32_16x16x32_bf16 v[66:69], v[138:141], v[202:205], v[66:69]
	v_mfma_f32_16x16x32_bf16 v[50:53], v[138:141], v[214:217], v[50:53]
	v_mfma_f32_16x16x32_bf16 v[50:53], v[142:145], v[218:221], v[50:53]
	v_mfma_f32_16x16x32_bf16 v[34:37], v[142:145], v[226:229], v[34:37]
	v_mfma_f32_16x16x32_bf16 v[34:37], v[138:141], v[222:225], v[34:37]
	v_mfma_f32_16x16x32_bf16 v[2:5], v[146:149], v[222:225], v[30:33]
	v_mfma_f32_16x16x32_bf16 v[30:33], v[150:153], v[226:229], v[2:5]
	v_mfma_f32_16x16x32_bf16 v[2:5], v[150:153], v[234:237], v[14:17]
	v_mfma_f32_16x16x32_bf16 v[14:17], v[146:149], v[230:233], v[2:5]
	v_mfma_f32_16x16x32_bf16 v[2:5], v[146:149], v[202:205], v[62:65]
	v_mfma_f32_16x16x32_bf16 v[62:65], v[150:153], v[206:209], v[2:5]
	v_mfma_f32_16x16x32_bf16 v[2:5], v[150:153], v[218:221], v[46:49]
	v_mfma_f32_16x16x32_bf16 v[46:49], v[146:149], v[214:217], v[2:5]
	v_mfma_f32_16x16x32_bf16 v[2:5], v[154:157], v[214:217], v[42:45]
	v_mfma_f32_16x16x32_bf16 v[42:45], v[158:161], v[218:221], v[2:5]
	v_mfma_f32_16x16x32_bf16 v[2:5], v[158:161], v[226:229], v[26:29]
	v_mfma_f32_16x16x32_bf16 v[26:29], v[154:157], v[222:225], v[2:5]
	v_mfma_f32_16x16x32_bf16 v[2:5], v[154:157], v[230:233], v[10:13]
	v_mfma_f32_16x16x32_bf16 v[10:13], v[158:161], v[234:237], v[2:5]
	v_mfma_f32_16x16x32_bf16 v[2:5], v[158:161], v[206:209], v[58:61]
	v_mfma_f32_16x16x32_bf16 v[58:61], v[154:157], v[202:205], v[2:5]
	s_barrier
	s_setprio 0
	s_add_i32 s33, s33, 2
	s_add_u32 s12, s12, 0x100
	s_addc_u32 s13, s13, 0
	s_add_u32 s29, s29, 0x100
	s_addc_u32 s30, s30, 0
	s_cmp_gt_u32 s33, 61
	s_cbranch_scc0 .LBB0_139
	s_and_b64 vcc, exec, s[48:49]
	s_cbranch_vccz .LBB0_142
	s_barrier

; #define PG8_STAGE(bufoff, gbase, voff) do { _Pragma("unroll") for (int _i = 0; _i < 2; ++_i) \
;         __builtin_amdgcn_global_load_lds((const unsigned*)((const char*)(gbase) + (voff)[_i]), (PG8_LAS unsigned*)(lds + (bufoff) + ldsw + _i * 8192), 16, 0, 0); } while (0)
; #define PG8_LDA(dst, b, h) do { _Pragma("unroll") for (int m = 0; m < 4; ++m) _Pragma("unroll") for (int k = 0; k < 2; ++k) dst[m][k] = *(const PG8_LAS bf16x8*)(lds + PG8_SA(b, h) + aoff + m * 2048 + k * 1024); } while (0)
; #define PG8_LDB(dst, b, h) do { _Pragma("unroll") for (int n = 0; n < 2; ++n) _Pragma("unroll") for (int k = 0; k < 2; ++k) dst[n][k] = *(const PG8_LAS bf16x8*)(lds + PG8_SB(b, h) + boff + n * 2048 + k * 1024); } while (0)
; #define PG8_MMA(ai, bj, At, Bt) do { __builtin_amdgcn_s_setprio(1); _Pragma("unroll") for (int m = 0; m < 4; ++m) _Pragma("unroll") for (int n = 0; n < 2; ++n) _Pragma("unroll") for (int k = 0; k < 2; ++k) \
;         acc[ai][bj][m][n] = __builtin_amdgcn_mfma_f32_16x16x32_bf16(Bt[n][k], At[m][k], acc[ai][bj][m][n], 0, 0, 0); __builtin_amdgcn_s_setprio(0); } while (0)
; #define PG8_WAIT_V(n) asm volatile("s_waitcnt vmcnt(" #n ")" ::: "memory")
; #define PG8_WAIT_L(n) asm volatile("s_waitcnt lgkmcnt(" #n ")" ::: "memory")
; template <class Epi, class Sched, bool ALIGN_EPI = false, bool SP2 = false>
; __device__ __forceinline__ void gemm_phase(PG8_LAS unsigned char* lds, const Gemm g, const Sched& S, const Epi& E) {
;     ...
;             const bool last = (t == nt - 2);
;             const char* a1 = cA + (size_t)(t + 1) * kstep;
;             const char* a2 = last ? nA : cA + (size_t)(t + 2) * kstep; const char* b2 = last ? nB : cB + (size_t)(t + 2) * kstep;
;             const char* a3 = a2 + kstep; const char* b3 = b2 + kstep;
;             if (last && has_next) S.a_ready(nxt);
;             if constexpr (SP2) {
;             PG8_LDB(B0, 0, 0); PG8_LDB(B1, 0, 1); PG8_SCHED; PG8_LDA(At, 0, 0); PG8_STAGE(PG8_SA(1, 1), a1 + hstep, voffA);
;             PG8_WAIT_V(8); PG8_WAIT_L(0); PG8_BAR; PG8_MMA(0, 0, At, B0); PG8_MMA(0, 1, At, B1); PG8_BAR; PG8_SCHED;
;             PG8_LDA(At, 0, 1); PG8_STAGE(PG8_SB(0, 0), b2, voffB); PG8_STAGE(PG8_SB(0, 1), b2 + hstep, voffB); PG8_STAGE(PG8_SA(0, 0), a2, voffA);
;             PG8_WAIT_V(8); PG8_WAIT_L(0); PG8_BAR; PG8_MMA(1, 0, At, B0); PG8_MMA(1, 1, At, B1); PG8_BAR; PG8_SCHED;
.LBB0_1062:
	ds_read_b128 v[146:149], v155
	ds_read_b128 v[158:161], v155 offset:1024
	ds_read_b128 v[168:171], v155 offset:2048
	ds_read_b128 v[172:175], v155 offset:3072
	ds_read_b128 v[176:179], v156
	ds_read_b128 v[180:183], v156 offset:1024
	ds_read_b128 v[184:187], v156 offset:2048
	ds_read_b128 v[188:191], v156 offset:3072
	s_add_u32 s72, s70, 0xfff80080
	s_addc_u32 s73, s71, -1
	s_cmp_eq_u32 s77, 28
	s_cselect_b32 s75, s34, s73
	s_cselect_b32 s74, s35, s72
	s_cselect_b32 s73, s61, s76
	s_cselect_b32 s72, s63, s69
	v_lshl_add_u64 v[150:151], s[70:71], 0, v[138:139]
	s_add_i32 m0, s25, 0xc000
	ds_read_b128 v[200:203], v157
	ds_read_b128 v[204:207], v157 offset:1024
	ds_read_b128 v[208:211], v157 offset:2048
	ds_read_b128 v[212:215], v157 offset:3072
	ds_read_b128 v[216:219], v157 offset:4096
	ds_read_b128 v[220:223], v157 offset:5120
	ds_read_b128 v[224:227], v157 offset:6144
	ds_read_b128 v[228:231], v157 offset:7168
	global_load_lds_dwordx4 v[150:151], off
	v_lshl_add_u64 v[150:151], s[70:71], 0, v[140:141]
	s_add_i32 m0, s25, 0xe000
	s_nop 0
	global_load_lds_dwordx4 v[150:151], off
	s_waitcnt vmcnt(8)
	s_waitcnt lgkmcnt(0)
	s_setprio 1
	s_barrier
	v_mfma_f32_16x16x32_bf16 v[126:129], v[146:149], v[200:203], v[126:129]
	v_mfma_f32_16x16x32_bf16 v[126:129], v[158:161], v[204:207], v[126:129]
	v_mfma_f32_16x16x32_bf16 v[110:113], v[158:161], v[212:215], v[110:113]
	v_mfma_f32_16x16x32_bf16 v[110:113], v[146:149], v[208:211], v[110:113]
	v_mfma_f32_16x16x32_bf16 v[94:97], v[146:149], v[216:219], v[94:97]
	v_mfma_f32_16x16x32_bf16 v[94:97], v[158:161], v[220:223], v[94:97]
	v_mfma_f32_16x16x32_bf16 v[78:81], v[158:161], v[228:231], v[78:81]
	v_mfma_f32_16x16x32_bf16 v[78:81], v[146:149], v[224:227], v[78:81]
	v_mfma_f32_16x16x32_bf16 v[74:77], v[168:171], v[224:227], v[74:77]
	v_mfma_f32_16x16x32_bf16 v[74:77], v[172:175], v[228:231], v[74:77]
	v_mfma_f32_16x16x32_bf16 v[122:125], v[172:175], v[204:207], v[122:125]
	v_mfma_f32_16x16x32_bf16 v[122:125], v[168:171], v[200:203], v[122:125]
	v_mfma_f32_16x16x32_bf16 v[106:109], v[168:171], v[208:211], v[106:109]
	v_mfma_f32_16x16x32_bf16 v[106:109], v[172:175], v[212:215], v[106:109]
	v_mfma_f32_16x16x32_bf16 v[90:93], v[172:175], v[220:223], v[90:93]
	v_mfma_f32_16x16x32_bf16 v[90:93], v[168:171], v[216:219], v[90:93]
	v_mfma_f32_16x16x32_bf16 v[86:89], v[176:179], v[216:219], v[86:89]
	v_mfma_f32_16x16x32_bf16 v[86:89], v[180:183], v[220:223], v[86:89]
	v_mfma_f32_16x16x32_bf16 v[118:121], v[180:183], v[204:207], v[118:121]
	v_mfma_f32_16x16x32_bf16 v[118:121], v[176:179], v[200:203], v[118:121]
	v_mfma_f32_16x16x32_bf16 v[102:105], v[176:179], v[208:211], v[102:105]
	v_mfma_f32_16x16x32_bf16 v[102:105], v[180:183], v[212:215], v[102:105]
	v_mfma_f32_16x16x32_bf16 v[70:73], v[180:183], v[228:231], v[70:73]
	v_mfma_f32_16x16x32_bf16 v[70:73], v[176:179], v[224:227], v[70:73]
	v_mfma_f32_16x16x32_bf16 v[66:69], v[184:187], v[224:227], v[66:69]
	v_mfma_f32_16x16x32_bf16 v[66:69], v[188:191], v[228:231], v[66:69]
	v_mfma_f32_16x16x32_bf16 v[114:117], v[188:191], v[204:207], v[114:117]
	v_mfma_f32_16x16x32_bf16 v[114:117], v[184:187], v[200:203], v[114:117]
	v_mfma_f32_16x16x32_bf16 v[98:101], v[184:187], v[208:211], v[98:101]
	v_mfma_f32_16x16x32_bf16 v[98:101], v[188:191], v[212:215], v[98:101]
	v_mfma_f32_16x16x32_bf16 v[82:85], v[188:191], v[220:223], v[82:85]
	v_mfma_f32_16x16x32_bf16 v[82:85], v[184:187], v[216:219], v[82:85]
	s_barrier
	s_setprio 0
	s_add_i32 s78, s31, s2
	v_lshl_add_u64 v[150:151], s[72:73], 0, v[134:135]
	s_mov_b32 m0, s78
	ds_read_b128 v[200:203], v157 offset:16384
	ds_read_b128 v[204:207], v157 offset:17408
	ds_read_b128 v[208:211], v157 offset:18432
	ds_read_b128 v[212:215], v157 offset:19456
	ds_read_b128 v[216:219], v157 offset:20480
	ds_read_b128 v[220:223], v157 offset:21504
	ds_read_b128 v[224:227], v157 offset:22528
	ds_read_b128 v[228:231], v157 offset:23552
	global_load_lds_dwordx4 v[150:151], off
	s_add_i32 m0, s78, 0x2000
	s_add_u32 s78, s72, 0x80000
	v_lshl_add_u64 v[162:163], s[72:73], 0, v[130:131]
	s_addc_u32 s79, s73, 0
	s_add_i32 s80, s40, s2
	global_load_lds_dwordx4 v[162:163], off
	v_lshl_add_u64 v[192:193], s[78:79], 0, v[134:135]
	s_mov_b32 m0, s80
	v_lshl_add_u64 v[232:233], s[74:75], 0, v[132:133]
	global_load_lds_dwordx4 v[192:193], off
	v_lshl_add_u64 v[192:193], s[78:79], 0, v[130:131]
	s_add_i32 m0, s80, 0x2000
	s_nop 0
	global_load_lds_dwordx4 v[192:193], off
	v_lshl_add_u64 v[192:193], s[74:75], 0, v[136:137]
	s_mov_b32 m0, s25
	s_nop 0
	global_load_lds_dwordx4 v[192:193], off
	s_mov_b32 m0, s26
	s_nop 0
	global_load_lds_dwordx4 v[232:233], off
	s_waitcnt vmcnt(8)
	s_waitcnt lgkmcnt(0)
	s_setprio 1
	s_barrier
; #define PG8_STAGE(bufoff, gbase, voff) do { _Pragma("unroll") for (int _i = 0; _i < 2; ++_i) \
;         __builtin_amdgcn_global_load_lds((const unsigned*)((const char*)(gbase) + (voff)[_i]), (PG8_LAS unsigned*)(lds + (bufoff) + ldsw + _i * 8192), 16, 0, 0); } while (0)
; #define PG8_LDA(dst, b, h) do { _Pragma("unroll") for (int m = 0; m < 4; ++m) _Pragma("unroll") for (int k = 0; k < 2; ++k) dst[m][k] = *(const PG8_LAS bf16x8*)(lds + PG8_SA(b, h) + aoff + m * 2048 + k * 1024); } while (0)
; #define PG8_LDB(dst, b, h) do { _Pragma("unroll") for (int n = 0; n < 2; ++n) _Pragma("unroll") for (int k = 0; k < 2; ++k) dst[n][k] = *(const PG8_LAS bf16x8*)(lds + PG8_SB(b, h) + boff + n * 2048 + k * 1024); } while (0)
; #define PG8_MMA(ai, bj, At, Bt) do { __builtin_amdgcn_s_setprio(1); _Pragma("unroll") for (int m = 0; m < 4; ++m) _Pragma("unroll") for (int n = 0; n < 2; ++n) _Pragma("unroll") for (int k = 0; k < 2; ++k) \
;         acc[ai][bj][m][n] = __builtin_amdgcn_mfma_f32_16x16x32_bf16(Bt[n][k], At[m][k], acc[ai][bj][m][n], 0, 0, 0); __builtin_amdgcn_s_setprio(0); } while (0)
; #define PG8_WAIT_V(n) asm volatile("s_waitcnt vmcnt(" #n ")" ::: "memory")
; #define PG8_WAIT_L(n) asm volatile("s_waitcnt lgkmcnt(" #n ")" ::: "memory")
; #define PG8_BAR __builtin_amdgcn_s_barrier()
; #define PG8_SCHED __builtin_amdgcn_sched_barrier(0)
; template <class Epi, class Sched, bool ALIGN_EPI = false, bool SP2 = false>
; __device__ __forceinline__ void gemm_phase(PG8_LAS unsigned char* lds, const Gemm g, const Sched& S, const Epi& E) {
;     ...
;             PG8_WAIT_V(8); PG8_WAIT_L(0); PG8_BAR; PG8_MMA(1, 0, At, B0); PG8_MMA(1, 1, At, B1); PG8_BAR; PG8_SCHED;
;             PG8_LDB(B0, 1, 0); PG8_LDB(B1, 1, 1); PG8_SCHED; PG8_LDA(At, 1, 0); PG8_STAGE(PG8_SA(0, 1), a2 + hstep, voffA);
;             PG8_WAIT_V(8); PG8_WAIT_L(0); PG8_BAR; PG8_MMA(0, 0, At, B0); PG8_MMA(0, 1, At, B1); PG8_BAR; PG8_SCHED;
	v_mfma_f32_16x16x32_bf16 v[62:65], v[146:149], v[200:203], v[62:65]
	v_mfma_f32_16x16x32_bf16 v[62:65], v[158:161], v[204:207], v[62:65]
	v_mfma_f32_16x16x32_bf16 v[46:49], v[158:161], v[212:215], v[46:49]
	v_mfma_f32_16x16x32_bf16 v[46:49], v[146:149], v[208:211], v[46:49]
	v_mfma_f32_16x16x32_bf16 v[30:33], v[146:149], v[216:219], v[30:33]
	v_mfma_f32_16x16x32_bf16 v[30:33], v[158:161], v[220:223], v[30:33]
	v_mfma_f32_16x16x32_bf16 v[14:17], v[158:161], v[228:231], v[14:17]
	v_mfma_f32_16x16x32_bf16 v[14:17], v[146:149], v[224:227], v[14:17]
	v_mfma_f32_16x16x32_bf16 v[10:13], v[168:171], v[224:227], v[10:13]
	v_mfma_f32_16x16x32_bf16 v[10:13], v[172:175], v[228:231], v[10:13]
	v_mfma_f32_16x16x32_bf16 v[58:61], v[172:175], v[204:207], v[58:61]
	v_mfma_f32_16x16x32_bf16 v[58:61], v[168:171], v[200:203], v[58:61]
	v_mfma_f32_16x16x32_bf16 v[42:45], v[168:171], v[208:211], v[42:45]
	v_mfma_f32_16x16x32_bf16 v[42:45], v[172:175], v[212:215], v[42:45]
	v_mfma_f32_16x16x32_bf16 v[26:29], v[172:175], v[220:223], v[26:29]
	v_mfma_f32_16x16x32_bf16 v[26:29], v[168:171], v[216:219], v[26:29]
	v_mfma_f32_16x16x32_bf16 v[22:25], v[176:179], v[216:219], v[22:25]
	v_mfma_f32_16x16x32_bf16 v[22:25], v[180:183], v[220:223], v[22:25]
	v_mfma_f32_16x16x32_bf16 v[54:57], v[180:183], v[204:207], v[54:57]
	v_mfma_f32_16x16x32_bf16 v[54:57], v[176:179], v[200:203], v[54:57]
	v_mfma_f32_16x16x32_bf16 v[38:41], v[176:179], v[208:211], v[38:41]
	v_mfma_f32_16x16x32_bf16 v[38:41], v[180:183], v[212:215], v[38:41]
	v_mfma_f32_16x16x32_bf16 v[6:9], v[180:183], v[228:231], v[6:9]
	v_mfma_f32_16x16x32_bf16 v[6:9], v[176:179], v[224:227], v[6:9]
	v_mfma_f32_16x16x32_bf16 v[2:5], v[184:187], v[224:227], v[2:5]
	v_mfma_f32_16x16x32_bf16 v[2:5], v[188:191], v[228:231], v[2:5]
	v_mfma_f32_16x16x32_bf16 v[50:53], v[188:191], v[204:207], v[50:53]
	v_mfma_f32_16x16x32_bf16 v[50:53], v[184:187], v[200:203], v[50:53]
	v_mfma_f32_16x16x32_bf16 v[34:37], v[184:187], v[208:211], v[34:37]
	v_mfma_f32_16x16x32_bf16 v[34:37], v[188:191], v[212:215], v[34:37]
	v_mfma_f32_16x16x32_bf16 v[18:21], v[188:191], v[220:223], v[18:21]
	v_mfma_f32_16x16x32_bf16 v[18:21], v[184:187], v[216:219], v[18:21]
	s_barrier
	s_setprio 0
	s_add_i32 s78, 0, 0x18000
	v_add_u32_e32 v166, s78, v153
	s_add_i32 s79, 0, 0x1c000
	ds_read_b128 v[146:149], v166
	ds_read_b128 v[158:161], v166 offset:1024
	ds_read_b128 v[168:171], v166 offset:2048
	ds_read_b128 v[172:175], v166 offset:3072
	v_add_u32_e32 v166, s79, v153
	ds_read_b128 v[176:179], v166
	ds_read_b128 v[180:183], v166 offset:1024
	ds_read_b128 v[184:187], v166 offset:2048
	ds_read_b128 v[188:191], v166 offset:3072
	s_add_u32 s74, s74, 0x80000
	s_addc_u32 s75, s75, 0
	s_mov_b32 m0, s27
	v_lshl_add_u64 v[240:241], s[74:75], 0, v[136:137]
	ds_read_b128 v[200:203], v157 offset:32768
	ds_read_b128 v[204:207], v157 offset:33792
	ds_read_b128 v[208:211], v157 offset:34816
	ds_read_b128 v[212:215], v157 offset:35840
	ds_read_b128 v[216:219], v157 offset:36864
	ds_read_b128 v[220:223], v157 offset:37888
	ds_read_b128 v[224:227], v157 offset:38912
	ds_read_b128 v[228:231], v157 offset:39936
	global_load_lds_dwordx4 v[240:241], off
	v_lshl_add_u64 v[240:241], s[74:75], 0, v[132:133]
	s_mov_b32 m0, s28
	s_nop 0
	global_load_lds_dwordx4 v[240:241], off
	s_waitcnt vmcnt(8)
	s_waitcnt lgkmcnt(0)
	s_setprio 1
	s_barrier
	v_mfma_f32_16x16x32_bf16 v[126:129], v[146:149], v[200:203], v[126:129]
	v_mfma_f32_16x16x32_bf16 v[126:129], v[158:161], v[204:207], v[126:129]
	v_mfma_f32_16x16x32_bf16 v[110:113], v[158:161], v[212:215], v[110:113]
	v_mfma_f32_16x16x32_bf16 v[110:113], v[146:149], v[208:211], v[110:113]
	v_mfma_f32_16x16x32_bf16 v[94:97], v[146:149], v[216:219], v[94:97]
	v_mfma_f32_16x16x32_bf16 v[94:97], v[158:161], v[220:223], v[94:97]
	v_mfma_f32_16x16x32_bf16 v[78:81], v[158:161], v[228:231], v[78:81]
	v_mfma_f32_16x16x32_bf16 v[78:81], v[146:149], v[224:227], v[78:81]
	v_mfma_f32_16x16x32_bf16 v[74:77], v[168:171], v[224:227], v[74:77]
	v_mfma_f32_16x16x32_bf16 v[74:77], v[172:175], v[228:231], v[74:77]
	v_mfma_f32_16x16x32_bf16 v[122:125], v[172:175], v[204:207], v[122:125]
	v_mfma_f32_16x16x32_bf16 v[122:125], v[168:171], v[200:203], v[122:125]
	v_mfma_f32_16x16x32_bf16 v[106:109], v[168:171], v[208:211], v[106:109]
	v_mfma_f32_16x16x32_bf16 v[106:109], v[172:175], v[212:215], v[106:109]
	v_mfma_f32_16x16x32_bf16 v[90:93], v[172:175], v[220:223], v[90:93]
	v_mfma_f32_16x16x32_bf16 v[90:93], v[168:171], v[216:219], v[90:93]
	v_mfma_f32_16x16x32_bf16 v[86:89], v[176:179], v[216:219], v[86:89]
	v_mfma_f32_16x16x32_bf16 v[86:89], v[180:183], v[220:223], v[86:89]
	v_mfma_f32_16x16x32_bf16 v[118:121], v[180:183], v[204:207], v[118:121]
	v_mfma_f32_16x16x32_bf16 v[118:121], v[176:179], v[200:203], v[118:121]
	v_mfma_f32_16x16x32_bf16 v[102:105], v[176:179], v[208:211], v[102:105]
	v_mfma_f32_16x16x32_bf16 v[102:105], v[180:183], v[212:215], v[102:105]
	v_mfma_f32_16x16x32_bf16 v[70:73], v[180:183], v[228:231], v[70:73]
	v_mfma_f32_16x16x32_bf16 v[70:73], v[176:179], v[224:227], v[70:73]
	v_mfma_f32_16x16x32_bf16 v[66:69], v[184:187], v[224:227], v[66:69]
	v_mfma_f32_16x16x32_bf16 v[66:69], v[188:191], v[228:231], v[66:69]
	v_mfma_f32_16x16x32_bf16 v[114:117], v[188:191], v[204:207], v[114:117]
	v_mfma_f32_16x16x32_bf16 v[114:117], v[184:187], v[200:203], v[114:117]
	v_mfma_f32_16x16x32_bf16 v[98:101], v[184:187], v[208:211], v[98:101]
	v_mfma_f32_16x16x32_bf16 v[98:101], v[188:191], v[212:215], v[98:101]
	v_mfma_f32_16x16x32_bf16 v[82:85], v[188:191], v[220:223], v[82:85]
	v_mfma_f32_16x16x32_bf16 v[82:85], v[184:187], v[216:219], v[82:85]
	s_barrier
; #define PG8_STAGE(bufoff, gbase, voff) do { _Pragma("unroll") for (int _i = 0; _i < 2; ++_i) \
;         __builtin_amdgcn_global_load_lds((const unsigned*)((const char*)(gbase) + (voff)[_i]), (PG8_LAS unsigned*)(lds + (bufoff) + ldsw + _i * 8192), 16, 0, 0); } while (0)
; #define PG8_LDA(dst, b, h) do { _Pragma("unroll") for (int m = 0; m < 4; ++m) _Pragma("unroll") for (int k = 0; k < 2; ++k) dst[m][k] = *(const PG8_LAS bf16x8*)(lds + PG8_SA(b, h) + aoff + m * 2048 + k * 1024); } while (0)
; #define PG8_MMA(ai, bj, At, Bt) do { __builtin_amdgcn_s_setprio(1); _Pragma("unroll") for (int m = 0; m < 4; ++m) _Pragma("unroll") for (int n = 0; n < 2; ++n) _Pragma("unroll") for (int k = 0; k < 2; ++k) \
;         acc[ai][bj][m][n] = __builtin_amdgcn_mfma_f32_16x16x32_bf16(Bt[n][k], At[m][k], acc[ai][bj][m][n], 0, 0, 0); __builtin_amdgcn_s_setprio(0); } while (0)
; #define PG8_WAIT_V(n) asm volatile("s_waitcnt vmcnt(" #n ")" ::: "memory")
; #define PG8_WAIT_L(n) asm volatile("s_waitcnt lgkmcnt(" #n ")" ::: "memory")
; #define PG8_BAR __builtin_amdgcn_s_barrier()
; #define PG8_SCHED __builtin_amdgcn_sched_barrier(0)
; template <class Epi, class Sched, bool ALIGN_EPI = false, bool SP2 = false>
; __device__ __forceinline__ void gemm_phase(PG8_LAS unsigned char* lds, const Gemm g, const Sched& S, const Epi& E) {
;     ...
;             PG8_LDA(At, 1, 1); PG8_STAGE(PG8_SB(1, 0), b3, voffB); PG8_STAGE(PG8_SB(1, 1), b3 + hstep, voffB); PG8_STAGE(PG8_SA(1, 0), a3, voffA);
;             PG8_WAIT_V(8); PG8_WAIT_L(0); PG8_BAR; PG8_MMA(1, 0, At, B0); PG8_MMA(1, 1, At, B1); PG8_BAR; PG8_SCHED;
;     ...
;         if constexpr (ALIGN_EPI) { if (wr == 0) PG8_BAR; }
	s_setprio 0
	s_add_i32 s74, s78, s2
	v_lshl_add_u64 v[150:151], v[150:151], 0, s[10:11]
	s_mov_b32 m0, s74
	ds_read_b128 v[200:203], v157 offset:49152
	ds_read_b128 v[204:207], v157 offset:50176
	ds_read_b128 v[208:211], v157 offset:51200
	ds_read_b128 v[212:215], v157 offset:52224
	ds_read_b128 v[216:219], v157 offset:53248
	ds_read_b128 v[220:223], v157 offset:54272
	ds_read_b128 v[224:227], v157 offset:55296
	ds_read_b128 v[228:231], v157 offset:56320
	global_load_lds_dwordx4 v[150:151], off
	s_add_i32 m0, s74, 0x2000
	s_add_u32 s72, s72, 0x80080
	v_lshl_add_u64 v[150:151], v[162:163], 0, s[10:11]
	s_addc_u32 s73, s73, 0
	s_add_i32 s74, s79, s2
	global_load_lds_dwordx4 v[150:151], off
	v_lshl_add_u64 v[150:151], s[72:73], 0, v[134:135]
	s_mov_b32 m0, s74
	s_nop 0
	global_load_lds_dwordx4 v[150:151], off
	v_lshl_add_u64 v[150:151], s[72:73], 0, v[130:131]
	s_add_i32 m0, s74, 0x2000
	s_nop 0
	global_load_lds_dwordx4 v[150:151], off
	v_lshl_add_u64 v[150:151], v[192:193], 0, s[10:11]
	s_mov_b32 m0, s30
	s_nop 0
	global_load_lds_dwordx4 v[150:151], off
	v_lshl_add_u64 v[150:151], v[232:233], 0, s[10:11]
	s_mov_b32 m0, s33
	s_nop 0
	global_load_lds_dwordx4 v[150:151], off
	s_waitcnt vmcnt(8)
	s_waitcnt lgkmcnt(0)
	s_setprio 1
	s_barrier
	v_mfma_f32_16x16x32_bf16 v[62:65], v[146:149], v[200:203], v[62:65]
	v_mfma_f32_16x16x32_bf16 v[62:65], v[158:161], v[204:207], v[62:65]
	v_mfma_f32_16x16x32_bf16 v[46:49], v[158:161], v[212:215], v[46:49]
	v_mfma_f32_16x16x32_bf16 v[46:49], v[146:149], v[208:211], v[46:49]
	v_mfma_f32_16x16x32_bf16 v[30:33], v[146:149], v[216:219], v[30:33]
	v_mfma_f32_16x16x32_bf16 v[30:33], v[158:161], v[220:223], v[30:33]
	v_mfma_f32_16x16x32_bf16 v[14:17], v[158:161], v[228:231], v[14:17]
	v_mfma_f32_16x16x32_bf16 v[14:17], v[146:149], v[224:227], v[14:17]
	v_mfma_f32_16x16x32_bf16 v[10:13], v[168:171], v[224:227], v[10:13]
	v_mfma_f32_16x16x32_bf16 v[10:13], v[172:175], v[228:231], v[10:13]
	v_mfma_f32_16x16x32_bf16 v[58:61], v[172:175], v[204:207], v[58:61]
	v_mfma_f32_16x16x32_bf16 v[58:61], v[168:171], v[200:203], v[58:61]
	v_mfma_f32_16x16x32_bf16 v[42:45], v[168:171], v[208:211], v[42:45]
	v_mfma_f32_16x16x32_bf16 v[42:45], v[172:175], v[212:215], v[42:45]
	v_mfma_f32_16x16x32_bf16 v[26:29], v[172:175], v[220:223], v[26:29]
	v_mfma_f32_16x16x32_bf16 v[26:29], v[168:171], v[216:219], v[26:29]
	v_mfma_f32_16x16x32_bf16 v[22:25], v[176:179], v[216:219], v[22:25]
	v_mfma_f32_16x16x32_bf16 v[22:25], v[180:183], v[220:223], v[22:25]
	v_mfma_f32_16x16x32_bf16 v[54:57], v[180:183], v[204:207], v[54:57]
	v_mfma_f32_16x16x32_bf16 v[54:57], v[176:179], v[200:203], v[54:57]
	v_mfma_f32_16x16x32_bf16 v[38:41], v[176:179], v[208:211], v[38:41]
	v_mfma_f32_16x16x32_bf16 v[38:41], v[180:183], v[212:215], v[38:41]
	v_mfma_f32_16x16x32_bf16 v[6:9], v[180:183], v[228:231], v[6:9]
	v_mfma_f32_16x16x32_bf16 v[6:9], v[176:179], v[224:227], v[6:9]
	v_mfma_f32_16x16x32_bf16 v[2:5], v[184:187], v[224:227], v[2:5]
	v_mfma_f32_16x16x32_bf16 v[2:5], v[188:191], v[228:231], v[2:5]
	v_mfma_f32_16x16x32_bf16 v[50:53], v[188:191], v[204:207], v[50:53]
	v_mfma_f32_16x16x32_bf16 v[50:53], v[184:187], v[200:203], v[50:53]
	v_mfma_f32_16x16x32_bf16 v[34:37], v[184:187], v[208:211], v[34:37]
	v_mfma_f32_16x16x32_bf16 v[34:37], v[188:191], v[212:215], v[34:37]
	v_mfma_f32_16x16x32_bf16 v[18:21], v[188:191], v[220:223], v[18:21]
	v_mfma_f32_16x16x32_bf16 v[18:21], v[184:187], v[216:219], v[18:21]
	s_barrier
	s_setprio 0
	s_add_i32 s77, s77, 2
	s_add_u32 s70, s70, 0x100
	s_addc_u32 s71, s71, 0
	s_add_u32 s69, s69, 0x100
	s_addc_u32 s76, s76, 0
	s_cmp_gt_u32 s77, 29
	s_cbranch_scc0 .LBB0_1062
	s_and_b64 vcc, exec, s[48:49]
	s_cbranch_vccz .LBB0_1065
	s_barrier

; #define PG8_STAGE(bufoff, gbase, voff) do { _Pragma("unroll") for (int _i = 0; _i < 2; ++_i) \
;         __builtin_amdgcn_global_load_lds((const unsigned*)((const char*)(gbase) + (voff)[_i]), (PG8_LAS unsigned*)(lds + (bufoff) + ldsw + _i * 8192), 16, 0, 0); } while (0)
; #define PG8_LDA(dst, b, h) do { _Pragma("unroll") for (int m = 0; m < 4; ++m) _Pragma("unroll") for (int k = 0; k < 2; ++k) dst[m][k] = *(const PG8_LAS bf16x8*)(lds + PG8_SA(b, h) + aoff + m * 2048 + k * 1024); } while (0)
; #define PG8_LDB(dst, b, h) do { _Pragma("unroll") for (int n = 0; n < 2; ++n) _Pragma("unroll") for (int k = 0; k < 2; ++k) dst[n][k] = *(const PG8_LAS bf16x8*)(lds + PG8_SB(b, h) + boff + n * 2048 + k * 1024); } while (0)
; #define PG8_MMA(ai, bj, At, Bt) do { __builtin_amdgcn_s_setprio(1); _Pragma("unroll") for (int m = 0; m < 4; ++m) _Pragma("unroll") for (int n = 0; n < 2; ++n) _Pragma("unroll") for (int k = 0; k < 2; ++k) \
;         acc[ai][bj][m][n] = __builtin_amdgcn_mfma_f32_16x16x32_bf16(Bt[n][k], At[m][k], acc[ai][bj][m][n], 0, 0, 0); __builtin_amdgcn_s_setprio(0); } while (0)
; #define PG8_WAIT_V(n) asm volatile("s_waitcnt vmcnt(" #n ")" ::: "memory")
; #define PG8_WAIT_L(n) asm volatile("s_waitcnt lgkmcnt(" #n ")" ::: "memory")
; template <class Epi, class Sched, bool ALIGN_EPI = false, bool SP2 = false>
; __device__ __forceinline__ void gemm_phase(PG8_LAS unsigned char* lds, const Gemm g, const Sched& S, const Epi& E) {
;     ...
;             const bool last = (t == nt - 2);
;             const char* a1 = cA + (size_t)(t + 1) * kstep;
;             const char* a2 = last ? nA : cA + (size_t)(t + 2) * kstep; const char* b2 = last ? nB : cB + (size_t)(t + 2) * kstep;
;             const char* a3 = a2 + kstep; const char* b3 = b2 + kstep;
;             if (last && has_next) S.a_ready(nxt);
;             if constexpr (SP2) {
;             PG8_LDB(B0, 0, 0); PG8_LDB(B1, 0, 1); PG8_SCHED; PG8_LDA(At, 0, 0); PG8_STAGE(PG8_SA(1, 1), a1 + hstep, voffA);
;             PG8_WAIT_V(8); PG8_WAIT_L(0); PG8_BAR; PG8_MMA(0, 0, At, B0); PG8_MMA(0, 1, At, B1); PG8_BAR; PG8_SCHED;
;             PG8_LDA(At, 0, 1); PG8_STAGE(PG8_SB(0, 0), b2, voffB); PG8_STAGE(PG8_SB(0, 1), b2 + hstep, voffB); PG8_STAGE(PG8_SA(0, 0), a2, voffA);
;             PG8_WAIT_V(8); PG8_WAIT_L(0); PG8_BAR; PG8_MMA(1, 0, At, B0); PG8_MMA(1, 1, At, B1); PG8_BAR; PG8_SCHED;
.LBB0_1078:
	ds_read_b128 v[146:149], v155
	ds_read_b128 v[158:161], v155 offset:1024
	ds_read_b128 v[168:171], v155 offset:2048
	ds_read_b128 v[172:175], v155 offset:3072
	ds_read_b128 v[176:179], v156
	ds_read_b128 v[180:183], v156 offset:1024
	ds_read_b128 v[184:187], v156 offset:2048
	ds_read_b128 v[188:191], v156 offset:3072
	s_add_u32 s68, s66, 0xfff80080
	s_addc_u32 s69, s67, -1
	s_cmp_eq_u32 s73, 28
	s_cselect_b32 s71, s34, s69
	s_cselect_b32 s70, s35, s68
	s_cselect_b32 s69, s57, s72
	s_cselect_b32 s68, s59, s65
	v_lshl_add_u64 v[150:151], s[66:67], 0, v[138:139]
	s_add_i32 m0, s25, 0xc000
	ds_read_b128 v[200:203], v157
	ds_read_b128 v[204:207], v157 offset:1024
	ds_read_b128 v[208:211], v157 offset:2048
	ds_read_b128 v[212:215], v157 offset:3072
	ds_read_b128 v[216:219], v157 offset:4096
	ds_read_b128 v[220:223], v157 offset:5120
	ds_read_b128 v[224:227], v157 offset:6144
	ds_read_b128 v[228:231], v157 offset:7168
	global_load_lds_dwordx4 v[150:151], off
	v_lshl_add_u64 v[150:151], s[66:67], 0, v[140:141]
	s_add_i32 m0, s25, 0xe000
	s_nop 0
	global_load_lds_dwordx4 v[150:151], off
	s_waitcnt vmcnt(8)
	s_waitcnt lgkmcnt(0)
	s_setprio 1
	s_barrier
	v_mfma_f32_16x16x32_bf16 v[126:129], v[146:149], v[200:203], v[126:129]
	v_mfma_f32_16x16x32_bf16 v[126:129], v[158:161], v[204:207], v[126:129]
	v_mfma_f32_16x16x32_bf16 v[110:113], v[158:161], v[212:215], v[110:113]
	v_mfma_f32_16x16x32_bf16 v[110:113], v[146:149], v[208:211], v[110:113]
	v_mfma_f32_16x16x32_bf16 v[94:97], v[146:149], v[216:219], v[94:97]
	v_mfma_f32_16x16x32_bf16 v[94:97], v[158:161], v[220:223], v[94:97]
	v_mfma_f32_16x16x32_bf16 v[78:81], v[158:161], v[228:231], v[78:81]
	v_mfma_f32_16x16x32_bf16 v[78:81], v[146:149], v[224:227], v[78:81]
	v_mfma_f32_16x16x32_bf16 v[74:77], v[168:171], v[224:227], v[74:77]
	v_mfma_f32_16x16x32_bf16 v[74:77], v[172:175], v[228:231], v[74:77]
	v_mfma_f32_16x16x32_bf16 v[122:125], v[172:175], v[204:207], v[122:125]
	v_mfma_f32_16x16x32_bf16 v[122:125], v[168:171], v[200:203], v[122:125]
	v_mfma_f32_16x16x32_bf16 v[106:109], v[168:171], v[208:211], v[106:109]
	v_mfma_f32_16x16x32_bf16 v[106:109], v[172:175], v[212:215], v[106:109]
	v_mfma_f32_16x16x32_bf16 v[90:93], v[172:175], v[220:223], v[90:93]
	v_mfma_f32_16x16x32_bf16 v[90:93], v[168:171], v[216:219], v[90:93]
	v_mfma_f32_16x16x32_bf16 v[86:89], v[176:179], v[216:219], v[86:89]
	v_mfma_f32_16x16x32_bf16 v[86:89], v[180:183], v[220:223], v[86:89]
	v_mfma_f32_16x16x32_bf16 v[118:121], v[180:183], v[204:207], v[118:121]
	v_mfma_f32_16x16x32_bf16 v[118:121], v[176:179], v[200:203], v[118:121]
	v_mfma_f32_16x16x32_bf16 v[102:105], v[176:179], v[208:211], v[102:105]
	v_mfma_f32_16x16x32_bf16 v[102:105], v[180:183], v[212:215], v[102:105]
	v_mfma_f32_16x16x32_bf16 v[70:73], v[180:183], v[228:231], v[70:73]
	v_mfma_f32_16x16x32_bf16 v[70:73], v[176:179], v[224:227], v[70:73]
	v_mfma_f32_16x16x32_bf16 v[66:69], v[184:187], v[224:227], v[66:69]
	v_mfma_f32_16x16x32_bf16 v[66:69], v[188:191], v[228:231], v[66:69]
	v_mfma_f32_16x16x32_bf16 v[114:117], v[188:191], v[204:207], v[114:117]
	v_mfma_f32_16x16x32_bf16 v[114:117], v[184:187], v[200:203], v[114:117]
	v_mfma_f32_16x16x32_bf16 v[98:101], v[184:187], v[208:211], v[98:101]
	v_mfma_f32_16x16x32_bf16 v[98:101], v[188:191], v[212:215], v[98:101]
	v_mfma_f32_16x16x32_bf16 v[82:85], v[188:191], v[220:223], v[82:85]
	v_mfma_f32_16x16x32_bf16 v[82:85], v[184:187], v[216:219], v[82:85]
	s_barrier
	s_setprio 0
	s_add_i32 s74, s31, s2
	v_lshl_add_u64 v[150:151], s[68:69], 0, v[134:135]
	s_mov_b32 m0, s74
	ds_read_b128 v[200:203], v157 offset:16384
	ds_read_b128 v[204:207], v157 offset:17408
	ds_read_b128 v[208:211], v157 offset:18432
	ds_read_b128 v[212:215], v157 offset:19456
	ds_read_b128 v[216:219], v157 offset:20480
	ds_read_b128 v[220:223], v157 offset:21504
	ds_read_b128 v[224:227], v157 offset:22528
	ds_read_b128 v[228:231], v157 offset:23552
	global_load_lds_dwordx4 v[150:151], off
	s_add_i32 m0, s74, 0x2000
	s_add_u32 s74, s68, 0x80000
	v_lshl_add_u64 v[162:163], s[68:69], 0, v[130:131]
	s_addc_u32 s75, s69, 0
	s_add_i32 s76, s40, s2
	global_load_lds_dwordx4 v[162:163], off
	v_lshl_add_u64 v[192:193], s[74:75], 0, v[134:135]
	s_mov_b32 m0, s76
	v_lshl_add_u64 v[232:233], s[70:71], 0, v[132:133]
	global_load_lds_dwordx4 v[192:193], off
	v_lshl_add_u64 v[192:193], s[74:75], 0, v[130:131]
	s_add_i32 m0, s76, 0x2000
	s_nop 0
	global_load_lds_dwordx4 v[192:193], off
	v_lshl_add_u64 v[192:193], s[70:71], 0, v[136:137]
	s_mov_b32 m0, s25
	s_nop 0
	global_load_lds_dwordx4 v[192:193], off
	s_mov_b32 m0, s26
	s_nop 0
	global_load_lds_dwordx4 v[232:233], off
	s_waitcnt vmcnt(8)
	s_waitcnt lgkmcnt(0)
	s_setprio 1
	s_barrier
; #define PG8_STAGE(bufoff, gbase, voff) do { _Pragma("unroll") for (int _i = 0; _i < 2; ++_i) \
;         __builtin_amdgcn_global_load_lds((const unsigned*)((const char*)(gbase) + (voff)[_i]), (PG8_LAS unsigned*)(lds + (bufoff) + ldsw + _i * 8192), 16, 0, 0); } while (0)
; #define PG8_LDA(dst, b, h) do { _Pragma("unroll") for (int m = 0; m < 4; ++m) _Pragma("unroll") for (int k = 0; k < 2; ++k) dst[m][k] = *(const PG8_LAS bf16x8*)(lds + PG8_SA(b, h) + aoff + m * 2048 + k * 1024); } while (0)
; #define PG8_LDB(dst, b, h) do { _Pragma("unroll") for (int n = 0; n < 2; ++n) _Pragma("unroll") for (int k = 0; k < 2; ++k) dst[n][k] = *(const PG8_LAS bf16x8*)(lds + PG8_SB(b, h) + boff + n * 2048 + k * 1024); } while (0)
; #define PG8_MMA(ai, bj, At, Bt) do { __builtin_amdgcn_s_setprio(1); _Pragma("unroll") for (int m = 0; m < 4; ++m) _Pragma("unroll") for (int n = 0; n < 2; ++n) _Pragma("unroll") for (int k = 0; k < 2; ++k) \
;         acc[ai][bj][m][n] = __builtin_amdgcn_mfma_f32_16x16x32_bf16(Bt[n][k], At[m][k], acc[ai][bj][m][n], 0, 0, 0); __builtin_amdgcn_s_setprio(0); } while (0)
; #define PG8_WAIT_V(n) asm volatile("s_waitcnt vmcnt(" #n ")" ::: "memory")
; #define PG8_WAIT_L(n) asm volatile("s_waitcnt lgkmcnt(" #n ")" ::: "memory")
; #define PG8_BAR __builtin_amdgcn_s_barrier()
; #define PG8_SCHED __builtin_amdgcn_sched_barrier(0)
; template <class Epi, class Sched, bool ALIGN_EPI = false, bool SP2 = false>
; __device__ __forceinline__ void gemm_phase(PG8_LAS unsigned char* lds, const Gemm g, const Sched& S, const Epi& E) {
;     ...
;             PG8_WAIT_V(8); PG8_WAIT_L(0); PG8_BAR; PG8_MMA(1, 0, At, B0); PG8_MMA(1, 1, At, B1); PG8_BAR; PG8_SCHED;
;             PG8_LDB(B0, 1, 0); PG8_LDB(B1, 1, 1); PG8_SCHED; PG8_LDA(At, 1, 0); PG8_STAGE(PG8_SA(0, 1), a2 + hstep, voffA);
;             PG8_WAIT_V(8); PG8_WAIT_L(0); PG8_BAR; PG8_MMA(0, 0, At, B0); PG8_MMA(0, 1, At, B1); PG8_BAR; PG8_SCHED;
	v_mfma_f32_16x16x32_bf16 v[62:65], v[146:149], v[200:203], v[62:65]
	v_mfma_f32_16x16x32_bf16 v[62:65], v[158:161], v[204:207], v[62:65]
	v_mfma_f32_16x16x32_bf16 v[46:49], v[158:161], v[212:215], v[46:49]
	v_mfma_f32_16x16x32_bf16 v[46:49], v[146:149], v[208:211], v[46:49]
	v_mfma_f32_16x16x32_bf16 v[30:33], v[146:149], v[216:219], v[30:33]
	v_mfma_f32_16x16x32_bf16 v[30:33], v[158:161], v[220:223], v[30:33]
	v_mfma_f32_16x16x32_bf16 v[14:17], v[158:161], v[228:231], v[14:17]
	v_mfma_f32_16x16x32_bf16 v[14:17], v[146:149], v[224:227], v[14:17]
	v_mfma_f32_16x16x32_bf16 v[10:13], v[168:171], v[224:227], v[10:13]
	v_mfma_f32_16x16x32_bf16 v[10:13], v[172:175], v[228:231], v[10:13]
	v_mfma_f32_16x16x32_bf16 v[58:61], v[172:175], v[204:207], v[58:61]
	v_mfma_f32_16x16x32_bf16 v[58:61], v[168:171], v[200:203], v[58:61]
	v_mfma_f32_16x16x32_bf16 v[42:45], v[168:171], v[208:211], v[42:45]
	v_mfma_f32_16x16x32_bf16 v[42:45], v[172:175], v[212:215], v[42:45]
	v_mfma_f32_16x16x32_bf16 v[26:29], v[172:175], v[220:223], v[26:29]
	v_mfma_f32_16x16x32_bf16 v[26:29], v[168:171], v[216:219], v[26:29]
	v_mfma_f32_16x16x32_bf16 v[22:25], v[176:179], v[216:219], v[22:25]
	v_mfma_f32_16x16x32_bf16 v[22:25], v[180:183], v[220:223], v[22:25]
	v_mfma_f32_16x16x32_bf16 v[54:57], v[180:183], v[204:207], v[54:57]
	v_mfma_f32_16x16x32_bf16 v[54:57], v[176:179], v[200:203], v[54:57]
	v_mfma_f32_16x16x32_bf16 v[38:41], v[176:179], v[208:211], v[38:41]
	v_mfma_f32_16x16x32_bf16 v[38:41], v[180:183], v[212:215], v[38:41]
	v_mfma_f32_16x16x32_bf16 v[6:9], v[180:183], v[228:231], v[6:9]
	v_mfma_f32_16x16x32_bf16 v[6:9], v[176:179], v[224:227], v[6:9]
	v_mfma_f32_16x16x32_bf16 v[2:5], v[184:187], v[224:227], v[2:5]
	v_mfma_f32_16x16x32_bf16 v[2:5], v[188:191], v[228:231], v[2:5]
	v_mfma_f32_16x16x32_bf16 v[50:53], v[188:191], v[204:207], v[50:53]
	v_mfma_f32_16x16x32_bf16 v[50:53], v[184:187], v[200:203], v[50:53]
	v_mfma_f32_16x16x32_bf16 v[34:37], v[184:187], v[208:211], v[34:37]
	v_mfma_f32_16x16x32_bf16 v[34:37], v[188:191], v[212:215], v[34:37]
	v_mfma_f32_16x16x32_bf16 v[18:21], v[188:191], v[220:223], v[18:21]
	v_mfma_f32_16x16x32_bf16 v[18:21], v[184:187], v[216:219], v[18:21]
	s_barrier
	s_setprio 0
	s_add_i32 s74, 0, 0x18000
	v_add_u32_e32 v166, s74, v153
	s_add_i32 s75, 0, 0x1c000
	ds_read_b128 v[146:149], v166
	ds_read_b128 v[158:161], v166 offset:1024
	ds_read_b128 v[168:171], v166 offset:2048
	ds_read_b128 v[172:175], v166 offset:3072
	v_add_u32_e32 v166, s75, v153
	ds_read_b128 v[176:179], v166
	ds_read_b128 v[180:183], v166 offset:1024
	ds_read_b128 v[184:187], v166 offset:2048
	ds_read_b128 v[188:191], v166 offset:3072
	s_add_u32 s70, s70, 0x80000
	s_addc_u32 s71, s71, 0
	s_mov_b32 m0, s27
	v_lshl_add_u64 v[240:241], s[70:71], 0, v[136:137]
	ds_read_b128 v[200:203], v157 offset:32768
	ds_read_b128 v[204:207], v157 offset:33792
	ds_read_b128 v[208:211], v157 offset:34816
	ds_read_b128 v[212:215], v157 offset:35840
	ds_read_b128 v[216:219], v157 offset:36864
	ds_read_b128 v[220:223], v157 offset:37888
	ds_read_b128 v[224:227], v157 offset:38912
	ds_read_b128 v[228:231], v157 offset:39936
	global_load_lds_dwordx4 v[240:241], off
	v_lshl_add_u64 v[240:241], s[70:71], 0, v[132:133]
	s_mov_b32 m0, s28
	s_nop 0
	global_load_lds_dwordx4 v[240:241], off
	s_waitcnt vmcnt(8)
	s_waitcnt lgkmcnt(0)
	s_setprio 1
	s_barrier
	v_mfma_f32_16x16x32_bf16 v[126:129], v[146:149], v[200:203], v[126:129]
	v_mfma_f32_16x16x32_bf16 v[126:129], v[158:161], v[204:207], v[126:129]
	v_mfma_f32_16x16x32_bf16 v[110:113], v[158:161], v[212:215], v[110:113]
	v_mfma_f32_16x16x32_bf16 v[110:113], v[146:149], v[208:211], v[110:113]
	v_mfma_f32_16x16x32_bf16 v[94:97], v[146:149], v[216:219], v[94:97]
	v_mfma_f32_16x16x32_bf16 v[94:97], v[158:161], v[220:223], v[94:97]
	v_mfma_f32_16x16x32_bf16 v[78:81], v[158:161], v[228:231], v[78:81]
	v_mfma_f32_16x16x32_bf16 v[78:81], v[146:149], v[224:227], v[78:81]
	v_mfma_f32_16x16x32_bf16 v[74:77], v[168:171], v[224:227], v[74:77]
	v_mfma_f32_16x16x32_bf16 v[74:77], v[172:175], v[228:231], v[74:77]
	v_mfma_f32_16x16x32_bf16 v[122:125], v[172:175], v[204:207], v[122:125]
	v_mfma_f32_16x16x32_bf16 v[122:125], v[168:171], v[200:203], v[122:125]
	v_mfma_f32_16x16x32_bf16 v[106:109], v[168:171], v[208:211], v[106:109]
	v_mfma_f32_16x16x32_bf16 v[106:109], v[172:175], v[212:215], v[106:109]
	v_mfma_f32_16x16x32_bf16 v[90:93], v[172:175], v[220:223], v[90:93]
	v_mfma_f32_16x16x32_bf16 v[90:93], v[168:171], v[216:219], v[90:93]
	v_mfma_f32_16x16x32_bf16 v[86:89], v[176:179], v[216:219], v[86:89]
	v_mfma_f32_16x16x32_bf16 v[86:89], v[180:183], v[220:223], v[86:89]
	v_mfma_f32_16x16x32_bf16 v[118:121], v[180:183], v[204:207], v[118:121]
	v_mfma_f32_16x16x32_bf16 v[118:121], v[176:179], v[200:203], v[118:121]
	v_mfma_f32_16x16x32_bf16 v[102:105], v[176:179], v[208:211], v[102:105]
	v_mfma_f32_16x16x32_bf16 v[102:105], v[180:183], v[212:215], v[102:105]
	v_mfma_f32_16x16x32_bf16 v[70:73], v[180:183], v[228:231], v[70:73]
	v_mfma_f32_16x16x32_bf16 v[70:73], v[176:179], v[224:227], v[70:73]
	v_mfma_f32_16x16x32_bf16 v[66:69], v[184:187], v[224:227], v[66:69]
	v_mfma_f32_16x16x32_bf16 v[66:69], v[188:191], v[228:231], v[66:69]
	v_mfma_f32_16x16x32_bf16 v[114:117], v[188:191], v[204:207], v[114:117]
	v_mfma_f32_16x16x32_bf16 v[114:117], v[184:187], v[200:203], v[114:117]
	v_mfma_f32_16x16x32_bf16 v[98:101], v[184:187], v[208:211], v[98:101]
	v_mfma_f32_16x16x32_bf16 v[98:101], v[188:191], v[212:215], v[98:101]
	v_mfma_f32_16x16x32_bf16 v[82:85], v[188:191], v[220:223], v[82:85]
	v_mfma_f32_16x16x32_bf16 v[82:85], v[184:187], v[216:219], v[82:85]
	s_barrier
; #define PG8_STAGE(bufoff, gbase, voff) do { _Pragma("unroll") for (int _i = 0; _i < 2; ++_i) \
;         __builtin_amdgcn_global_load_lds((const unsigned*)((const char*)(gbase) + (voff)[_i]), (PG8_LAS unsigned*)(lds + (bufoff) + ldsw + _i * 8192), 16, 0, 0); } while (0)
; #define PG8_LDA(dst, b, h) do { _Pragma("unroll") for (int m = 0; m < 4; ++m) _Pragma("unroll") for (int k = 0; k < 2; ++k) dst[m][k] = *(const PG8_LAS bf16x8*)(lds + PG8_SA(b, h) + aoff + m * 2048 + k * 1024); } while (0)
; #define PG8_MMA(ai, bj, At, Bt) do { __builtin_amdgcn_s_setprio(1); _Pragma("unroll") for (int m = 0; m < 4; ++m) _Pragma("unroll") for (int n = 0; n < 2; ++n) _Pragma("unroll") for (int k = 0; k < 2; ++k) \
;         acc[ai][bj][m][n] = __builtin_amdgcn_mfma_f32_16x16x32_bf16(Bt[n][k], At[m][k], acc[ai][bj][m][n], 0, 0, 0); __builtin_amdgcn_s_setprio(0); } while (0)
; #define PG8_WAIT_V(n) asm volatile("s_waitcnt vmcnt(" #n ")" ::: "memory")
; #define PG8_WAIT_L(n) asm volatile("s_waitcnt lgkmcnt(" #n ")" ::: "memory")
; #define PG8_BAR __builtin_amdgcn_s_barrier()
; #define PG8_SCHED __builtin_amdgcn_sched_barrier(0)
; template <class Epi, class Sched, bool ALIGN_EPI = false, bool SP2 = false>
; __device__ __forceinline__ void gemm_phase(PG8_LAS unsigned char* lds, const Gemm g, const Sched& S, const Epi& E) {
;     ...
;             PG8_LDA(At, 1, 1); PG8_STAGE(PG8_SB(1, 0), b3, voffB); PG8_STAGE(PG8_SB(1, 1), b3 + hstep, voffB); PG8_STAGE(PG8_SA(1, 0), a3, voffA);
;             PG8_WAIT_V(8); PG8_WAIT_L(0); PG8_BAR; PG8_MMA(1, 0, At, B0); PG8_MMA(1, 1, At, B1); PG8_BAR; PG8_SCHED;
;     ...
;         if constexpr (ALIGN_EPI) { if (wr == 0) PG8_BAR; }
	s_setprio 0
	s_add_i32 s70, s74, s2
	v_lshl_add_u64 v[150:151], v[150:151], 0, s[8:9]
	s_mov_b32 m0, s70
	ds_read_b128 v[200:203], v157 offset:49152
	ds_read_b128 v[204:207], v157 offset:50176
	ds_read_b128 v[208:211], v157 offset:51200
	ds_read_b128 v[212:215], v157 offset:52224
	ds_read_b128 v[216:219], v157 offset:53248
	ds_read_b128 v[220:223], v157 offset:54272
	ds_read_b128 v[224:227], v157 offset:55296
	ds_read_b128 v[228:231], v157 offset:56320
	global_load_lds_dwordx4 v[150:151], off
	s_add_i32 m0, s70, 0x2000
	s_add_u32 s68, s68, 0x80080
	v_lshl_add_u64 v[150:151], v[162:163], 0, s[8:9]
	s_addc_u32 s69, s69, 0
	s_add_i32 s70, s75, s2
	global_load_lds_dwordx4 v[150:151], off
	v_lshl_add_u64 v[150:151], s[68:69], 0, v[134:135]
	s_mov_b32 m0, s70
	s_nop 0
	global_load_lds_dwordx4 v[150:151], off
	v_lshl_add_u64 v[150:151], s[68:69], 0, v[130:131]
	s_add_i32 m0, s70, 0x2000
	s_nop 0
	global_load_lds_dwordx4 v[150:151], off
	v_lshl_add_u64 v[150:151], v[192:193], 0, s[8:9]
	s_mov_b32 m0, s30
	s_nop 0
	global_load_lds_dwordx4 v[150:151], off
	v_lshl_add_u64 v[150:151], v[232:233], 0, s[8:9]
	s_mov_b32 m0, s33
	s_nop 0
	global_load_lds_dwordx4 v[150:151], off
	s_waitcnt vmcnt(8)
	s_waitcnt lgkmcnt(0)
	s_setprio 1
	s_barrier
	v_mfma_f32_16x16x32_bf16 v[62:65], v[146:149], v[200:203], v[62:65]
	v_mfma_f32_16x16x32_bf16 v[62:65], v[158:161], v[204:207], v[62:65]
	v_mfma_f32_16x16x32_bf16 v[46:49], v[158:161], v[212:215], v[46:49]
	v_mfma_f32_16x16x32_bf16 v[46:49], v[146:149], v[208:211], v[46:49]
	v_mfma_f32_16x16x32_bf16 v[30:33], v[146:149], v[216:219], v[30:33]
	v_mfma_f32_16x16x32_bf16 v[30:33], v[158:161], v[220:223], v[30:33]
	v_mfma_f32_16x16x32_bf16 v[14:17], v[158:161], v[228:231], v[14:17]
	v_mfma_f32_16x16x32_bf16 v[14:17], v[146:149], v[224:227], v[14:17]
	v_mfma_f32_16x16x32_bf16 v[10:13], v[168:171], v[224:227], v[10:13]
	v_mfma_f32_16x16x32_bf16 v[10:13], v[172:175], v[228:231], v[10:13]
	v_mfma_f32_16x16x32_bf16 v[58:61], v[172:175], v[204:207], v[58:61]
	v_mfma_f32_16x16x32_bf16 v[58:61], v[168:171], v[200:203], v[58:61]
	v_mfma_f32_16x16x32_bf16 v[42:45], v[168:171], v[208:211], v[42:45]
	v_mfma_f32_16x16x32_bf16 v[42:45], v[172:175], v[212:215], v[42:45]
	v_mfma_f32_16x16x32_bf16 v[26:29], v[172:175], v[220:223], v[26:29]
	v_mfma_f32_16x16x32_bf16 v[26:29], v[168:171], v[216:219], v[26:29]
	v_mfma_f32_16x16x32_bf16 v[22:25], v[176:179], v[216:219], v[22:25]
	v_mfma_f32_16x16x32_bf16 v[22:25], v[180:183], v[220:223], v[22:25]
	v_mfma_f32_16x16x32_bf16 v[54:57], v[180:183], v[204:207], v[54:57]
	v_mfma_f32_16x16x32_bf16 v[54:57], v[176:179], v[200:203], v[54:57]
	v_mfma_f32_16x16x32_bf16 v[38:41], v[176:179], v[208:211], v[38:41]
	v_mfma_f32_16x16x32_bf16 v[38:41], v[180:183], v[212:215], v[38:41]
	v_mfma_f32_16x16x32_bf16 v[6:9], v[180:183], v[228:231], v[6:9]
	v_mfma_f32_16x16x32_bf16 v[6:9], v[176:179], v[224:227], v[6:9]
	v_mfma_f32_16x16x32_bf16 v[2:5], v[184:187], v[224:227], v[2:5]
	v_mfma_f32_16x16x32_bf16 v[2:5], v[188:191], v[228:231], v[2:5]
	v_mfma_f32_16x16x32_bf16 v[50:53], v[188:191], v[204:207], v[50:53]
	v_mfma_f32_16x16x32_bf16 v[50:53], v[184:187], v[200:203], v[50:53]
	v_mfma_f32_16x16x32_bf16 v[34:37], v[184:187], v[208:211], v[34:37]
	v_mfma_f32_16x16x32_bf16 v[34:37], v[188:191], v[212:215], v[34:37]
	v_mfma_f32_16x16x32_bf16 v[18:21], v[188:191], v[220:223], v[18:21]
	v_mfma_f32_16x16x32_bf16 v[18:21], v[184:187], v[216:219], v[18:21]
	s_barrier
	s_setprio 0
	s_add_i32 s73, s73, 2
	s_add_u32 s66, s66, 0x100
	s_addc_u32 s67, s67, 0
	s_add_u32 s65, s65, 0x100
	s_addc_u32 s72, s72, 0
	s_cmp_gt_u32 s73, 29
	s_cbranch_scc0 .LBB0_1078
	s_and_b64 vcc, exec, s[10:11]
	s_cbranch_vccz .LBB0_1081
	s_barrier

; #define PG8_STAGE(bufoff, gbase, voff) do { _Pragma("unroll") for (int _i = 0; _i < 2; ++_i) \
;         __builtin_amdgcn_global_load_lds((const unsigned*)((const char*)(gbase) + (voff)[_i]), (PG8_LAS unsigned*)(lds + (bufoff) + ldsw + _i * 8192), 16, 0, 0); } while (0)
; #define PG8_LDA(dst, b, h) do { _Pragma("unroll") for (int m = 0; m < 4; ++m) _Pragma("unroll") for (int k = 0; k < 2; ++k) dst[m][k] = *(const PG8_LAS bf16x8*)(lds + PG8_SA(b, h) + aoff + m * 2048 + k * 1024); } while (0)
; #define PG8_LDB(dst, b, h) do { _Pragma("unroll") for (int n = 0; n < 2; ++n) _Pragma("unroll") for (int k = 0; k < 2; ++k) dst[n][k] = *(const PG8_LAS bf16x8*)(lds + PG8_SB(b, h) + boff + n * 2048 + k * 1024); } while (0)
; #define PG8_MMA(ai, bj, At, Bt) do { __builtin_amdgcn_s_setprio(1); _Pragma("unroll") for (int m = 0; m < 4; ++m) _Pragma("unroll") for (int n = 0; n < 2; ++n) _Pragma("unroll") for (int k = 0; k < 2; ++k) \
;         acc[ai][bj][m][n] = __builtin_amdgcn_mfma_f32_16x16x32_bf16(Bt[n][k], At[m][k], acc[ai][bj][m][n], 0, 0, 0); __builtin_amdgcn_s_setprio(0); } while (0)
; #define PG8_WAIT_V(n) asm volatile("s_waitcnt vmcnt(" #n ")" ::: "memory")
; #define PG8_WAIT_L(n) asm volatile("s_waitcnt lgkmcnt(" #n ")" ::: "memory")
; template <class Epi, class Sched, bool ALIGN_EPI = false, bool SP2 = false>
; __device__ __forceinline__ void gemm_phase(PG8_LAS unsigned char* lds, const Gemm g, const Sched& S, const Epi& E) {
;     ...
;             const bool last = (t == nt - 2);
;             const char* a1 = cA + (size_t)(t + 1) * kstep;
;             const char* a2 = last ? nA : cA + (size_t)(t + 2) * kstep; const char* b2 = last ? nB : cB + (size_t)(t + 2) * kstep;
;             const char* a3 = a2 + kstep; const char* b3 = b2 + kstep;
;             if (last && has_next) S.a_ready(nxt);
;             if constexpr (SP2) {
;             PG8_LDB(B0, 0, 0); PG8_LDB(B1, 0, 1); PG8_SCHED; PG8_LDA(At, 0, 0); PG8_STAGE(PG8_SA(1, 1), a1 + hstep, voffA);
;             PG8_WAIT_V(8); PG8_WAIT_L(0); PG8_BAR; PG8_MMA(0, 0, At, B0); PG8_MMA(0, 1, At, B1); PG8_BAR; PG8_SCHED;
;             PG8_LDA(At, 0, 1); PG8_STAGE(PG8_SB(0, 0), b2, voffB); PG8_STAGE(PG8_SB(0, 1), b2 + hstep, voffB); PG8_STAGE(PG8_SA(0, 0), a2, voffA);
;             PG8_WAIT_V(8); PG8_WAIT_L(0); PG8_BAR; PG8_MMA(1, 0, At, B0); PG8_MMA(1, 1, At, B1); PG8_BAR; PG8_SCHED;
.LBB0_1203:
	ds_read_b128 v[146:149], v171
	ds_read_b128 v[176:179], v171 offset:1024
	ds_read_b128 v[180:183], v171 offset:2048
	ds_read_b128 v[184:187], v171 offset:3072
	ds_read_b128 v[188:191], v172
	ds_read_b128 v[200:203], v172 offset:1024
	ds_read_b128 v[204:207], v172 offset:2048
	ds_read_b128 v[208:211], v172 offset:3072
	s_add_u32 s63, s64, 0xfff00080
	s_addc_u32 s66, s65, -1
	s_cmp_eq_u32 s61, 60
	s_cselect_b32 s69, s34, s66
	s_cselect_b32 s68, s35, s63
	s_cselect_b32 s67, s40, s55
	s_cselect_b32 s66, s41, s53
	v_lshl_add_u64 v[150:151], s[64:65], 0, v[138:139]
	s_add_i32 m0, s4, 0xc000
	ds_read_b128 v[212:215], v173
	ds_read_b128 v[216:219], v173 offset:1024
	ds_read_b128 v[220:223], v173 offset:2048
	ds_read_b128 v[224:227], v173 offset:3072
	ds_read_b128 v[228:231], v173 offset:4096
	ds_read_b128 v[240:243], v173 offset:5120
	ds_read_b128 v[244:247], v173 offset:6144
	ds_read_b128 v[248:251], v173 offset:7168
	global_load_lds_dwordx4 v[150:151], off
	v_lshl_add_u64 v[150:151], s[64:65], 0, v[140:141]
	s_add_i32 m0, s4, 0xe000
	s_nop 0
	global_load_lds_dwordx4 v[150:151], off
	s_waitcnt vmcnt(8)
	s_waitcnt lgkmcnt(0)
	s_setprio 1
	s_barrier
	v_mfma_f32_16x16x32_bf16 v[126:129], v[146:149], v[212:215], v[126:129]
	v_mfma_f32_16x16x32_bf16 v[126:129], v[176:179], v[216:219], v[126:129]
	v_mfma_f32_16x16x32_bf16 v[110:113], v[176:179], v[224:227], v[110:113]
	v_mfma_f32_16x16x32_bf16 v[110:113], v[146:149], v[220:223], v[110:113]
	v_mfma_f32_16x16x32_bf16 v[94:97], v[146:149], v[228:231], v[94:97]
	v_mfma_f32_16x16x32_bf16 v[94:97], v[176:179], v[240:243], v[94:97]
	v_mfma_f32_16x16x32_bf16 v[78:81], v[176:179], v[248:251], v[78:81]
	v_mfma_f32_16x16x32_bf16 v[78:81], v[146:149], v[244:247], v[78:81]
	v_mfma_f32_16x16x32_bf16 v[74:77], v[180:183], v[244:247], v[74:77]
	v_mfma_f32_16x16x32_bf16 v[74:77], v[184:187], v[248:251], v[74:77]
	v_mfma_f32_16x16x32_bf16 v[122:125], v[184:187], v[216:219], v[122:125]
	v_mfma_f32_16x16x32_bf16 v[122:125], v[180:183], v[212:215], v[122:125]
	v_mfma_f32_16x16x32_bf16 v[106:109], v[180:183], v[220:223], v[106:109]
	v_mfma_f32_16x16x32_bf16 v[106:109], v[184:187], v[224:227], v[106:109]
	v_mfma_f32_16x16x32_bf16 v[90:93], v[184:187], v[240:243], v[90:93]
	v_mfma_f32_16x16x32_bf16 v[90:93], v[180:183], v[228:231], v[90:93]
	v_mfma_f32_16x16x32_bf16 v[86:89], v[188:191], v[228:231], v[86:89]
	v_mfma_f32_16x16x32_bf16 v[86:89], v[200:203], v[240:243], v[86:89]
	v_mfma_f32_16x16x32_bf16 v[118:121], v[200:203], v[216:219], v[118:121]
	v_mfma_f32_16x16x32_bf16 v[118:121], v[188:191], v[212:215], v[118:121]
	v_mfma_f32_16x16x32_bf16 v[102:105], v[188:191], v[220:223], v[102:105]
	v_mfma_f32_16x16x32_bf16 v[102:105], v[200:203], v[224:227], v[102:105]
	v_mfma_f32_16x16x32_bf16 v[70:73], v[200:203], v[248:251], v[70:73]
	v_mfma_f32_16x16x32_bf16 v[70:73], v[188:191], v[244:247], v[70:73]
	v_mfma_f32_16x16x32_bf16 v[66:69], v[204:207], v[244:247], v[66:69]
	v_mfma_f32_16x16x32_bf16 v[66:69], v[208:211], v[248:251], v[66:69]
	v_mfma_f32_16x16x32_bf16 v[114:117], v[208:211], v[216:219], v[114:117]
	v_mfma_f32_16x16x32_bf16 v[114:117], v[204:207], v[212:215], v[114:117]
	v_mfma_f32_16x16x32_bf16 v[98:101], v[204:207], v[220:223], v[98:101]
	v_mfma_f32_16x16x32_bf16 v[98:101], v[208:211], v[224:227], v[98:101]
	v_mfma_f32_16x16x32_bf16 v[82:85], v[208:211], v[240:243], v[82:85]
	v_mfma_f32_16x16x32_bf16 v[82:85], v[204:207], v[228:231], v[82:85]
	s_barrier
	s_setprio 0
	s_add_i32 s63, s31, s2
	v_lshl_add_u64 v[150:151], s[66:67], 0, v[132:133]
	s_mov_b32 m0, s63
	ds_read_b128 v[212:215], v173 offset:16384
	ds_read_b128 v[216:219], v173 offset:17408
	ds_read_b128 v[220:223], v173 offset:18432
	ds_read_b128 v[224:227], v173 offset:19456
	ds_read_b128 v[228:231], v173 offset:20480
	ds_read_b128 v[240:243], v173 offset:21504
	ds_read_b128 v[244:247], v173 offset:22528
	ds_read_b128 v[248:251], v173 offset:23552
	global_load_lds_dwordx4 v[150:151], off
	s_add_i32 m0, s63, 0x2000
	s_add_u32 s70, s66, 0x100000
	v_lshl_add_u64 v[192:193], s[66:67], 0, v[136:137]
	s_addc_u32 s71, s67, 0
	s_add_i32 s63, s39, s2
	global_load_lds_dwordx4 v[192:193], off
	v_lshl_add_u64 v[232:233], s[70:71], 0, v[132:133]
	s_mov_b32 m0, s63
	v_lshl_add_u64 v[252:253], s[68:69], 0, v[134:135]
	global_load_lds_dwordx4 v[232:233], off
	v_lshl_add_u64 v[232:233], s[70:71], 0, v[136:137]
	s_add_i32 m0, s63, 0x2000
	s_nop 0
	global_load_lds_dwordx4 v[232:233], off
	v_lshl_add_u64 v[232:233], s[68:69], 0, v[130:131]
	s_mov_b32 m0, s4
	s_nop 0
	global_load_lds_dwordx4 v[232:233], off
	s_mov_b32 m0, s5
	s_nop 0
	global_load_lds_dwordx4 v[252:253], off
	s_waitcnt vmcnt(8)
	s_waitcnt lgkmcnt(0)
	s_setprio 1
	s_barrier
; #define PG8_STAGE(bufoff, gbase, voff) do { _Pragma("unroll") for (int _i = 0; _i < 2; ++_i) \
;         __builtin_amdgcn_global_load_lds((const unsigned*)((const char*)(gbase) + (voff)[_i]), (PG8_LAS unsigned*)(lds + (bufoff) + ldsw + _i * 8192), 16, 0, 0); } while (0)
; #define PG8_LDA(dst, b, h) do { _Pragma("unroll") for (int m = 0; m < 4; ++m) _Pragma("unroll") for (int k = 0; k < 2; ++k) dst[m][k] = *(const PG8_LAS bf16x8*)(lds + PG8_SA(b, h) + aoff + m * 2048 + k * 1024); } while (0)
; #define PG8_LDB(dst, b, h) do { _Pragma("unroll") for (int n = 0; n < 2; ++n) _Pragma("unroll") for (int k = 0; k < 2; ++k) dst[n][k] = *(const PG8_LAS bf16x8*)(lds + PG8_SB(b, h) + boff + n * 2048 + k * 1024); } while (0)
; #define PG8_MMA(ai, bj, At, Bt) do { __builtin_amdgcn_s_setprio(1); _Pragma("unroll") for (int m = 0; m < 4; ++m) _Pragma("unroll") for (int n = 0; n < 2; ++n) _Pragma("unroll") for (int k = 0; k < 2; ++k) \
;         acc[ai][bj][m][n] = __builtin_amdgcn_mfma_f32_16x16x32_bf16(Bt[n][k], At[m][k], acc[ai][bj][m][n], 0, 0, 0); __builtin_amdgcn_s_setprio(0); } while (0)
; #define PG8_WAIT_V(n) asm volatile("s_waitcnt vmcnt(" #n ")" ::: "memory")
; #define PG8_WAIT_L(n) asm volatile("s_waitcnt lgkmcnt(" #n ")" ::: "memory")
; #define PG8_BAR __builtin_amdgcn_s_barrier()
; #define PG8_SCHED __builtin_amdgcn_sched_barrier(0)
; template <class Epi, class Sched, bool ALIGN_EPI = false, bool SP2 = false>
; __device__ __forceinline__ void gemm_phase(PG8_LAS unsigned char* lds, const Gemm g, const Sched& S, const Epi& E) {
;     ...
;             PG8_WAIT_V(8); PG8_WAIT_L(0); PG8_BAR; PG8_MMA(1, 0, At, B0); PG8_MMA(1, 1, At, B1); PG8_BAR; PG8_SCHED;
;             PG8_LDB(B0, 1, 0); PG8_LDB(B1, 1, 1); PG8_SCHED; PG8_LDA(At, 1, 0); PG8_STAGE(PG8_SA(0, 1), a2 + hstep, voffA);
;             PG8_WAIT_V(8); PG8_WAIT_L(0); PG8_BAR; PG8_MMA(0, 0, At, B0); PG8_MMA(0, 1, At, B1); PG8_BAR; PG8_SCHED;
	v_mfma_f32_16x16x32_bf16 v[62:65], v[146:149], v[212:215], v[62:65]
	v_mfma_f32_16x16x32_bf16 v[62:65], v[176:179], v[216:219], v[62:65]
	v_mfma_f32_16x16x32_bf16 v[46:49], v[176:179], v[224:227], v[46:49]
	v_mfma_f32_16x16x32_bf16 v[46:49], v[146:149], v[220:223], v[46:49]
	v_mfma_f32_16x16x32_bf16 v[30:33], v[146:149], v[228:231], v[30:33]
	v_mfma_f32_16x16x32_bf16 v[30:33], v[176:179], v[240:243], v[30:33]
	v_mfma_f32_16x16x32_bf16 v[14:17], v[176:179], v[248:251], v[14:17]
	v_mfma_f32_16x16x32_bf16 v[14:17], v[146:149], v[244:247], v[14:17]
	v_mfma_f32_16x16x32_bf16 v[10:13], v[180:183], v[244:247], v[10:13]
	v_mfma_f32_16x16x32_bf16 v[10:13], v[184:187], v[248:251], v[10:13]
	v_mfma_f32_16x16x32_bf16 v[58:61], v[184:187], v[216:219], v[58:61]
	v_mfma_f32_16x16x32_bf16 v[58:61], v[180:183], v[212:215], v[58:61]
	v_mfma_f32_16x16x32_bf16 v[42:45], v[180:183], v[220:223], v[42:45]
	v_mfma_f32_16x16x32_bf16 v[42:45], v[184:187], v[224:227], v[42:45]
	v_mfma_f32_16x16x32_bf16 v[26:29], v[184:187], v[240:243], v[26:29]
	v_mfma_f32_16x16x32_bf16 v[26:29], v[180:183], v[228:231], v[26:29]
	v_mfma_f32_16x16x32_bf16 v[22:25], v[188:191], v[228:231], v[22:25]
	v_mfma_f32_16x16x32_bf16 v[22:25], v[200:203], v[240:243], v[22:25]
	v_mfma_f32_16x16x32_bf16 v[54:57], v[200:203], v[216:219], v[54:57]
	v_mfma_f32_16x16x32_bf16 v[54:57], v[188:191], v[212:215], v[54:57]
	v_mfma_f32_16x16x32_bf16 v[38:41], v[188:191], v[220:223], v[38:41]
	v_mfma_f32_16x16x32_bf16 v[38:41], v[200:203], v[224:227], v[38:41]
	v_mfma_f32_16x16x32_bf16 v[6:9], v[200:203], v[248:251], v[6:9]
	v_mfma_f32_16x16x32_bf16 v[6:9], v[188:191], v[244:247], v[6:9]
	v_mfma_f32_16x16x32_bf16 v[2:5], v[204:207], v[244:247], v[2:5]
	v_mfma_f32_16x16x32_bf16 v[2:5], v[208:211], v[248:251], v[2:5]
	v_mfma_f32_16x16x32_bf16 v[50:53], v[208:211], v[216:219], v[50:53]
	v_mfma_f32_16x16x32_bf16 v[50:53], v[204:207], v[212:215], v[50:53]
	v_mfma_f32_16x16x32_bf16 v[34:37], v[204:207], v[220:223], v[34:37]
	v_mfma_f32_16x16x32_bf16 v[34:37], v[208:211], v[224:227], v[34:37]
	v_mfma_f32_16x16x32_bf16 v[18:21], v[208:211], v[240:243], v[18:21]
	v_mfma_f32_16x16x32_bf16 v[18:21], v[204:207], v[228:231], v[18:21]
	s_barrier
	s_setprio 0
	s_add_i32 s63, 0, 0x18000
	v_add_u32_e32 v175, s63, v153
	s_add_i32 s70, 0, 0x1c000
	ds_read_b128 v[146:149], v175
	ds_read_b128 v[176:179], v175 offset:1024
	ds_read_b128 v[180:183], v175 offset:2048
	ds_read_b128 v[184:187], v175 offset:3072
	v_add_u32_e32 v175, s70, v153
	ds_read_b128 v[188:191], v175
	ds_read_b128 v[200:203], v175 offset:1024
	ds_read_b128 v[204:207], v175 offset:2048
	ds_read_b128 v[208:211], v175 offset:3072
	s_add_u32 s68, s68, 0x100000
	s_addc_u32 s69, s69, 0
	s_mov_b32 m0, s16
	v_lshl_add_u64 v[194:195], s[68:69], 0, v[130:131]
	ds_read_b128 v[212:215], v173 offset:32768
	ds_read_b128 v[216:219], v173 offset:33792
	ds_read_b128 v[220:223], v173 offset:34816
	ds_read_b128 v[224:227], v173 offset:35840
	ds_read_b128 v[228:231], v173 offset:36864
	ds_read_b128 v[240:243], v173 offset:37888
	ds_read_b128 v[244:247], v173 offset:38912
	ds_read_b128 v[248:251], v173 offset:39936
	global_load_lds_dwordx4 v[194:195], off
	v_lshl_add_u64 v[194:195], s[68:69], 0, v[134:135]
	s_mov_b32 m0, s17
	s_nop 0
	global_load_lds_dwordx4 v[194:195], off
	s_waitcnt vmcnt(8)
	s_waitcnt lgkmcnt(0)
	s_setprio 1
	s_barrier
	v_mfma_f32_16x16x32_bf16 v[126:129], v[146:149], v[212:215], v[126:129]
	v_mfma_f32_16x16x32_bf16 v[126:129], v[176:179], v[216:219], v[126:129]
	v_mfma_f32_16x16x32_bf16 v[110:113], v[176:179], v[224:227], v[110:113]
	v_mfma_f32_16x16x32_bf16 v[110:113], v[146:149], v[220:223], v[110:113]
	v_mfma_f32_16x16x32_bf16 v[94:97], v[146:149], v[228:231], v[94:97]
	v_mfma_f32_16x16x32_bf16 v[94:97], v[176:179], v[240:243], v[94:97]
	v_mfma_f32_16x16x32_bf16 v[78:81], v[176:179], v[248:251], v[78:81]
	v_mfma_f32_16x16x32_bf16 v[78:81], v[146:149], v[244:247], v[78:81]
	v_mfma_f32_16x16x32_bf16 v[74:77], v[180:183], v[244:247], v[74:77]
	v_mfma_f32_16x16x32_bf16 v[74:77], v[184:187], v[248:251], v[74:77]
	v_mfma_f32_16x16x32_bf16 v[122:125], v[184:187], v[216:219], v[122:125]
	v_mfma_f32_16x16x32_bf16 v[122:125], v[180:183], v[212:215], v[122:125]
	v_mfma_f32_16x16x32_bf16 v[106:109], v[180:183], v[220:223], v[106:109]
	v_mfma_f32_16x16x32_bf16 v[106:109], v[184:187], v[224:227], v[106:109]
	v_mfma_f32_16x16x32_bf16 v[90:93], v[184:187], v[240:243], v[90:93]
	v_mfma_f32_16x16x32_bf16 v[90:93], v[180:183], v[228:231], v[90:93]
	v_mfma_f32_16x16x32_bf16 v[86:89], v[188:191], v[228:231], v[86:89]
	v_mfma_f32_16x16x32_bf16 v[86:89], v[200:203], v[240:243], v[86:89]
	v_mfma_f32_16x16x32_bf16 v[118:121], v[200:203], v[216:219], v[118:121]
	v_mfma_f32_16x16x32_bf16 v[118:121], v[188:191], v[212:215], v[118:121]
	v_mfma_f32_16x16x32_bf16 v[102:105], v[188:191], v[220:223], v[102:105]
	v_mfma_f32_16x16x32_bf16 v[102:105], v[200:203], v[224:227], v[102:105]
	v_mfma_f32_16x16x32_bf16 v[70:73], v[200:203], v[248:251], v[70:73]
	v_mfma_f32_16x16x32_bf16 v[70:73], v[188:191], v[244:247], v[70:73]
	v_mfma_f32_16x16x32_bf16 v[66:69], v[204:207], v[244:247], v[66:69]
	v_mfma_f32_16x16x32_bf16 v[66:69], v[208:211], v[248:251], v[66:69]
	v_mfma_f32_16x16x32_bf16 v[114:117], v[208:211], v[216:219], v[114:117]
	v_mfma_f32_16x16x32_bf16 v[114:117], v[204:207], v[212:215], v[114:117]
	v_mfma_f32_16x16x32_bf16 v[98:101], v[204:207], v[220:223], v[98:101]
	v_mfma_f32_16x16x32_bf16 v[98:101], v[208:211], v[224:227], v[98:101]
	v_mfma_f32_16x16x32_bf16 v[82:85], v[208:211], v[240:243], v[82:85]
	v_mfma_f32_16x16x32_bf16 v[82:85], v[204:207], v[228:231], v[82:85]
	s_barrier
; #define PG8_STAGE(bufoff, gbase, voff) do { _Pragma("unroll") for (int _i = 0; _i < 2; ++_i) \
;         __builtin_amdgcn_global_load_lds((const unsigned*)((const char*)(gbase) + (voff)[_i]), (PG8_LAS unsigned*)(lds + (bufoff) + ldsw + _i * 8192), 16, 0, 0); } while (0)
; #define PG8_LDA(dst, b, h) do { _Pragma("unroll") for (int m = 0; m < 4; ++m) _Pragma("unroll") for (int k = 0; k < 2; ++k) dst[m][k] = *(const PG8_LAS bf16x8*)(lds + PG8_SA(b, h) + aoff + m * 2048 + k * 1024); } while (0)
; #define PG8_MMA(ai, bj, At, Bt) do { __builtin_amdgcn_s_setprio(1); _Pragma("unroll") for (int m = 0; m < 4; ++m) _Pragma("unroll") for (int n = 0; n < 2; ++n) _Pragma("unroll") for (int k = 0; k < 2; ++k) \
;         acc[ai][bj][m][n] = __builtin_amdgcn_mfma_f32_16x16x32_bf16(Bt[n][k], At[m][k], acc[ai][bj][m][n], 0, 0, 0); __builtin_amdgcn_s_setprio(0); } while (0)
; #define PG8_WAIT_V(n) asm volatile("s_waitcnt vmcnt(" #n ")" ::: "memory")
; #define PG8_WAIT_L(n) asm volatile("s_waitcnt lgkmcnt(" #n ")" ::: "memory")
; #define PG8_BAR __builtin_amdgcn_s_barrier()
; #define PG8_SCHED __builtin_amdgcn_sched_barrier(0)
; template <class Epi, class Sched, bool ALIGN_EPI = false, bool SP2 = false>
; __device__ __forceinline__ void gemm_phase(PG8_LAS unsigned char* lds, const Gemm g, const Sched& S, const Epi& E) {
;     ...
;             PG8_LDA(At, 1, 1); PG8_STAGE(PG8_SB(1, 0), b3, voffB); PG8_STAGE(PG8_SB(1, 1), b3 + hstep, voffB); PG8_STAGE(PG8_SA(1, 0), a3, voffA);
;             PG8_WAIT_V(8); PG8_WAIT_L(0); PG8_BAR; PG8_MMA(1, 0, At, B0); PG8_MMA(1, 1, At, B1); PG8_BAR; PG8_SCHED;
;     ...
;         if constexpr (ALIGN_EPI) { if (wr == 0) PG8_BAR; }
	s_setprio 0
	s_add_i32 s63, s63, s2
	v_lshl_add_u64 v[150:151], v[150:151], 0, s[44:45]
	s_mov_b32 m0, s63
	ds_read_b128 v[212:215], v173 offset:49152
	ds_read_b128 v[216:219], v173 offset:50176
	ds_read_b128 v[220:223], v173 offset:51200
	ds_read_b128 v[224:227], v173 offset:52224
	ds_read_b128 v[228:231], v173 offset:53248
	ds_read_b128 v[240:243], v173 offset:54272
	ds_read_b128 v[244:247], v173 offset:55296
	ds_read_b128 v[248:251], v173 offset:56320
	global_load_lds_dwordx4 v[150:151], off
	s_add_i32 m0, s63, 0x2000
	s_add_u32 s66, s66, 0x100080
	v_lshl_add_u64 v[150:151], v[192:193], 0, s[44:45]
	s_addc_u32 s67, s67, 0
	s_add_i32 s63, s70, s2
	global_load_lds_dwordx4 v[150:151], off
	v_lshl_add_u64 v[150:151], s[66:67], 0, v[132:133]
	s_mov_b32 m0, s63
	s_nop 0
	global_load_lds_dwordx4 v[150:151], off
	v_lshl_add_u64 v[150:151], s[66:67], 0, v[136:137]
	s_add_i32 m0, s63, 0x2000
	s_nop 0
	global_load_lds_dwordx4 v[150:151], off
	v_lshl_add_u64 v[150:151], v[232:233], 0, s[44:45]
	s_mov_b32 m0, s26
	s_nop 0
	global_load_lds_dwordx4 v[150:151], off
	v_lshl_add_u64 v[150:151], v[252:253], 0, s[44:45]
	s_mov_b32 m0, s27
	s_nop 0
	global_load_lds_dwordx4 v[150:151], off
	s_waitcnt vmcnt(8)
	s_waitcnt lgkmcnt(0)
	s_setprio 1
	s_barrier
	v_mfma_f32_16x16x32_bf16 v[62:65], v[146:149], v[212:215], v[62:65]
	v_mfma_f32_16x16x32_bf16 v[62:65], v[176:179], v[216:219], v[62:65]
	v_mfma_f32_16x16x32_bf16 v[46:49], v[176:179], v[224:227], v[46:49]
	v_mfma_f32_16x16x32_bf16 v[46:49], v[146:149], v[220:223], v[46:49]
	v_mfma_f32_16x16x32_bf16 v[30:33], v[146:149], v[228:231], v[30:33]
	v_mfma_f32_16x16x32_bf16 v[30:33], v[176:179], v[240:243], v[30:33]
	v_mfma_f32_16x16x32_bf16 v[14:17], v[176:179], v[248:251], v[14:17]
	v_mfma_f32_16x16x32_bf16 v[14:17], v[146:149], v[244:247], v[14:17]
	v_mfma_f32_16x16x32_bf16 v[10:13], v[180:183], v[244:247], v[10:13]
	v_mfma_f32_16x16x32_bf16 v[10:13], v[184:187], v[248:251], v[10:13]
	v_mfma_f32_16x16x32_bf16 v[58:61], v[184:187], v[216:219], v[58:61]
	v_mfma_f32_16x16x32_bf16 v[58:61], v[180:183], v[212:215], v[58:61]
	v_mfma_f32_16x16x32_bf16 v[42:45], v[180:183], v[220:223], v[42:45]
	v_mfma_f32_16x16x32_bf16 v[42:45], v[184:187], v[224:227], v[42:45]
	v_mfma_f32_16x16x32_bf16 v[26:29], v[184:187], v[240:243], v[26:29]
	v_mfma_f32_16x16x32_bf16 v[26:29], v[180:183], v[228:231], v[26:29]
	v_mfma_f32_16x16x32_bf16 v[22:25], v[188:191], v[228:231], v[22:25]
	v_mfma_f32_16x16x32_bf16 v[22:25], v[200:203], v[240:243], v[22:25]
	v_mfma_f32_16x16x32_bf16 v[54:57], v[200:203], v[216:219], v[54:57]
	v_mfma_f32_16x16x32_bf16 v[54:57], v[188:191], v[212:215], v[54:57]
	v_mfma_f32_16x16x32_bf16 v[38:41], v[188:191], v[220:223], v[38:41]
	v_mfma_f32_16x16x32_bf16 v[38:41], v[200:203], v[224:227], v[38:41]
	v_mfma_f32_16x16x32_bf16 v[6:9], v[200:203], v[248:251], v[6:9]
	v_mfma_f32_16x16x32_bf16 v[6:9], v[188:191], v[244:247], v[6:9]
	v_mfma_f32_16x16x32_bf16 v[2:5], v[204:207], v[244:247], v[2:5]
	v_mfma_f32_16x16x32_bf16 v[2:5], v[208:211], v[248:251], v[2:5]
	v_mfma_f32_16x16x32_bf16 v[50:53], v[208:211], v[216:219], v[50:53]
	v_mfma_f32_16x16x32_bf16 v[50:53], v[204:207], v[212:215], v[50:53]
	v_mfma_f32_16x16x32_bf16 v[34:37], v[204:207], v[220:223], v[34:37]
	v_mfma_f32_16x16x32_bf16 v[34:37], v[208:211], v[224:227], v[34:37]
	v_mfma_f32_16x16x32_bf16 v[18:21], v[208:211], v[240:243], v[18:21]
	v_mfma_f32_16x16x32_bf16 v[18:21], v[204:207], v[228:231], v[18:21]
	s_barrier
	s_setprio 0
	s_add_i32 s61, s61, 2
	s_add_u32 s64, s64, 0x100
	s_addc_u32 s65, s65, 0
	s_add_u32 s53, s53, 0x100
	s_addc_u32 s55, s55, 0
	s_cmp_gt_u32 s61, 61
	s_cbranch_scc0 .LBB0_1203
	s_and_b64 vcc, exec, s[46:47]
	s_cbranch_vccz .LBB0_1206
	s_barrier

; #define PG8_STAGE(bufoff, gbase, voff) do { _Pragma("unroll") for (int _i = 0; _i < 2; ++_i) \
;         __builtin_amdgcn_global_load_lds((const unsigned*)((const char*)(gbase) + (voff)[_i]), (PG8_LAS unsigned*)(lds + (bufoff) + ldsw + _i * 8192), 16, 0, 0); } while (0)
; #define PG8_LDA(dst, b, h) do { _Pragma("unroll") for (int m = 0; m < 4; ++m) _Pragma("unroll") for (int k = 0; k < 2; ++k) dst[m][k] = *(const PG8_LAS bf16x8*)(lds + PG8_SA(b, h) + aoff + m * 2048 + k * 1024); } while (0)
; #define PG8_LDB(dst, b, h) do { _Pragma("unroll") for (int n = 0; n < 2; ++n) _Pragma("unroll") for (int k = 0; k < 2; ++k) dst[n][k] = *(const PG8_LAS bf16x8*)(lds + PG8_SB(b, h) + boff + n * 2048 + k * 1024); } while (0)
; #define PG8_MMA(ai, bj, At, Bt) do { __builtin_amdgcn_s_setprio(1); _Pragma("unroll") for (int m = 0; m < 4; ++m) _Pragma("unroll") for (int n = 0; n < 2; ++n) _Pragma("unroll") for (int k = 0; k < 2; ++k) \
;         acc[ai][bj][m][n] = __builtin_amdgcn_mfma_f32_16x16x32_bf16(Bt[n][k], At[m][k], acc[ai][bj][m][n], 0, 0, 0); __builtin_amdgcn_s_setprio(0); } while (0)
; #define PG8_WAIT_V(n) asm volatile("s_waitcnt vmcnt(" #n ")" ::: "memory")
; #define PG8_WAIT_L(n) asm volatile("s_waitcnt lgkmcnt(" #n ")" ::: "memory")
; template <class Epi, class Sched, bool ALIGN_EPI = false, bool SP2 = false>
; __device__ __forceinline__ void gemm_phase(PG8_LAS unsigned char* lds, const Gemm g, const Sched& S, const Epi& E) {
;     ...
;             const bool last = (t == nt - 2);
;             const char* a1 = cA + (size_t)(t + 1) * kstep;
;             const char* a2 = last ? nA : cA + (size_t)(t + 2) * kstep; const char* b2 = last ? nB : cB + (size_t)(t + 2) * kstep;
;             const char* a3 = a2 + kstep; const char* b3 = b2 + kstep;
;             if (last && has_next) S.a_ready(nxt);
;             if constexpr (SP2) {
;             PG8_LDB(B0, 0, 0); PG8_LDB(B1, 0, 1); PG8_SCHED; PG8_LDA(At, 0, 0); PG8_STAGE(PG8_SA(1, 1), a1 + hstep, voffA);
;             PG8_WAIT_V(8); PG8_WAIT_L(0); PG8_BAR; PG8_MMA(0, 0, At, B0); PG8_MMA(0, 1, At, B1); PG8_BAR; PG8_SCHED;
;             PG8_LDA(At, 0, 1); PG8_STAGE(PG8_SB(0, 0), b2, voffB); PG8_STAGE(PG8_SB(0, 1), b2 + hstep, voffB); PG8_STAGE(PG8_SA(0, 0), a2, voffA);
;             PG8_WAIT_V(8); PG8_WAIT_L(0); PG8_BAR; PG8_MMA(1, 0, At, B0); PG8_MMA(1, 1, At, B1); PG8_BAR; PG8_SCHED;
.LBB0_1230:
	ds_read_b128 v[146:149], v140
	ds_read_b128 v[150:153], v140 offset:1024
	ds_read_b128 v[154:157], v140 offset:2048
	ds_read_b128 v[158:161], v140 offset:3072
	ds_read_b128 v[168:171], v141
	ds_read_b128 v[172:175], v141 offset:1024
	ds_read_b128 v[176:179], v141 offset:2048
	ds_read_b128 v[180:183], v141 offset:3072
	s_add_u32 s50, s46, 0x100
	s_addc_u32 s51, s47, 0
	s_cmp_lg_u32 s30, 12
	s_cselect_b32 s52, s50, 0
	s_cselect_b32 s53, s51, 0
	s_add_u32 s54, s10, s52
	s_addc_u32 s55, s11, s53
	s_add_u32 s52, s8, s52
	s_addc_u32 s53, s9, s53
	s_mov_b32 m0, s33
	v_lshl_add_u64 v[162:163], v[134:135], 0, s[46:47]
	ds_read_b128 v[184:187], v142
	ds_read_b128 v[188:191], v142 offset:1024
	ds_read_b128 v[200:203], v142 offset:2048
	ds_read_b128 v[204:207], v142 offset:3072
	ds_read_b128 v[208:211], v142 offset:4096
	ds_read_b128 v[212:215], v142 offset:5120
	ds_read_b128 v[216:219], v142 offset:6144
	ds_read_b128 v[220:223], v142 offset:7168
	global_load_lds_dwordx4 v[162:163], off
	v_lshl_add_u64 v[162:163], v[136:137], 0, s[46:47]
	s_mov_b32 m0, s34
	s_nop 0
	global_load_lds_dwordx4 v[162:163], off
	s_waitcnt vmcnt(8)
	s_waitcnt lgkmcnt(0)
	s_setprio 1
	s_barrier
	v_mfma_f32_16x16x32_bf16 v[126:129], v[146:149], v[184:187], v[126:129]
	v_mfma_f32_16x16x32_bf16 v[126:129], v[150:153], v[188:191], v[126:129]
	v_mfma_f32_16x16x32_bf16 v[118:121], v[150:153], v[204:207], v[118:121]
	v_mfma_f32_16x16x32_bf16 v[118:121], v[146:149], v[200:203], v[118:121]
	v_mfma_f32_16x16x32_bf16 v[106:109], v[146:149], v[208:211], v[106:109]
	v_mfma_f32_16x16x32_bf16 v[106:109], v[150:153], v[212:215], v[106:109]
	v_mfma_f32_16x16x32_bf16 v[90:93], v[150:153], v[220:223], v[90:93]
	v_mfma_f32_16x16x32_bf16 v[90:93], v[146:149], v[216:219], v[90:93]
	v_mfma_f32_16x16x32_bf16 v[82:85], v[154:157], v[216:219], v[82:85]
	v_mfma_f32_16x16x32_bf16 v[82:85], v[158:161], v[220:223], v[82:85]
	v_mfma_f32_16x16x32_bf16 v[122:125], v[158:161], v[188:191], v[122:125]
	v_mfma_f32_16x16x32_bf16 v[122:125], v[154:157], v[184:187], v[122:125]
	v_mfma_f32_16x16x32_bf16 v[114:117], v[154:157], v[200:203], v[114:117]
	v_mfma_f32_16x16x32_bf16 v[114:117], v[158:161], v[204:207], v[114:117]
	v_mfma_f32_16x16x32_bf16 v[98:101], v[158:161], v[212:215], v[98:101]
	v_mfma_f32_16x16x32_bf16 v[98:101], v[154:157], v[208:211], v[98:101]
	v_mfma_f32_16x16x32_bf16 v[78:81], v[168:171], v[208:211], v[78:81]
	v_mfma_f32_16x16x32_bf16 v[78:81], v[172:175], v[212:215], v[78:81]
	v_mfma_f32_16x16x32_bf16 v[110:113], v[172:175], v[188:191], v[110:113]
	v_mfma_f32_16x16x32_bf16 v[110:113], v[168:171], v[184:187], v[110:113]
	v_mfma_f32_16x16x32_bf16 v[94:97], v[168:171], v[200:203], v[94:97]
	v_mfma_f32_16x16x32_bf16 v[94:97], v[172:175], v[204:207], v[94:97]
	v_mfma_f32_16x16x32_bf16 v[70:73], v[172:175], v[220:223], v[70:73]
	v_mfma_f32_16x16x32_bf16 v[70:73], v[168:171], v[216:219], v[70:73]
	v_mfma_f32_16x16x32_bf16 v[66:69], v[176:179], v[216:219], v[66:69]
	v_mfma_f32_16x16x32_bf16 v[66:69], v[180:183], v[220:223], v[66:69]
	v_mfma_f32_16x16x32_bf16 v[102:105], v[180:183], v[188:191], v[102:105]
	v_mfma_f32_16x16x32_bf16 v[102:105], v[176:179], v[184:187], v[102:105]
	v_mfma_f32_16x16x32_bf16 v[86:89], v[176:179], v[200:203], v[86:89]
	v_mfma_f32_16x16x32_bf16 v[86:89], v[180:183], v[204:207], v[86:89]
	v_mfma_f32_16x16x32_bf16 v[74:77], v[180:183], v[212:215], v[74:77]
	v_mfma_f32_16x16x32_bf16 v[74:77], v[176:179], v[208:211], v[74:77]
	s_barrier
	s_setprio 0
	s_mov_b32 m0, s35
	v_lshl_add_u64 v[162:163], s[52:53], 0, v[130:131]
	s_add_u32 s46, s52, 0x100000
	ds_read_b128 v[184:187], v142 offset:16384
	ds_read_b128 v[188:191], v142 offset:17408
	ds_read_b128 v[200:203], v142 offset:18432
	ds_read_b128 v[204:207], v142 offset:19456
	ds_read_b128 v[208:211], v142 offset:20480
	ds_read_b128 v[212:215], v142 offset:21504
	ds_read_b128 v[216:219], v142 offset:22528
	ds_read_b128 v[220:223], v142 offset:23552
	global_load_lds_dwordx4 v[162:163], off
	v_lshl_add_u64 v[192:193], s[52:53], 0, v[132:133]
	s_mov_b32 m0, s39
	s_addc_u32 s47, s53, 0
	global_load_lds_dwordx4 v[192:193], off
	v_lshl_add_u64 v[194:195], s[46:47], 0, v[130:131]
	s_mov_b32 m0, s40
	v_lshl_add_u64 v[224:225], s[54:55], 0, v[132:133]
	global_load_lds_dwordx4 v[194:195], off
	v_lshl_add_u64 v[194:195], s[46:47], 0, v[132:133]
	s_mov_b32 m0, s41
	s_nop 0
	global_load_lds_dwordx4 v[194:195], off
	v_lshl_add_u64 v[194:195], s[54:55], 0, v[130:131]
	s_mov_b32 m0, s7
	s_nop 0
	global_load_lds_dwordx4 v[194:195], off
	s_mov_b32 m0, s16
	s_nop 0
	global_load_lds_dwordx4 v[224:225], off
	s_waitcnt vmcnt(8)
	s_waitcnt lgkmcnt(0)
	s_setprio 1
	s_barrier
; #define PG8_STAGE(bufoff, gbase, voff) do { _Pragma("unroll") for (int _i = 0; _i < 2; ++_i) \
;         __builtin_amdgcn_global_load_lds((const unsigned*)((const char*)(gbase) + (voff)[_i]), (PG8_LAS unsigned*)(lds + (bufoff) + ldsw + _i * 8192), 16, 0, 0); } while (0)
; #define PG8_LDA(dst, b, h) do { _Pragma("unroll") for (int m = 0; m < 4; ++m) _Pragma("unroll") for (int k = 0; k < 2; ++k) dst[m][k] = *(const PG8_LAS bf16x8*)(lds + PG8_SA(b, h) + aoff + m * 2048 + k * 1024); } while (0)
; #define PG8_LDB(dst, b, h) do { _Pragma("unroll") for (int n = 0; n < 2; ++n) _Pragma("unroll") for (int k = 0; k < 2; ++k) dst[n][k] = *(const PG8_LAS bf16x8*)(lds + PG8_SB(b, h) + boff + n * 2048 + k * 1024); } while (0)
; #define PG8_MMA(ai, bj, At, Bt) do { __builtin_amdgcn_s_setprio(1); _Pragma("unroll") for (int m = 0; m < 4; ++m) _Pragma("unroll") for (int n = 0; n < 2; ++n) _Pragma("unroll") for (int k = 0; k < 2; ++k) \
;         acc[ai][bj][m][n] = __builtin_amdgcn_mfma_f32_16x16x32_bf16(Bt[n][k], At[m][k], acc[ai][bj][m][n], 0, 0, 0); __builtin_amdgcn_s_setprio(0); } while (0)
; #define PG8_WAIT_V(n) asm volatile("s_waitcnt vmcnt(" #n ")" ::: "memory")
; #define PG8_WAIT_L(n) asm volatile("s_waitcnt lgkmcnt(" #n ")" ::: "memory")
; #define PG8_BAR __builtin_amdgcn_s_barrier()
; #define PG8_SCHED __builtin_amdgcn_sched_barrier(0)
; template <class Epi, class Sched, bool ALIGN_EPI = false, bool SP2 = false>
; __device__ __forceinline__ void gemm_phase(PG8_LAS unsigned char* lds, const Gemm g, const Sched& S, const Epi& E) {
;     ...
;             PG8_WAIT_V(8); PG8_WAIT_L(0); PG8_BAR; PG8_MMA(1, 0, At, B0); PG8_MMA(1, 1, At, B1); PG8_BAR; PG8_SCHED;
;             PG8_LDB(B0, 1, 0); PG8_LDB(B1, 1, 1); PG8_SCHED; PG8_LDA(At, 1, 0); PG8_STAGE(PG8_SA(0, 1), a2 + hstep, voffA);
;             PG8_WAIT_V(8); PG8_WAIT_L(0); PG8_BAR; PG8_MMA(0, 0, At, B0); PG8_MMA(0, 1, At, B1); PG8_BAR; PG8_SCHED;
	v_mfma_f32_16x16x32_bf16 v[62:65], v[146:149], v[184:187], v[62:65]
	v_mfma_f32_16x16x32_bf16 v[62:65], v[150:153], v[188:191], v[62:65]
	v_mfma_f32_16x16x32_bf16 v[54:57], v[150:153], v[204:207], v[54:57]
	v_mfma_f32_16x16x32_bf16 v[54:57], v[146:149], v[200:203], v[54:57]
	v_mfma_f32_16x16x32_bf16 v[42:45], v[146:149], v[208:211], v[42:45]
	v_mfma_f32_16x16x32_bf16 v[42:45], v[150:153], v[212:215], v[42:45]
	v_mfma_f32_16x16x32_bf16 v[26:29], v[150:153], v[220:223], v[26:29]
	v_mfma_f32_16x16x32_bf16 v[26:29], v[146:149], v[216:219], v[26:29]
	v_mfma_f32_16x16x32_bf16 v[18:21], v[154:157], v[216:219], v[18:21]
	v_mfma_f32_16x16x32_bf16 v[18:21], v[158:161], v[220:223], v[18:21]
	v_mfma_f32_16x16x32_bf16 v[58:61], v[158:161], v[188:191], v[58:61]
	v_mfma_f32_16x16x32_bf16 v[58:61], v[154:157], v[184:187], v[58:61]
	v_mfma_f32_16x16x32_bf16 v[50:53], v[154:157], v[200:203], v[50:53]
	v_mfma_f32_16x16x32_bf16 v[50:53], v[158:161], v[204:207], v[50:53]
	v_mfma_f32_16x16x32_bf16 v[34:37], v[158:161], v[212:215], v[34:37]
	v_mfma_f32_16x16x32_bf16 v[34:37], v[154:157], v[208:211], v[34:37]
	v_mfma_f32_16x16x32_bf16 v[14:17], v[168:171], v[208:211], v[14:17]
	v_mfma_f32_16x16x32_bf16 v[14:17], v[172:175], v[212:215], v[14:17]
	v_mfma_f32_16x16x32_bf16 v[46:49], v[172:175], v[188:191], v[46:49]
	v_mfma_f32_16x16x32_bf16 v[46:49], v[168:171], v[184:187], v[46:49]
	v_mfma_f32_16x16x32_bf16 v[30:33], v[168:171], v[200:203], v[30:33]
	v_mfma_f32_16x16x32_bf16 v[30:33], v[172:175], v[204:207], v[30:33]
	v_mfma_f32_16x16x32_bf16 v[6:9], v[172:175], v[220:223], v[6:9]
	v_mfma_f32_16x16x32_bf16 v[6:9], v[168:171], v[216:219], v[6:9]
	v_mfma_f32_16x16x32_bf16 v[2:5], v[176:179], v[216:219], v[2:5]
	v_mfma_f32_16x16x32_bf16 v[2:5], v[180:183], v[220:223], v[2:5]
	v_mfma_f32_16x16x32_bf16 v[38:41], v[180:183], v[188:191], v[38:41]
	v_mfma_f32_16x16x32_bf16 v[38:41], v[176:179], v[184:187], v[38:41]
	v_mfma_f32_16x16x32_bf16 v[22:25], v[176:179], v[200:203], v[22:25]
	v_mfma_f32_16x16x32_bf16 v[22:25], v[180:183], v[204:207], v[22:25]
	v_mfma_f32_16x16x32_bf16 v[10:13], v[180:183], v[212:215], v[10:13]
	v_mfma_f32_16x16x32_bf16 v[10:13], v[176:179], v[208:211], v[10:13]
	s_barrier
	s_setprio 0
	ds_read_b128 v[146:149], v143
	ds_read_b128 v[150:153], v143 offset:1024
	ds_read_b128 v[154:157], v143 offset:2048
	ds_read_b128 v[158:161], v143 offset:3072
	ds_read_b128 v[168:171], v144
	ds_read_b128 v[172:175], v144 offset:1024
	ds_read_b128 v[176:179], v144 offset:2048
	ds_read_b128 v[180:183], v144 offset:3072
	s_add_u32 s46, s54, 0x100000
	s_addc_u32 s47, s55, 0
	s_mov_b32 m0, s17
	v_lshl_add_u64 v[226:227], s[46:47], 0, v[130:131]
	ds_read_b128 v[184:187], v142 offset:32768
	ds_read_b128 v[188:191], v142 offset:33792
	ds_read_b128 v[200:203], v142 offset:34816
	ds_read_b128 v[204:207], v142 offset:35840
	ds_read_b128 v[208:211], v142 offset:36864
	ds_read_b128 v[212:215], v142 offset:37888
	ds_read_b128 v[216:219], v142 offset:38912
	ds_read_b128 v[220:223], v142 offset:39936
	global_load_lds_dwordx4 v[226:227], off
	v_lshl_add_u64 v[226:227], s[46:47], 0, v[132:133]
	s_mov_b32 m0, s26
	s_nop 0
	global_load_lds_dwordx4 v[226:227], off
	s_waitcnt vmcnt(8)
	s_waitcnt lgkmcnt(0)
	s_setprio 1
	s_barrier
	v_mfma_f32_16x16x32_bf16 v[126:129], v[146:149], v[184:187], v[126:129]
	v_mfma_f32_16x16x32_bf16 v[126:129], v[150:153], v[188:191], v[126:129]
	v_mfma_f32_16x16x32_bf16 v[118:121], v[150:153], v[204:207], v[118:121]
	v_mfma_f32_16x16x32_bf16 v[118:121], v[146:149], v[200:203], v[118:121]
	v_mfma_f32_16x16x32_bf16 v[106:109], v[146:149], v[208:211], v[106:109]
	v_mfma_f32_16x16x32_bf16 v[106:109], v[150:153], v[212:215], v[106:109]
	v_mfma_f32_16x16x32_bf16 v[90:93], v[150:153], v[220:223], v[90:93]
	v_mfma_f32_16x16x32_bf16 v[90:93], v[146:149], v[216:219], v[90:93]
	v_mfma_f32_16x16x32_bf16 v[82:85], v[154:157], v[216:219], v[82:85]
	v_mfma_f32_16x16x32_bf16 v[82:85], v[158:161], v[220:223], v[82:85]
	v_mfma_f32_16x16x32_bf16 v[122:125], v[158:161], v[188:191], v[122:125]
	v_mfma_f32_16x16x32_bf16 v[122:125], v[154:157], v[184:187], v[122:125]
	v_mfma_f32_16x16x32_bf16 v[114:117], v[154:157], v[200:203], v[114:117]
	v_mfma_f32_16x16x32_bf16 v[114:117], v[158:161], v[204:207], v[114:117]
	v_mfma_f32_16x16x32_bf16 v[98:101], v[158:161], v[212:215], v[98:101]
	v_mfma_f32_16x16x32_bf16 v[98:101], v[154:157], v[208:211], v[98:101]
	v_mfma_f32_16x16x32_bf16 v[78:81], v[168:171], v[208:211], v[78:81]
	v_mfma_f32_16x16x32_bf16 v[78:81], v[172:175], v[212:215], v[78:81]
	v_mfma_f32_16x16x32_bf16 v[110:113], v[172:175], v[188:191], v[110:113]
	v_mfma_f32_16x16x32_bf16 v[110:113], v[168:171], v[184:187], v[110:113]
	v_mfma_f32_16x16x32_bf16 v[94:97], v[168:171], v[200:203], v[94:97]
	v_mfma_f32_16x16x32_bf16 v[94:97], v[172:175], v[204:207], v[94:97]
	v_mfma_f32_16x16x32_bf16 v[70:73], v[172:175], v[220:223], v[70:73]
	v_mfma_f32_16x16x32_bf16 v[70:73], v[168:171], v[216:219], v[70:73]
	v_mfma_f32_16x16x32_bf16 v[66:69], v[176:179], v[216:219], v[66:69]
	v_mfma_f32_16x16x32_bf16 v[66:69], v[180:183], v[220:223], v[66:69]
	v_mfma_f32_16x16x32_bf16 v[102:105], v[180:183], v[188:191], v[102:105]
	v_mfma_f32_16x16x32_bf16 v[102:105], v[176:179], v[184:187], v[102:105]
	v_mfma_f32_16x16x32_bf16 v[86:89], v[176:179], v[200:203], v[86:89]
	v_mfma_f32_16x16x32_bf16 v[86:89], v[180:183], v[204:207], v[86:89]
	v_mfma_f32_16x16x32_bf16 v[74:77], v[180:183], v[212:215], v[74:77]
	v_mfma_f32_16x16x32_bf16 v[74:77], v[176:179], v[208:211], v[74:77]
	s_barrier
; #define PG8_STAGE(bufoff, gbase, voff) do { _Pragma("unroll") for (int _i = 0; _i < 2; ++_i) \
;         __builtin_amdgcn_global_load_lds((const unsigned*)((const char*)(gbase) + (voff)[_i]), (PG8_LAS unsigned*)(lds + (bufoff) + ldsw + _i * 8192), 16, 0, 0); } while (0)
; #define PG8_LDA(dst, b, h) do { _Pragma("unroll") for (int m = 0; m < 4; ++m) _Pragma("unroll") for (int k = 0; k < 2; ++k) dst[m][k] = *(const PG8_LAS bf16x8*)(lds + PG8_SA(b, h) + aoff + m * 2048 + k * 1024); } while (0)
; #define PG8_MMA(ai, bj, At, Bt) do { __builtin_amdgcn_s_setprio(1); _Pragma("unroll") for (int m = 0; m < 4; ++m) _Pragma("unroll") for (int n = 0; n < 2; ++n) _Pragma("unroll") for (int k = 0; k < 2; ++k) \
;         acc[ai][bj][m][n] = __builtin_amdgcn_mfma_f32_16x16x32_bf16(Bt[n][k], At[m][k], acc[ai][bj][m][n], 0, 0, 0); __builtin_amdgcn_s_setprio(0); } while (0)
; #define PG8_WAIT_V(n) asm volatile("s_waitcnt vmcnt(" #n ")" ::: "memory")
; #define PG8_WAIT_L(n) asm volatile("s_waitcnt lgkmcnt(" #n ")" ::: "memory")
; #define PG8_BAR __builtin_amdgcn_s_barrier()
; #define PG8_SCHED __builtin_amdgcn_sched_barrier(0)
; template <class Epi, class Sched, bool ALIGN_EPI = false, bool SP2 = false>
; __device__ __forceinline__ void gemm_phase(PG8_LAS unsigned char* lds, const Gemm g, const Sched& S, const Epi& E) {
;     ...
;         for (int t = 0; t < nt; t += 2) {
;     ...
;             PG8_LDA(At, 1, 1); PG8_STAGE(PG8_SB(1, 0), b3, voffB); PG8_STAGE(PG8_SB(1, 1), b3 + hstep, voffB); PG8_STAGE(PG8_SA(1, 0), a3, voffA);
;             PG8_WAIT_V(8); PG8_WAIT_L(0); PG8_BAR; PG8_MMA(1, 0, At, B0); PG8_MMA(1, 1, At, B1); PG8_BAR; PG8_SCHED;
;     ...
;         if constexpr (ALIGN_EPI) { if (wr == 0) PG8_BAR; }
	s_setprio 0
	s_mov_b32 m0, s44
	v_lshl_add_u64 v[162:163], v[162:163], 0, s[12:13]
	s_add_u32 s46, s52, 0x100080
	ds_read_b128 v[184:187], v142 offset:49152
	ds_read_b128 v[188:191], v142 offset:50176
	ds_read_b128 v[200:203], v142 offset:51200
	ds_read_b128 v[204:207], v142 offset:52224
	ds_read_b128 v[208:211], v142 offset:53248
	ds_read_b128 v[212:215], v142 offset:54272
	ds_read_b128 v[216:219], v142 offset:55296
	ds_read_b128 v[220:223], v142 offset:56320
	global_load_lds_dwordx4 v[162:163], off
	v_lshl_add_u64 v[162:163], v[192:193], 0, s[12:13]
	s_mov_b32 m0, s45
	s_addc_u32 s47, s53, 0
	global_load_lds_dwordx4 v[162:163], off
	v_lshl_add_u64 v[162:163], s[46:47], 0, v[130:131]
	s_mov_b32 m0, s56
	s_nop 0
	global_load_lds_dwordx4 v[162:163], off
	v_lshl_add_u64 v[162:163], s[46:47], 0, v[132:133]
	s_mov_b32 m0, s57
	s_nop 0
	global_load_lds_dwordx4 v[162:163], off
	v_lshl_add_u64 v[162:163], v[194:195], 0, s[12:13]
	s_mov_b32 m0, s28
	s_nop 0
	global_load_lds_dwordx4 v[162:163], off
	v_lshl_add_u64 v[162:163], v[224:225], 0, s[12:13]
	s_mov_b32 m0, s29
	s_nop 0
	global_load_lds_dwordx4 v[162:163], off
	s_waitcnt vmcnt(8)
	s_waitcnt lgkmcnt(0)
	s_setprio 1
	s_barrier
	v_mfma_f32_16x16x32_bf16 v[62:65], v[146:149], v[184:187], v[62:65]
	v_mfma_f32_16x16x32_bf16 v[62:65], v[150:153], v[188:191], v[62:65]
	v_mfma_f32_16x16x32_bf16 v[54:57], v[150:153], v[204:207], v[54:57]
	v_mfma_f32_16x16x32_bf16 v[54:57], v[146:149], v[200:203], v[54:57]
	v_mfma_f32_16x16x32_bf16 v[42:45], v[146:149], v[208:211], v[42:45]
	v_mfma_f32_16x16x32_bf16 v[42:45], v[150:153], v[212:215], v[42:45]
	v_mfma_f32_16x16x32_bf16 v[26:29], v[150:153], v[220:223], v[26:29]
	v_mfma_f32_16x16x32_bf16 v[26:29], v[146:149], v[216:219], v[26:29]
	v_mfma_f32_16x16x32_bf16 v[18:21], v[154:157], v[216:219], v[18:21]
	v_mfma_f32_16x16x32_bf16 v[18:21], v[158:161], v[220:223], v[18:21]
	v_mfma_f32_16x16x32_bf16 v[58:61], v[158:161], v[188:191], v[58:61]
	v_mfma_f32_16x16x32_bf16 v[58:61], v[154:157], v[184:187], v[58:61]
	v_mfma_f32_16x16x32_bf16 v[50:53], v[154:157], v[200:203], v[50:53]
	v_mfma_f32_16x16x32_bf16 v[50:53], v[158:161], v[204:207], v[50:53]
	v_mfma_f32_16x16x32_bf16 v[34:37], v[158:161], v[212:215], v[34:37]
	v_mfma_f32_16x16x32_bf16 v[34:37], v[154:157], v[208:211], v[34:37]
	v_mfma_f32_16x16x32_bf16 v[14:17], v[168:171], v[208:211], v[14:17]
	v_mfma_f32_16x16x32_bf16 v[14:17], v[172:175], v[212:215], v[14:17]
	v_mfma_f32_16x16x32_bf16 v[46:49], v[172:175], v[188:191], v[46:49]
	v_mfma_f32_16x16x32_bf16 v[46:49], v[168:171], v[184:187], v[46:49]
	v_mfma_f32_16x16x32_bf16 v[30:33], v[168:171], v[200:203], v[30:33]
	v_mfma_f32_16x16x32_bf16 v[30:33], v[172:175], v[204:207], v[30:33]
	v_mfma_f32_16x16x32_bf16 v[6:9], v[172:175], v[220:223], v[6:9]
	v_mfma_f32_16x16x32_bf16 v[6:9], v[168:171], v[216:219], v[6:9]
	v_mfma_f32_16x16x32_bf16 v[2:5], v[176:179], v[216:219], v[2:5]
	v_mfma_f32_16x16x32_bf16 v[2:5], v[180:183], v[220:223], v[2:5]
	v_mfma_f32_16x16x32_bf16 v[38:41], v[180:183], v[188:191], v[38:41]
	v_mfma_f32_16x16x32_bf16 v[38:41], v[176:179], v[184:187], v[38:41]
	v_mfma_f32_16x16x32_bf16 v[22:25], v[176:179], v[200:203], v[22:25]
	v_mfma_f32_16x16x32_bf16 v[22:25], v[180:183], v[204:207], v[22:25]
	v_mfma_f32_16x16x32_bf16 v[10:13], v[180:183], v[212:215], v[10:13]
	v_mfma_f32_16x16x32_bf16 v[10:13], v[176:179], v[208:211], v[10:13]
	s_barrier
	s_setprio 0
	s_add_i32 s30, s30, 2
	s_cmp_gt_u32 s30, 13
	s_mov_b64 s[46:47], s[50:51]
	s_cbranch_scc0 .LBB0_1230
	s_cmpk_lt_u32 s2, 0x100
	s_cbranch_scc0 .LBB0_1233
	s_barrier

; #define PG8_STAGE(bufoff, gbase, voff) do { _Pragma("unroll") for (int _i = 0; _i < 2; ++_i) \
;         __builtin_amdgcn_global_load_lds((const unsigned*)((const char*)(gbase) + (voff)[_i]), (PG8_LAS unsigned*)(lds + (bufoff) + ldsw + _i * 8192), 16, 0, 0); } while (0)
; #define PG8_LDA(dst, b, h) do { _Pragma("unroll") for (int m = 0; m < 4; ++m) _Pragma("unroll") for (int k = 0; k < 2; ++k) dst[m][k] = *(const PG8_LAS bf16x8*)(lds + PG8_SA(b, h) + aoff + m * 2048 + k * 1024); } while (0)
; #define PG8_LDB(dst, b, h) do { _Pragma("unroll") for (int n = 0; n < 2; ++n) _Pragma("unroll") for (int k = 0; k < 2; ++k) dst[n][k] = *(const PG8_LAS bf16x8*)(lds + PG8_SB(b, h) + boff + n * 2048 + k * 1024); } while (0)
; #define PG8_MMA(ai, bj, At, Bt) do { __builtin_amdgcn_s_setprio(1); _Pragma("unroll") for (int m = 0; m < 4; ++m) _Pragma("unroll") for (int n = 0; n < 2; ++n) _Pragma("unroll") for (int k = 0; k < 2; ++k) \
;         acc[ai][bj][m][n] = __builtin_amdgcn_mfma_f32_16x16x32_bf16(Bt[n][k], At[m][k], acc[ai][bj][m][n], 0, 0, 0); __builtin_amdgcn_s_setprio(0); } while (0)
; #define PG8_WAIT_V(n) asm volatile("s_waitcnt vmcnt(" #n ")" ::: "memory")
; #define PG8_WAIT_L(n) asm volatile("s_waitcnt lgkmcnt(" #n ")" ::: "memory")
; template <class Epi, class Sched, bool ALIGN_EPI = false, bool SP2 = false>
; __device__ __forceinline__ void gemm_phase(PG8_LAS unsigned char* lds, const Gemm g, const Sched& S, const Epi& E) {
;     ...
;             const bool last = (t == nt - 2);
;             const char* a1 = cA + (size_t)(t + 1) * kstep;
;             const char* a2 = last ? nA : cA + (size_t)(t + 2) * kstep; const char* b2 = last ? nB : cB + (size_t)(t + 2) * kstep;
;             const char* a3 = a2 + kstep; const char* b3 = b2 + kstep;
;             if (last && has_next) S.a_ready(nxt);
;             if constexpr (SP2) {
;             PG8_LDB(B0, 0, 0); PG8_LDB(B1, 0, 1); PG8_SCHED; PG8_LDA(At, 0, 0); PG8_STAGE(PG8_SA(1, 1), a1 + hstep, voffA);
;             PG8_WAIT_V(8); PG8_WAIT_L(0); PG8_BAR; PG8_MMA(0, 0, At, B0); PG8_MMA(0, 1, At, B1); PG8_BAR; PG8_SCHED;
;             PG8_LDA(At, 0, 1); PG8_STAGE(PG8_SB(0, 0), b2, voffB); PG8_STAGE(PG8_SB(0, 1), b2 + hstep, voffB); PG8_STAGE(PG8_SA(0, 0), a2, voffA);
;             PG8_WAIT_V(8); PG8_WAIT_L(0); PG8_BAR; PG8_MMA(1, 0, At, B0); PG8_MMA(1, 1, At, B1); PG8_BAR; PG8_SCHED;
.LBB0_1478:
	v_add_u32_e32 v144, s31, v201
	v_add_u32_e32 v160, s52, v201
	ds_read_b128 v[132:135], v144
	ds_read_b128 v[136:139], v144 offset:1024
	ds_read_b128 v[140:143], v144 offset:2048
	ds_read_b128 v[144:147], v144 offset:3072
	ds_read_b128 v[148:151], v160
	ds_read_b128 v[152:155], v160 offset:1024
	ds_read_b128 v[156:159], v160 offset:2048
	ds_read_b128 v[160:163], v160 offset:3072
	s_add_u32 s50, s82, 0xfff00080
	s_addc_u32 s56, s83, -1
	s_and_b64 s[34:35], s[84:85], exec
	s_cselect_b32 s87, s65, s56
	s_cselect_b32 s86, s69, s50
	s_cselect_b32 s85, s67, s88
	s_cselect_b32 s84, s77, s79
	v_lshl_add_u64 v[192:193], s[82:83], 0, v[220:221]
	s_add_i32 m0, s28, 0xc000
	ds_read_b128 v[164:167], v242
	ds_read_b128 v[168:171], v242 offset:1024
	ds_read_b128 v[172:175], v242 offset:2048
	ds_read_b128 v[176:179], v242 offset:3072
	ds_read_b128 v[180:183], v242 offset:4096
	ds_read_b128 v[184:187], v242 offset:5120
	ds_read_b128 v[188:191], v242 offset:6144
	ds_read_b128 v[226:229], v242 offset:7168
	global_load_lds_dwordx4 v[192:193], off
	v_lshl_add_u64 v[192:193], s[82:83], 0, v[222:223]
	s_add_i32 m0, s28, 0xe000
	s_nop 0
	global_load_lds_dwordx4 v[192:193], off
	s_waitcnt vmcnt(8)
	s_waitcnt lgkmcnt(0)
	s_setprio 1
	s_barrier
	v_mfma_f32_16x16x32_bf16 v[126:129], v[132:135], v[164:167], v[126:129]
	v_mfma_f32_16x16x32_bf16 v[126:129], v[136:139], v[168:171], v[126:129]
	v_mfma_f32_16x16x32_bf16 v[118:121], v[136:139], v[176:179], v[118:121]
	v_mfma_f32_16x16x32_bf16 v[118:121], v[132:135], v[172:175], v[118:121]
	v_mfma_f32_16x16x32_bf16 v[110:113], v[132:135], v[180:183], v[110:113]
	v_mfma_f32_16x16x32_bf16 v[110:113], v[136:139], v[184:187], v[110:113]
	v_mfma_f32_16x16x32_bf16 v[102:105], v[136:139], v[226:229], v[102:105]
	v_mfma_f32_16x16x32_bf16 v[102:105], v[132:135], v[188:191], v[102:105]
	v_mfma_f32_16x16x32_bf16 v[106:109], v[140:143], v[188:191], v[106:109]
	v_mfma_f32_16x16x32_bf16 v[106:109], v[144:147], v[226:229], v[106:109]
	v_mfma_f32_16x16x32_bf16 v[46:49], v[144:147], v[168:171], v[46:49]
	v_mfma_f32_16x16x32_bf16 v[46:49], v[140:143], v[164:167], v[46:49]
	v_mfma_f32_16x16x32_bf16 v[122:125], v[140:143], v[172:175], v[122:125]
	v_mfma_f32_16x16x32_bf16 v[122:125], v[144:147], v[176:179], v[122:125]
	v_mfma_f32_16x16x32_bf16 v[114:117], v[144:147], v[184:187], v[114:117]
	v_mfma_f32_16x16x32_bf16 v[114:117], v[140:143], v[180:183], v[114:117]
	v_mfma_f32_16x16x32_bf16 v[62:65], v[148:151], v[180:183], v[62:65]
	v_mfma_f32_16x16x32_bf16 v[62:65], v[152:155], v[184:187], v[62:65]
	v_mfma_f32_16x16x32_bf16 v[54:57], v[152:155], v[168:171], v[54:57]
	v_mfma_f32_16x16x32_bf16 v[54:57], v[148:151], v[164:167], v[54:57]
	v_mfma_f32_16x16x32_bf16 v[58:61], v[148:151], v[172:175], v[58:61]
	v_mfma_f32_16x16x32_bf16 v[58:61], v[152:155], v[176:179], v[58:61]
	v_mfma_f32_16x16x32_bf16 v[98:101], v[152:155], v[226:229], v[98:101]
	v_mfma_f32_16x16x32_bf16 v[98:101], v[148:151], v[188:191], v[98:101]
	v_mfma_f32_16x16x32_bf16 v[50:53], v[156:159], v[188:191], v[50:53]
	v_mfma_f32_16x16x32_bf16 v[50:53], v[160:163], v[226:229], v[50:53]
	v_mfma_f32_16x16x32_bf16 v[38:41], v[160:163], v[168:171], v[38:41]
	v_mfma_f32_16x16x32_bf16 v[38:41], v[156:159], v[164:167], v[38:41]
	v_mfma_f32_16x16x32_bf16 v[30:33], v[156:159], v[172:175], v[30:33]
	v_mfma_f32_16x16x32_bf16 v[30:33], v[160:163], v[176:179], v[30:33]
	v_mfma_f32_16x16x32_bf16 v[22:25], v[160:163], v[184:187], v[22:25]
	v_mfma_f32_16x16x32_bf16 v[22:25], v[156:159], v[180:183], v[22:25]
	s_barrier
	s_setprio 0
	s_add_i32 s34, s31, s45
	v_lshl_add_u64 v[192:193], s[84:85], 0, v[208:209]
	s_mov_b32 m0, s34
	ds_read_b128 v[164:167], v242 offset:16384
	ds_read_b128 v[168:171], v242 offset:17408
	ds_read_b128 v[172:175], v242 offset:18432
	ds_read_b128 v[176:179], v242 offset:19456
	ds_read_b128 v[180:183], v242 offset:20480
	ds_read_b128 v[184:187], v242 offset:21504
	ds_read_b128 v[188:191], v242 offset:22528
	ds_read_b128 v[226:229], v242 offset:23552
	global_load_lds_dwordx4 v[192:193], off
	s_add_i32 m0, s34, 0x2000
	s_add_u32 s34, s84, 0x100000
	v_lshl_add_u64 v[194:195], s[84:85], 0, v[212:213]
	s_addc_u32 s35, s85, 0
	s_add_i32 s50, s52, s45
	global_load_lds_dwordx4 v[194:195], off
	v_lshl_add_u64 v[230:231], s[34:35], 0, v[208:209]
	s_mov_b32 m0, s50
	v_lshl_add_u64 v[232:233], s[86:87], 0, v[210:211]
	global_load_lds_dwordx4 v[230:231], off
	v_lshl_add_u64 v[230:231], s[34:35], 0, v[212:213]
	s_add_i32 m0, s50, 0x2000
	s_nop 0
	global_load_lds_dwordx4 v[230:231], off
	v_lshl_add_u64 v[230:231], s[86:87], 0, v[206:207]
	s_mov_b32 m0, s28
	s_nop 0
	global_load_lds_dwordx4 v[230:231], off
	s_mov_b32 m0, s29
	s_nop 0
	global_load_lds_dwordx4 v[232:233], off
	s_waitcnt vmcnt(8)
	s_waitcnt lgkmcnt(0)
	s_setprio 1
	s_barrier
; #define PG8_STAGE(bufoff, gbase, voff) do { _Pragma("unroll") for (int _i = 0; _i < 2; ++_i) \
;         __builtin_amdgcn_global_load_lds((const unsigned*)((const char*)(gbase) + (voff)[_i]), (PG8_LAS unsigned*)(lds + (bufoff) + ldsw + _i * 8192), 16, 0, 0); } while (0)
; #define PG8_LDA(dst, b, h) do { _Pragma("unroll") for (int m = 0; m < 4; ++m) _Pragma("unroll") for (int k = 0; k < 2; ++k) dst[m][k] = *(const PG8_LAS bf16x8*)(lds + PG8_SA(b, h) + aoff + m * 2048 + k * 1024); } while (0)
; #define PG8_LDB(dst, b, h) do { _Pragma("unroll") for (int n = 0; n < 2; ++n) _Pragma("unroll") for (int k = 0; k < 2; ++k) dst[n][k] = *(const PG8_LAS bf16x8*)(lds + PG8_SB(b, h) + boff + n * 2048 + k * 1024); } while (0)
; #define PG8_MMA(ai, bj, At, Bt) do { __builtin_amdgcn_s_setprio(1); _Pragma("unroll") for (int m = 0; m < 4; ++m) _Pragma("unroll") for (int n = 0; n < 2; ++n) _Pragma("unroll") for (int k = 0; k < 2; ++k) \
;         acc[ai][bj][m][n] = __builtin_amdgcn_mfma_f32_16x16x32_bf16(Bt[n][k], At[m][k], acc[ai][bj][m][n], 0, 0, 0); __builtin_amdgcn_s_setprio(0); } while (0)
; #define PG8_WAIT_V(n) asm volatile("s_waitcnt vmcnt(" #n ")" ::: "memory")
; #define PG8_WAIT_L(n) asm volatile("s_waitcnt lgkmcnt(" #n ")" ::: "memory")
; #define PG8_BAR __builtin_amdgcn_s_barrier()
; #define PG8_SCHED __builtin_amdgcn_sched_barrier(0)
; template <class Epi, class Sched, bool ALIGN_EPI = false, bool SP2 = false>
; __device__ __forceinline__ void gemm_phase(PG8_LAS unsigned char* lds, const Gemm g, const Sched& S, const Epi& E) {
;     ...
;             PG8_WAIT_V(8); PG8_WAIT_L(0); PG8_BAR; PG8_MMA(1, 0, At, B0); PG8_MMA(1, 1, At, B1); PG8_BAR; PG8_SCHED;
;             PG8_LDB(B0, 1, 0); PG8_LDB(B1, 1, 1); PG8_SCHED; PG8_LDA(At, 1, 0); PG8_STAGE(PG8_SA(0, 1), a2 + hstep, voffA);
;             PG8_WAIT_V(8); PG8_WAIT_L(0); PG8_BAR; PG8_MMA(0, 0, At, B0); PG8_MMA(0, 1, At, B1); PG8_BAR; PG8_SCHED;
	v_mfma_f32_16x16x32_bf16 v[78:81], v[132:135], v[164:167], v[78:81]
	v_mfma_f32_16x16x32_bf16 v[78:81], v[136:139], v[168:171], v[78:81]
	v_mfma_f32_16x16x32_bf16 v[66:69], v[136:139], v[176:179], v[66:69]
	v_mfma_f32_16x16x32_bf16 v[66:69], v[132:135], v[172:175], v[66:69]
	v_mfma_f32_16x16x32_bf16 v[70:73], v[132:135], v[180:183], v[70:73]
	v_mfma_f32_16x16x32_bf16 v[70:73], v[136:139], v[184:187], v[70:73]
	v_mfma_f32_16x16x32_bf16 v[74:77], v[136:139], v[226:229], v[74:77]
	v_mfma_f32_16x16x32_bf16 v[74:77], v[132:135], v[188:191], v[74:77]
	v_mfma_f32_16x16x32_bf16 v[10:13], v[140:143], v[188:191], v[10:13]
	v_mfma_f32_16x16x32_bf16 v[10:13], v[144:147], v[226:229], v[10:13]
	v_mfma_f32_16x16x32_bf16 v[14:17], v[144:147], v[168:171], v[14:17]
	v_mfma_f32_16x16x32_bf16 v[14:17], v[140:143], v[164:167], v[14:17]
	v_mfma_f32_16x16x32_bf16 v[94:97], v[140:143], v[172:175], v[94:97]
	v_mfma_f32_16x16x32_bf16 v[94:97], v[144:147], v[176:179], v[94:97]
	v_mfma_f32_16x16x32_bf16 v[90:93], v[144:147], v[184:187], v[90:93]
	v_mfma_f32_16x16x32_bf16 v[90:93], v[140:143], v[180:183], v[90:93]
	v_mfma_f32_16x16x32_bf16 v[86:89], v[148:151], v[180:183], v[86:89]
	v_mfma_f32_16x16x32_bf16 v[86:89], v[152:155], v[184:187], v[86:89]
	v_mfma_f32_16x16x32_bf16 v[42:45], v[152:155], v[168:171], v[42:45]
	v_mfma_f32_16x16x32_bf16 v[42:45], v[148:151], v[164:167], v[42:45]
	v_mfma_f32_16x16x32_bf16 v[34:37], v[148:151], v[172:175], v[34:37]
	v_mfma_f32_16x16x32_bf16 v[34:37], v[152:155], v[176:179], v[34:37]
	v_mfma_f32_16x16x32_bf16 v[82:85], v[152:155], v[226:229], v[82:85]
	v_mfma_f32_16x16x32_bf16 v[82:85], v[148:151], v[188:191], v[82:85]
	v_mfma_f32_16x16x32_bf16 v[18:21], v[156:159], v[188:191], v[18:21]
	v_mfma_f32_16x16x32_bf16 v[18:21], v[160:163], v[226:229], v[18:21]
	v_mfma_f32_16x16x32_bf16 v[2:5], v[160:163], v[168:171], v[2:5]
	v_mfma_f32_16x16x32_bf16 v[2:5], v[156:159], v[164:167], v[2:5]
	v_mfma_f32_16x16x32_bf16 v[6:9], v[156:159], v[172:175], v[6:9]
	v_mfma_f32_16x16x32_bf16 v[6:9], v[160:163], v[176:179], v[6:9]
	v_mfma_f32_16x16x32_bf16 v[26:29], v[160:163], v[184:187], v[26:29]
	v_mfma_f32_16x16x32_bf16 v[26:29], v[156:159], v[180:183], v[26:29]
	s_barrier
	s_setprio 0
	s_add_i32 s50, 0, 0x18000
	s_add_i32 s56, 0, 0x1c000
	v_add_u32_e32 v144, s50, v201
	v_add_u32_e32 v160, s56, v201
	ds_read_b128 v[132:135], v144
	ds_read_b128 v[136:139], v144 offset:1024
	ds_read_b128 v[140:143], v144 offset:2048
	ds_read_b128 v[144:147], v144 offset:3072
	ds_read_b128 v[148:151], v160
	ds_read_b128 v[152:155], v160 offset:1024
	ds_read_b128 v[156:159], v160 offset:2048
	ds_read_b128 v[160:163], v160 offset:3072
	s_add_u32 s34, s86, 0x100000
	s_addc_u32 s35, s87, 0
	s_mov_b32 m0, s16
	v_lshl_add_u64 v[246:247], s[34:35], 0, v[206:207]
	ds_read_b128 v[164:167], v242 offset:32768
	ds_read_b128 v[168:171], v242 offset:33792
	ds_read_b128 v[172:175], v242 offset:34816
	ds_read_b128 v[176:179], v242 offset:35840
	ds_read_b128 v[180:183], v242 offset:36864
	ds_read_b128 v[184:187], v242 offset:37888
	ds_read_b128 v[188:191], v242 offset:38912
	ds_read_b128 v[226:229], v242 offset:39936
	global_load_lds_dwordx4 v[246:247], off
	v_lshl_add_u64 v[246:247], s[34:35], 0, v[210:211]
	s_mov_b32 m0, s17
	s_nop 0
	global_load_lds_dwordx4 v[246:247], off
	s_waitcnt vmcnt(8)
	s_waitcnt lgkmcnt(0)
	s_setprio 1
	s_barrier
	v_mfma_f32_16x16x32_bf16 v[126:129], v[132:135], v[164:167], v[126:129]
	v_mfma_f32_16x16x32_bf16 v[126:129], v[136:139], v[168:171], v[126:129]
	v_mfma_f32_16x16x32_bf16 v[118:121], v[136:139], v[176:179], v[118:121]
	v_mfma_f32_16x16x32_bf16 v[118:121], v[132:135], v[172:175], v[118:121]
	v_mfma_f32_16x16x32_bf16 v[110:113], v[132:135], v[180:183], v[110:113]
	v_mfma_f32_16x16x32_bf16 v[110:113], v[136:139], v[184:187], v[110:113]
	v_mfma_f32_16x16x32_bf16 v[102:105], v[136:139], v[226:229], v[102:105]
	v_mfma_f32_16x16x32_bf16 v[102:105], v[132:135], v[188:191], v[102:105]
	v_mfma_f32_16x16x32_bf16 v[106:109], v[140:143], v[188:191], v[106:109]
	v_mfma_f32_16x16x32_bf16 v[106:109], v[144:147], v[226:229], v[106:109]
	v_mfma_f32_16x16x32_bf16 v[46:49], v[144:147], v[168:171], v[46:49]
	v_mfma_f32_16x16x32_bf16 v[46:49], v[140:143], v[164:167], v[46:49]
	v_mfma_f32_16x16x32_bf16 v[122:125], v[140:143], v[172:175], v[122:125]
	v_mfma_f32_16x16x32_bf16 v[122:125], v[144:147], v[176:179], v[122:125]
	v_mfma_f32_16x16x32_bf16 v[114:117], v[144:147], v[184:187], v[114:117]
	v_mfma_f32_16x16x32_bf16 v[114:117], v[140:143], v[180:183], v[114:117]
	v_mfma_f32_16x16x32_bf16 v[62:65], v[148:151], v[180:183], v[62:65]
	v_mfma_f32_16x16x32_bf16 v[62:65], v[152:155], v[184:187], v[62:65]
	v_mfma_f32_16x16x32_bf16 v[54:57], v[152:155], v[168:171], v[54:57]
	v_mfma_f32_16x16x32_bf16 v[54:57], v[148:151], v[164:167], v[54:57]
	v_mfma_f32_16x16x32_bf16 v[58:61], v[148:151], v[172:175], v[58:61]
	v_mfma_f32_16x16x32_bf16 v[58:61], v[152:155], v[176:179], v[58:61]
	v_mfma_f32_16x16x32_bf16 v[98:101], v[152:155], v[226:229], v[98:101]
	v_mfma_f32_16x16x32_bf16 v[98:101], v[148:151], v[188:191], v[98:101]
	v_mfma_f32_16x16x32_bf16 v[50:53], v[156:159], v[188:191], v[50:53]
	v_mfma_f32_16x16x32_bf16 v[50:53], v[160:163], v[226:229], v[50:53]
	v_mfma_f32_16x16x32_bf16 v[38:41], v[160:163], v[168:171], v[38:41]
	v_mfma_f32_16x16x32_bf16 v[38:41], v[156:159], v[164:167], v[38:41]
	v_mfma_f32_16x16x32_bf16 v[30:33], v[156:159], v[172:175], v[30:33]
	v_mfma_f32_16x16x32_bf16 v[30:33], v[160:163], v[176:179], v[30:33]
	v_mfma_f32_16x16x32_bf16 v[22:25], v[160:163], v[184:187], v[22:25]
	v_mfma_f32_16x16x32_bf16 v[22:25], v[156:159], v[180:183], v[22:25]
	s_barrier
; #define PG8_STAGE(bufoff, gbase, voff) do { _Pragma("unroll") for (int _i = 0; _i < 2; ++_i) \
;         __builtin_amdgcn_global_load_lds((const unsigned*)((const char*)(gbase) + (voff)[_i]), (PG8_LAS unsigned*)(lds + (bufoff) + ldsw + _i * 8192), 16, 0, 0); } while (0)
; #define PG8_LDA(dst, b, h) do { _Pragma("unroll") for (int m = 0; m < 4; ++m) _Pragma("unroll") for (int k = 0; k < 2; ++k) dst[m][k] = *(const PG8_LAS bf16x8*)(lds + PG8_SA(b, h) + aoff + m * 2048 + k * 1024); } while (0)
; #define PG8_MMA(ai, bj, At, Bt) do { __builtin_amdgcn_s_setprio(1); _Pragma("unroll") for (int m = 0; m < 4; ++m) _Pragma("unroll") for (int n = 0; n < 2; ++n) _Pragma("unroll") for (int k = 0; k < 2; ++k) \
;         acc[ai][bj][m][n] = __builtin_amdgcn_mfma_f32_16x16x32_bf16(Bt[n][k], At[m][k], acc[ai][bj][m][n], 0, 0, 0); __builtin_amdgcn_s_setprio(0); } while (0)
; #define PG8_WAIT_V(n) asm volatile("s_waitcnt vmcnt(" #n ")" ::: "memory")
; #define PG8_WAIT_L(n) asm volatile("s_waitcnt lgkmcnt(" #n ")" ::: "memory")
; #define PG8_BAR __builtin_amdgcn_s_barrier()
; #define PG8_SCHED __builtin_amdgcn_sched_barrier(0)
; template <class Epi, class Sched, bool ALIGN_EPI = false, bool SP2 = false>
; __device__ __forceinline__ void gemm_phase(PG8_LAS unsigned char* lds, const Gemm g, const Sched& S, const Epi& E) {
;     ...
;         for (int t = 0; t < nt; t += 2) {
;     ...
;             PG8_LDA(At, 1, 1); PG8_STAGE(PG8_SB(1, 0), b3, voffB); PG8_STAGE(PG8_SB(1, 1), b3 + hstep, voffB); PG8_STAGE(PG8_SA(1, 0), a3, voffA);
;             PG8_WAIT_V(8); PG8_WAIT_L(0); PG8_BAR; PG8_MMA(1, 0, At, B0); PG8_MMA(1, 1, At, B1); PG8_BAR; PG8_SCHED;
	s_setprio 0
	s_add_i32 s34, s50, s45
	v_lshl_add_u64 v[192:193], v[192:193], 0, s[54:55]
	s_mov_b32 m0, s34
	ds_read_b128 v[164:167], v242 offset:49152
	ds_read_b128 v[168:171], v242 offset:50176
	ds_read_b128 v[172:175], v242 offset:51200
	ds_read_b128 v[176:179], v242 offset:52224
	ds_read_b128 v[180:183], v242 offset:53248
	ds_read_b128 v[184:187], v242 offset:54272
	ds_read_b128 v[188:191], v242 offset:55296
	ds_read_b128 v[226:229], v242 offset:56320
	global_load_lds_dwordx4 v[192:193], off
	s_add_i32 m0, s34, 0x2000
	s_add_u32 s34, s84, 0x100080
	v_lshl_add_u64 v[192:193], v[194:195], 0, s[54:55]
	s_addc_u32 s35, s85, 0
	s_add_i32 s50, s56, s45
	global_load_lds_dwordx4 v[192:193], off
	v_lshl_add_u64 v[192:193], s[34:35], 0, v[208:209]
	s_mov_b32 m0, s50
	s_nop 0
	global_load_lds_dwordx4 v[192:193], off
	v_lshl_add_u64 v[192:193], s[34:35], 0, v[212:213]
	s_add_i32 m0, s50, 0x2000
	s_nop 0
	global_load_lds_dwordx4 v[192:193], off
	v_lshl_add_u64 v[192:193], v[230:231], 0, s[54:55]
	s_mov_b32 m0, s39
	s_nop 0
	global_load_lds_dwordx4 v[192:193], off
	v_lshl_add_u64 v[192:193], v[232:233], 0, s[54:55]
	s_mov_b32 m0, s46
	s_nop 0
	global_load_lds_dwordx4 v[192:193], off
	s_waitcnt vmcnt(8)
	s_waitcnt lgkmcnt(0)
	s_setprio 1
	s_barrier
	v_mfma_f32_16x16x32_bf16 v[78:81], v[132:135], v[164:167], v[78:81]
	v_mfma_f32_16x16x32_bf16 v[78:81], v[136:139], v[168:171], v[78:81]
	v_mfma_f32_16x16x32_bf16 v[66:69], v[136:139], v[176:179], v[66:69]
	v_mfma_f32_16x16x32_bf16 v[66:69], v[132:135], v[172:175], v[66:69]
	v_mfma_f32_16x16x32_bf16 v[70:73], v[132:135], v[180:183], v[70:73]
	v_mfma_f32_16x16x32_bf16 v[70:73], v[136:139], v[184:187], v[70:73]
	v_mfma_f32_16x16x32_bf16 v[74:77], v[136:139], v[226:229], v[74:77]
	v_mfma_f32_16x16x32_bf16 v[74:77], v[132:135], v[188:191], v[74:77]
	v_mfma_f32_16x16x32_bf16 v[10:13], v[140:143], v[188:191], v[10:13]
	v_mfma_f32_16x16x32_bf16 v[10:13], v[144:147], v[226:229], v[10:13]
	v_mfma_f32_16x16x32_bf16 v[14:17], v[144:147], v[168:171], v[14:17]
	v_mfma_f32_16x16x32_bf16 v[14:17], v[140:143], v[164:167], v[14:17]
	v_mfma_f32_16x16x32_bf16 v[94:97], v[140:143], v[172:175], v[94:97]
	v_mfma_f32_16x16x32_bf16 v[94:97], v[144:147], v[176:179], v[94:97]
	v_mfma_f32_16x16x32_bf16 v[90:93], v[144:147], v[184:187], v[90:93]
	v_mfma_f32_16x16x32_bf16 v[90:93], v[140:143], v[180:183], v[90:93]
	v_mfma_f32_16x16x32_bf16 v[86:89], v[148:151], v[180:183], v[86:89]
	v_mfma_f32_16x16x32_bf16 v[86:89], v[152:155], v[184:187], v[86:89]
	v_mfma_f32_16x16x32_bf16 v[42:45], v[152:155], v[168:171], v[42:45]
	v_mfma_f32_16x16x32_bf16 v[42:45], v[148:151], v[164:167], v[42:45]
	v_mfma_f32_16x16x32_bf16 v[34:37], v[148:151], v[172:175], v[34:37]
	v_mfma_f32_16x16x32_bf16 v[34:37], v[152:155], v[176:179], v[34:37]
	v_mfma_f32_16x16x32_bf16 v[82:85], v[152:155], v[226:229], v[82:85]
	v_mfma_f32_16x16x32_bf16 v[82:85], v[148:151], v[188:191], v[82:85]
	v_mfma_f32_16x16x32_bf16 v[18:21], v[156:159], v[188:191], v[18:21]
	v_mfma_f32_16x16x32_bf16 v[18:21], v[160:163], v[226:229], v[18:21]
	v_mfma_f32_16x16x32_bf16 v[2:5], v[160:163], v[168:171], v[2:5]
	v_mfma_f32_16x16x32_bf16 v[2:5], v[156:159], v[164:167], v[2:5]
	v_mfma_f32_16x16x32_bf16 v[6:9], v[156:159], v[172:175], v[6:9]
	v_mfma_f32_16x16x32_bf16 v[6:9], v[160:163], v[176:179], v[6:9]
	v_mfma_f32_16x16x32_bf16 v[26:29], v[160:163], v[184:187], v[26:29]
	v_mfma_f32_16x16x32_bf16 v[26:29], v[156:159], v[180:183], v[26:29]
	s_barrier
	s_setprio 0
	s_add_i32 s89, s89, 2
	s_add_u32 s82, s82, 0x100
	s_addc_u32 s83, s83, 0
	s_add_u32 s79, s79, 0x100
	s_addc_u32 s88, s88, 0
	s_cmp_gt_u32 s89, 61
	s_cbranch_scc1 .LBB0_1490

; #define PG8_STAGE(bufoff, gbase, voff) do { _Pragma("unroll") for (int _i = 0; _i < 2; ++_i) \
;         __builtin_amdgcn_global_load_lds((const unsigned*)((const char*)(gbase) + (voff)[_i]), (PG8_LAS unsigned*)(lds + (bufoff) + ldsw + _i * 8192), 16, 0, 0); } while (0)
; #define PG8_LDA(dst, b, h) do { _Pragma("unroll") for (int m = 0; m < 4; ++m) _Pragma("unroll") for (int k = 0; k < 2; ++k) dst[m][k] = *(const PG8_LAS bf16x8*)(lds + PG8_SA(b, h) + aoff + m * 2048 + k * 1024); } while (0)
; #define PG8_LDB(dst, b, h) do { _Pragma("unroll") for (int n = 0; n < 2; ++n) _Pragma("unroll") for (int k = 0; k < 2; ++k) dst[n][k] = *(const PG8_LAS bf16x8*)(lds + PG8_SB(b, h) + boff + n * 2048 + k * 1024); } while (0)
; #define PG8_MMA(ai, bj, At, Bt) do { __builtin_amdgcn_s_setprio(1); _Pragma("unroll") for (int m = 0; m < 4; ++m) _Pragma("unroll") for (int n = 0; n < 2; ++n) _Pragma("unroll") for (int k = 0; k < 2; ++k) \
;         acc[ai][bj][m][n] = __builtin_amdgcn_mfma_f32_16x16x32_bf16(Bt[n][k], At[m][k], acc[ai][bj][m][n], 0, 0, 0); __builtin_amdgcn_s_setprio(0); } while (0)
; #define PG8_WAIT_V(n) asm volatile("s_waitcnt vmcnt(" #n ")" ::: "memory")
; #define PG8_WAIT_L(n) asm volatile("s_waitcnt lgkmcnt(" #n ")" ::: "memory")
; template <class Epi, class Sched, bool ALIGN_EPI = false, bool SP2 = false>
; __device__ __forceinline__ void gemm_phase(PG8_LAS unsigned char* lds, const Gemm g, const Sched& S, const Epi& E) {
;     ...
;             const bool last = (t == nt - 2);
;             const char* a1 = cA + (size_t)(t + 1) * kstep;
;             const char* a2 = last ? nA : cA + (size_t)(t + 2) * kstep; const char* b2 = last ? nB : cB + (size_t)(t + 2) * kstep;
;             const char* a3 = a2 + kstep; const char* b3 = b2 + kstep;
;             if (last && has_next) S.a_ready(nxt);
;             if constexpr (SP2) {
;             PG8_LDB(B0, 0, 0); PG8_LDB(B1, 0, 1); PG8_SCHED; PG8_LDA(At, 0, 0); PG8_STAGE(PG8_SA(1, 1), a1 + hstep, voffA);
;             PG8_WAIT_V(8); PG8_WAIT_L(0); PG8_BAR; PG8_MMA(0, 0, At, B0); PG8_MMA(0, 1, At, B1); PG8_BAR; PG8_SCHED;
;             PG8_LDA(At, 0, 1); PG8_STAGE(PG8_SB(0, 0), b2, voffB); PG8_STAGE(PG8_SB(0, 1), b2 + hstep, voffB); PG8_STAGE(PG8_SA(0, 0), a2, voffA);
;             PG8_WAIT_V(8); PG8_WAIT_L(0); PG8_BAR; PG8_MMA(1, 0, At, B0); PG8_MMA(1, 1, At, B1); PG8_BAR; PG8_SCHED;
.LBB0_1731:
	ds_read_b128 v[170:173], v166
	ds_read_b128 v[174:177], v166 offset:1024
	ds_read_b128 v[178:181], v166 offset:2048
	ds_read_b128 v[182:185], v166 offset:3072
	ds_read_b128 v[186:189], v167
	ds_read_b128 v[190:193], v167 offset:1024
	ds_read_b128 v[196:199], v167 offset:2048
	ds_read_b128 v[202:205], v167 offset:3072
	s_add_u32 s48, s40, 0x100
	s_addc_u32 s49, s41, 0
	s_cmpk_eq_i32 s56, 0xa8
	s_cselect_b32 s53, s7, s49
	s_cselect_b32 s52, s6, s48
	s_cselect_b32 s51, s39, s55
	s_cselect_b32 s50, s38, s54
	v_lshl_add_u64 v[146:147], s[40:41], 0, v[138:139]
	s_add_i32 m0, s16, 0xc000
	ds_read_b128 v[206:209], v168
	ds_read_b128 v[210:213], v168 offset:1024
	ds_read_b128 v[214:217], v168 offset:2048
	ds_read_b128 v[218:221], v168 offset:3072
	ds_read_b128 v[222:225], v168 offset:4096
	ds_read_b128 v[226:229], v168 offset:5120
	ds_read_b128 v[230:233], v168 offset:6144
	ds_read_b128 v[234:237], v168 offset:7168
	global_load_lds_dwordx4 v[146:147], off
	v_lshl_add_u64 v[146:147], s[40:41], 0, v[140:141]
	s_add_i32 m0, s16, 0xe000
	s_nop 0
	global_load_lds_dwordx4 v[146:147], off
	s_waitcnt vmcnt(8)
	s_waitcnt lgkmcnt(0)
	s_setprio 1
	s_barrier
	v_mfma_f32_16x16x32_bf16 v[126:129], v[170:173], v[206:209], v[126:129]
	v_mfma_f32_16x16x32_bf16 v[126:129], v[174:177], v[210:213], v[126:129]
	v_mfma_f32_16x16x32_bf16 v[110:113], v[174:177], v[218:221], v[110:113]
	v_mfma_f32_16x16x32_bf16 v[110:113], v[170:173], v[214:217], v[110:113]
	v_mfma_f32_16x16x32_bf16 v[94:97], v[170:173], v[222:225], v[94:97]
	v_mfma_f32_16x16x32_bf16 v[94:97], v[174:177], v[226:229], v[94:97]
	v_mfma_f32_16x16x32_bf16 v[78:81], v[174:177], v[234:237], v[78:81]
	v_mfma_f32_16x16x32_bf16 v[78:81], v[170:173], v[230:233], v[78:81]
	v_mfma_f32_16x16x32_bf16 v[74:77], v[178:181], v[230:233], v[74:77]
	v_mfma_f32_16x16x32_bf16 v[74:77], v[182:185], v[234:237], v[74:77]
	v_mfma_f32_16x16x32_bf16 v[122:125], v[182:185], v[210:213], v[122:125]
	v_mfma_f32_16x16x32_bf16 v[122:125], v[178:181], v[206:209], v[122:125]
	v_mfma_f32_16x16x32_bf16 v[106:109], v[178:181], v[214:217], v[106:109]
	v_mfma_f32_16x16x32_bf16 v[106:109], v[182:185], v[218:221], v[106:109]
	v_mfma_f32_16x16x32_bf16 v[90:93], v[182:185], v[226:229], v[90:93]
	v_mfma_f32_16x16x32_bf16 v[90:93], v[178:181], v[222:225], v[90:93]
	v_mfma_f32_16x16x32_bf16 v[86:89], v[186:189], v[222:225], v[86:89]
	v_mfma_f32_16x16x32_bf16 v[86:89], v[190:193], v[226:229], v[86:89]
	v_mfma_f32_16x16x32_bf16 v[118:121], v[190:193], v[210:213], v[118:121]
	v_mfma_f32_16x16x32_bf16 v[118:121], v[186:189], v[206:209], v[118:121]
	v_mfma_f32_16x16x32_bf16 v[102:105], v[186:189], v[214:217], v[102:105]
	v_mfma_f32_16x16x32_bf16 v[102:105], v[190:193], v[218:221], v[102:105]
	v_mfma_f32_16x16x32_bf16 v[70:73], v[190:193], v[234:237], v[70:73]
	v_mfma_f32_16x16x32_bf16 v[70:73], v[186:189], v[230:233], v[70:73]
	v_mfma_f32_16x16x32_bf16 v[66:69], v[196:199], v[230:233], v[66:69]
	v_mfma_f32_16x16x32_bf16 v[66:69], v[202:205], v[234:237], v[66:69]
	v_mfma_f32_16x16x32_bf16 v[114:117], v[202:205], v[210:213], v[114:117]
	v_mfma_f32_16x16x32_bf16 v[114:117], v[196:199], v[206:209], v[114:117]
	v_mfma_f32_16x16x32_bf16 v[98:101], v[196:199], v[214:217], v[98:101]
	v_mfma_f32_16x16x32_bf16 v[98:101], v[202:205], v[218:221], v[98:101]
	v_mfma_f32_16x16x32_bf16 v[82:85], v[202:205], v[226:229], v[82:85]
	v_mfma_f32_16x16x32_bf16 v[82:85], v[196:199], v[222:225], v[82:85]
	s_barrier
	s_setprio 0
	s_add_i32 s40, s31, s3
	v_lshl_add_u64 v[146:147], s[50:51], 0, v[132:133]
	s_mov_b32 m0, s40
	ds_read_b128 v[206:209], v168 offset:16384
	ds_read_b128 v[210:213], v168 offset:17408
	ds_read_b128 v[214:217], v168 offset:18432
	ds_read_b128 v[218:221], v168 offset:19456
	ds_read_b128 v[222:225], v168 offset:20480
	ds_read_b128 v[226:229], v168 offset:21504
	ds_read_b128 v[230:233], v168 offset:22528
	ds_read_b128 v[234:237], v168 offset:23552
	global_load_lds_dwordx4 v[146:147], off
	s_add_i32 m0, s40, 0x2000
	s_add_u32 s40, s50, 0x2b0000
	v_lshl_add_u64 v[194:195], s[50:51], 0, v[136:137]
	s_addc_u32 s41, s51, 0
	s_add_i32 s57, s35, s3
	global_load_lds_dwordx4 v[194:195], off
	v_lshl_add_u64 v[238:239], s[40:41], 0, v[132:133]
	s_mov_b32 m0, s57
	v_lshl_add_u64 v[240:241], s[52:53], 0, v[134:135]
	global_load_lds_dwordx4 v[238:239], off
	v_lshl_add_u64 v[238:239], s[40:41], 0, v[136:137]
	s_add_i32 m0, s57, 0x2000
	s_nop 0
	global_load_lds_dwordx4 v[238:239], off
	v_lshl_add_u64 v[238:239], s[52:53], 0, v[130:131]
	s_mov_b32 m0, s16
	s_nop 0
	global_load_lds_dwordx4 v[238:239], off
	s_mov_b32 m0, s17
	s_nop 0
	global_load_lds_dwordx4 v[240:241], off
	s_waitcnt vmcnt(8)
	s_waitcnt lgkmcnt(0)
	s_setprio 1
	s_barrier
; #define PG8_STAGE(bufoff, gbase, voff) do { _Pragma("unroll") for (int _i = 0; _i < 2; ++_i) \
;         __builtin_amdgcn_global_load_lds((const unsigned*)((const char*)(gbase) + (voff)[_i]), (PG8_LAS unsigned*)(lds + (bufoff) + ldsw + _i * 8192), 16, 0, 0); } while (0)
; #define PG8_LDA(dst, b, h) do { _Pragma("unroll") for (int m = 0; m < 4; ++m) _Pragma("unroll") for (int k = 0; k < 2; ++k) dst[m][k] = *(const PG8_LAS bf16x8*)(lds + PG8_SA(b, h) + aoff + m * 2048 + k * 1024); } while (0)
; #define PG8_LDB(dst, b, h) do { _Pragma("unroll") for (int n = 0; n < 2; ++n) _Pragma("unroll") for (int k = 0; k < 2; ++k) dst[n][k] = *(const PG8_LAS bf16x8*)(lds + PG8_SB(b, h) + boff + n * 2048 + k * 1024); } while (0)
; #define PG8_MMA(ai, bj, At, Bt) do { __builtin_amdgcn_s_setprio(1); _Pragma("unroll") for (int m = 0; m < 4; ++m) _Pragma("unroll") for (int n = 0; n < 2; ++n) _Pragma("unroll") for (int k = 0; k < 2; ++k) \
;         acc[ai][bj][m][n] = __builtin_amdgcn_mfma_f32_16x16x32_bf16(Bt[n][k], At[m][k], acc[ai][bj][m][n], 0, 0, 0); __builtin_amdgcn_s_setprio(0); } while (0)
; #define PG8_WAIT_V(n) asm volatile("s_waitcnt vmcnt(" #n ")" ::: "memory")
; #define PG8_WAIT_L(n) asm volatile("s_waitcnt lgkmcnt(" #n ")" ::: "memory")
; #define PG8_BAR __builtin_amdgcn_s_barrier()
; #define PG8_SCHED __builtin_amdgcn_sched_barrier(0)
; template <class Epi, class Sched, bool ALIGN_EPI = false, bool SP2 = false>
; __device__ __forceinline__ void gemm_phase(PG8_LAS unsigned char* lds, const Gemm g, const Sched& S, const Epi& E) {
;     ...
;             PG8_WAIT_V(8); PG8_WAIT_L(0); PG8_BAR; PG8_MMA(1, 0, At, B0); PG8_MMA(1, 1, At, B1); PG8_BAR; PG8_SCHED;
;             PG8_LDB(B0, 1, 0); PG8_LDB(B1, 1, 1); PG8_SCHED; PG8_LDA(At, 1, 0); PG8_STAGE(PG8_SA(0, 1), a2 + hstep, voffA);
;             PG8_WAIT_V(8); PG8_WAIT_L(0); PG8_BAR; PG8_MMA(0, 0, At, B0); PG8_MMA(0, 1, At, B1); PG8_BAR; PG8_SCHED;
	v_mfma_f32_16x16x32_bf16 v[62:65], v[170:173], v[206:209], v[62:65]
	v_mfma_f32_16x16x32_bf16 v[62:65], v[174:177], v[210:213], v[62:65]
	v_mfma_f32_16x16x32_bf16 v[46:49], v[174:177], v[218:221], v[46:49]
	v_mfma_f32_16x16x32_bf16 v[46:49], v[170:173], v[214:217], v[46:49]
	v_mfma_f32_16x16x32_bf16 v[30:33], v[170:173], v[222:225], v[30:33]
	v_mfma_f32_16x16x32_bf16 v[30:33], v[174:177], v[226:229], v[30:33]
	v_mfma_f32_16x16x32_bf16 v[14:17], v[174:177], v[234:237], v[14:17]
	v_mfma_f32_16x16x32_bf16 v[14:17], v[170:173], v[230:233], v[14:17]
	v_mfma_f32_16x16x32_bf16 v[10:13], v[178:181], v[230:233], v[10:13]
	v_mfma_f32_16x16x32_bf16 v[10:13], v[182:185], v[234:237], v[10:13]
	v_mfma_f32_16x16x32_bf16 v[58:61], v[182:185], v[210:213], v[58:61]
	v_mfma_f32_16x16x32_bf16 v[58:61], v[178:181], v[206:209], v[58:61]
	v_mfma_f32_16x16x32_bf16 v[42:45], v[178:181], v[214:217], v[42:45]
	v_mfma_f32_16x16x32_bf16 v[42:45], v[182:185], v[218:221], v[42:45]
	v_mfma_f32_16x16x32_bf16 v[26:29], v[182:185], v[226:229], v[26:29]
	v_mfma_f32_16x16x32_bf16 v[26:29], v[178:181], v[222:225], v[26:29]
	v_mfma_f32_16x16x32_bf16 v[22:25], v[186:189], v[222:225], v[22:25]
	v_mfma_f32_16x16x32_bf16 v[22:25], v[190:193], v[226:229], v[22:25]
	v_mfma_f32_16x16x32_bf16 v[54:57], v[190:193], v[210:213], v[54:57]
	v_mfma_f32_16x16x32_bf16 v[54:57], v[186:189], v[206:209], v[54:57]
	v_mfma_f32_16x16x32_bf16 v[38:41], v[186:189], v[214:217], v[38:41]
	v_mfma_f32_16x16x32_bf16 v[38:41], v[190:193], v[218:221], v[38:41]
	v_mfma_f32_16x16x32_bf16 v[6:9], v[190:193], v[234:237], v[6:9]
	v_mfma_f32_16x16x32_bf16 v[6:9], v[186:189], v[230:233], v[6:9]
	v_mfma_f32_16x16x32_bf16 v[2:5], v[196:199], v[230:233], v[2:5]
	v_mfma_f32_16x16x32_bf16 v[2:5], v[202:205], v[234:237], v[2:5]
	v_mfma_f32_16x16x32_bf16 v[50:53], v[202:205], v[210:213], v[50:53]
	v_mfma_f32_16x16x32_bf16 v[50:53], v[196:199], v[206:209], v[50:53]
	v_mfma_f32_16x16x32_bf16 v[34:37], v[196:199], v[214:217], v[34:37]
	v_mfma_f32_16x16x32_bf16 v[34:37], v[202:205], v[218:221], v[34:37]
	v_mfma_f32_16x16x32_bf16 v[18:21], v[202:205], v[226:229], v[18:21]
	v_mfma_f32_16x16x32_bf16 v[18:21], v[196:199], v[222:225], v[18:21]
	s_barrier
	s_setprio 0
	s_add_i32 s57, 0, 0x18000
	v_add_u32_e32 v169, s57, v148
	s_add_i32 s58, 0, 0x1c000
	ds_read_b128 v[170:173], v169
	ds_read_b128 v[174:177], v169 offset:1024
	ds_read_b128 v[178:181], v169 offset:2048
	ds_read_b128 v[182:185], v169 offset:3072
	v_add_u32_e32 v169, s58, v148
	ds_read_b128 v[186:189], v169
	ds_read_b128 v[190:193], v169 offset:1024
	ds_read_b128 v[196:199], v169 offset:2048
	ds_read_b128 v[202:205], v169 offset:3072
	s_add_u32 s40, s52, 0x2b0000
	s_addc_u32 s41, s53, 0
	s_mov_b32 m0, s25
	v_lshl_add_u64 v[242:243], s[40:41], 0, v[130:131]
	ds_read_b128 v[206:209], v168 offset:32768
	ds_read_b128 v[210:213], v168 offset:33792
	ds_read_b128 v[214:217], v168 offset:34816
	ds_read_b128 v[218:221], v168 offset:35840
	ds_read_b128 v[222:225], v168 offset:36864
	ds_read_b128 v[226:229], v168 offset:37888
	ds_read_b128 v[230:233], v168 offset:38912
	ds_read_b128 v[234:237], v168 offset:39936
	global_load_lds_dwordx4 v[242:243], off
	v_lshl_add_u64 v[242:243], s[40:41], 0, v[134:135]
	s_mov_b32 m0, s26
	s_nop 0
	global_load_lds_dwordx4 v[242:243], off
	s_waitcnt vmcnt(8)
	s_waitcnt lgkmcnt(0)
	s_setprio 1
	s_barrier
	v_mfma_f32_16x16x32_bf16 v[126:129], v[170:173], v[206:209], v[126:129]
	v_mfma_f32_16x16x32_bf16 v[126:129], v[174:177], v[210:213], v[126:129]
	v_mfma_f32_16x16x32_bf16 v[110:113], v[174:177], v[218:221], v[110:113]
	v_mfma_f32_16x16x32_bf16 v[110:113], v[170:173], v[214:217], v[110:113]
	v_mfma_f32_16x16x32_bf16 v[94:97], v[170:173], v[222:225], v[94:97]
	v_mfma_f32_16x16x32_bf16 v[94:97], v[174:177], v[226:229], v[94:97]
	v_mfma_f32_16x16x32_bf16 v[78:81], v[174:177], v[234:237], v[78:81]
	v_mfma_f32_16x16x32_bf16 v[78:81], v[170:173], v[230:233], v[78:81]
	v_mfma_f32_16x16x32_bf16 v[74:77], v[178:181], v[230:233], v[74:77]
	v_mfma_f32_16x16x32_bf16 v[74:77], v[182:185], v[234:237], v[74:77]
	v_mfma_f32_16x16x32_bf16 v[122:125], v[182:185], v[210:213], v[122:125]
	v_mfma_f32_16x16x32_bf16 v[122:125], v[178:181], v[206:209], v[122:125]
	v_mfma_f32_16x16x32_bf16 v[106:109], v[178:181], v[214:217], v[106:109]
	v_mfma_f32_16x16x32_bf16 v[106:109], v[182:185], v[218:221], v[106:109]
	v_mfma_f32_16x16x32_bf16 v[90:93], v[182:185], v[226:229], v[90:93]
	v_mfma_f32_16x16x32_bf16 v[90:93], v[178:181], v[222:225], v[90:93]
	v_mfma_f32_16x16x32_bf16 v[86:89], v[186:189], v[222:225], v[86:89]
	v_mfma_f32_16x16x32_bf16 v[86:89], v[190:193], v[226:229], v[86:89]
	v_mfma_f32_16x16x32_bf16 v[118:121], v[190:193], v[210:213], v[118:121]
	v_mfma_f32_16x16x32_bf16 v[118:121], v[186:189], v[206:209], v[118:121]
	v_mfma_f32_16x16x32_bf16 v[102:105], v[186:189], v[214:217], v[102:105]
	v_mfma_f32_16x16x32_bf16 v[102:105], v[190:193], v[218:221], v[102:105]
	v_mfma_f32_16x16x32_bf16 v[70:73], v[190:193], v[234:237], v[70:73]
	v_mfma_f32_16x16x32_bf16 v[70:73], v[186:189], v[230:233], v[70:73]
	v_mfma_f32_16x16x32_bf16 v[66:69], v[196:199], v[230:233], v[66:69]
	v_mfma_f32_16x16x32_bf16 v[66:69], v[202:205], v[234:237], v[66:69]
	v_mfma_f32_16x16x32_bf16 v[114:117], v[202:205], v[210:213], v[114:117]
	v_mfma_f32_16x16x32_bf16 v[114:117], v[196:199], v[206:209], v[114:117]
	v_mfma_f32_16x16x32_bf16 v[98:101], v[196:199], v[214:217], v[98:101]
	v_mfma_f32_16x16x32_bf16 v[98:101], v[202:205], v[218:221], v[98:101]
	v_mfma_f32_16x16x32_bf16 v[82:85], v[202:205], v[226:229], v[82:85]
	v_mfma_f32_16x16x32_bf16 v[82:85], v[196:199], v[222:225], v[82:85]
	s_barrier
; #define PG8_STAGE(bufoff, gbase, voff) do { _Pragma("unroll") for (int _i = 0; _i < 2; ++_i) \
;         __builtin_amdgcn_global_load_lds((const unsigned*)((const char*)(gbase) + (voff)[_i]), (PG8_LAS unsigned*)(lds + (bufoff) + ldsw + _i * 8192), 16, 0, 0); } while (0)
; #define PG8_LDA(dst, b, h) do { _Pragma("unroll") for (int m = 0; m < 4; ++m) _Pragma("unroll") for (int k = 0; k < 2; ++k) dst[m][k] = *(const PG8_LAS bf16x8*)(lds + PG8_SA(b, h) + aoff + m * 2048 + k * 1024); } while (0)
; #define PG8_MMA(ai, bj, At, Bt) do { __builtin_amdgcn_s_setprio(1); _Pragma("unroll") for (int m = 0; m < 4; ++m) _Pragma("unroll") for (int n = 0; n < 2; ++n) _Pragma("unroll") for (int k = 0; k < 2; ++k) \
;         acc[ai][bj][m][n] = __builtin_amdgcn_mfma_f32_16x16x32_bf16(Bt[n][k], At[m][k], acc[ai][bj][m][n], 0, 0, 0); __builtin_amdgcn_s_setprio(0); } while (0)
; #define PG8_WAIT_V(n) asm volatile("s_waitcnt vmcnt(" #n ")" ::: "memory")
; #define PG8_WAIT_L(n) asm volatile("s_waitcnt lgkmcnt(" #n ")" ::: "memory")
; #define PG8_BAR __builtin_amdgcn_s_barrier()
; #define PG8_SCHED __builtin_amdgcn_sched_barrier(0)
; template <class Epi, class Sched, bool ALIGN_EPI = false, bool SP2 = false>
; __device__ __forceinline__ void gemm_phase(PG8_LAS unsigned char* lds, const Gemm g, const Sched& S, const Epi& E) {
;     ...
;         for (int t = 0; t < nt; t += 2) {
;     ...
;             PG8_LDA(At, 1, 1); PG8_STAGE(PG8_SB(1, 0), b3, voffB); PG8_STAGE(PG8_SB(1, 1), b3 + hstep, voffB); PG8_STAGE(PG8_SA(1, 0), a3, voffA);
;             PG8_WAIT_V(8); PG8_WAIT_L(0); PG8_BAR; PG8_MMA(1, 0, At, B0); PG8_MMA(1, 1, At, B1); PG8_BAR; PG8_SCHED;
;     ...
;         if constexpr (ALIGN_EPI) { if (wr == 0) PG8_BAR; }
	s_setprio 0
	s_add_i32 s40, s57, s3
	v_lshl_add_u64 v[146:147], v[146:147], 0, s[10:11]
	s_mov_b32 m0, s40
	ds_read_b128 v[206:209], v168 offset:49152
	ds_read_b128 v[210:213], v168 offset:50176
	ds_read_b128 v[214:217], v168 offset:51200
	ds_read_b128 v[218:221], v168 offset:52224
	ds_read_b128 v[222:225], v168 offset:53248
	ds_read_b128 v[226:229], v168 offset:54272
	ds_read_b128 v[230:233], v168 offset:55296
	ds_read_b128 v[234:237], v168 offset:56320
	global_load_lds_dwordx4 v[146:147], off
	s_add_i32 m0, s40, 0x2000
	s_add_u32 s40, s50, 0x2b0080
	v_lshl_add_u64 v[146:147], v[194:195], 0, s[10:11]
	s_addc_u32 s41, s51, 0
	s_add_i32 s50, s58, s3
	global_load_lds_dwordx4 v[146:147], off
	v_lshl_add_u64 v[146:147], s[40:41], 0, v[132:133]
	s_mov_b32 m0, s50
	s_nop 0
	global_load_lds_dwordx4 v[146:147], off
	v_lshl_add_u64 v[146:147], s[40:41], 0, v[136:137]
	s_add_i32 m0, s50, 0x2000
	s_nop 0
	global_load_lds_dwordx4 v[146:147], off
	v_lshl_add_u64 v[146:147], v[238:239], 0, s[10:11]
	s_mov_b32 m0, s28
	s_nop 0
	global_load_lds_dwordx4 v[146:147], off
	v_lshl_add_u64 v[146:147], v[240:241], 0, s[10:11]
	s_mov_b32 m0, s29
	s_nop 0
	global_load_lds_dwordx4 v[146:147], off
	s_waitcnt vmcnt(8)
	s_waitcnt lgkmcnt(0)
	s_setprio 1
	s_barrier
	v_mfma_f32_16x16x32_bf16 v[62:65], v[170:173], v[206:209], v[62:65]
	v_mfma_f32_16x16x32_bf16 v[62:65], v[174:177], v[210:213], v[62:65]
	v_mfma_f32_16x16x32_bf16 v[46:49], v[174:177], v[218:221], v[46:49]
	v_mfma_f32_16x16x32_bf16 v[46:49], v[170:173], v[214:217], v[46:49]
	v_mfma_f32_16x16x32_bf16 v[30:33], v[170:173], v[222:225], v[30:33]
	v_mfma_f32_16x16x32_bf16 v[30:33], v[174:177], v[226:229], v[30:33]
	v_mfma_f32_16x16x32_bf16 v[14:17], v[174:177], v[234:237], v[14:17]
	v_mfma_f32_16x16x32_bf16 v[14:17], v[170:173], v[230:233], v[14:17]
	v_mfma_f32_16x16x32_bf16 v[10:13], v[178:181], v[230:233], v[10:13]
	v_mfma_f32_16x16x32_bf16 v[10:13], v[182:185], v[234:237], v[10:13]
	v_mfma_f32_16x16x32_bf16 v[58:61], v[182:185], v[210:213], v[58:61]
	v_mfma_f32_16x16x32_bf16 v[58:61], v[178:181], v[206:209], v[58:61]
	v_mfma_f32_16x16x32_bf16 v[42:45], v[178:181], v[214:217], v[42:45]
	v_mfma_f32_16x16x32_bf16 v[42:45], v[182:185], v[218:221], v[42:45]
	v_mfma_f32_16x16x32_bf16 v[26:29], v[182:185], v[226:229], v[26:29]
	v_mfma_f32_16x16x32_bf16 v[26:29], v[178:181], v[222:225], v[26:29]
	v_mfma_f32_16x16x32_bf16 v[22:25], v[186:189], v[222:225], v[22:25]
	v_mfma_f32_16x16x32_bf16 v[22:25], v[190:193], v[226:229], v[22:25]
	v_mfma_f32_16x16x32_bf16 v[54:57], v[190:193], v[210:213], v[54:57]
	v_mfma_f32_16x16x32_bf16 v[54:57], v[186:189], v[206:209], v[54:57]
	v_mfma_f32_16x16x32_bf16 v[38:41], v[186:189], v[214:217], v[38:41]
	v_mfma_f32_16x16x32_bf16 v[38:41], v[190:193], v[218:221], v[38:41]
	v_mfma_f32_16x16x32_bf16 v[6:9], v[190:193], v[234:237], v[6:9]
	v_mfma_f32_16x16x32_bf16 v[6:9], v[186:189], v[230:233], v[6:9]
	v_mfma_f32_16x16x32_bf16 v[2:5], v[196:199], v[230:233], v[2:5]
	v_mfma_f32_16x16x32_bf16 v[2:5], v[202:205], v[234:237], v[2:5]
	v_mfma_f32_16x16x32_bf16 v[50:53], v[202:205], v[210:213], v[50:53]
	v_mfma_f32_16x16x32_bf16 v[50:53], v[196:199], v[206:209], v[50:53]
	v_mfma_f32_16x16x32_bf16 v[34:37], v[196:199], v[214:217], v[34:37]
	v_mfma_f32_16x16x32_bf16 v[34:37], v[202:205], v[218:221], v[34:37]
	v_mfma_f32_16x16x32_bf16 v[18:21], v[202:205], v[226:229], v[18:21]
	v_mfma_f32_16x16x32_bf16 v[18:21], v[196:199], v[222:225], v[18:21]
	s_barrier
	s_setprio 0
	s_add_i32 s56, s56, 2
	s_add_u32 s54, s54, 0x100
	s_addc_u32 s55, s55, 0
	s_cmpk_gt_u32 s56, 0xa9
	s_mov_b64 s[40:41], s[48:49]
	s_cbranch_scc0 .LBB0_1731
	s_and_b64 vcc, exec, s[12:13]
	s_cbranch_vccz .LBB0_1734
	s_barrier

; #define PG8_STAGE(bufoff, gbase, voff) do { _Pragma("unroll") for (int _i = 0; _i < 2; ++_i) \
;         __builtin_amdgcn_global_load_lds((const unsigned*)((const char*)(gbase) + (voff)[_i]), (PG8_LAS unsigned*)(lds + (bufoff) + ldsw + _i * 8192), 16, 0, 0); } while (0)
; #define PG8_LDA(dst, b, h) do { _Pragma("unroll") for (int m = 0; m < 4; ++m) _Pragma("unroll") for (int k = 0; k < 2; ++k) dst[m][k] = *(const PG8_LAS bf16x8*)(lds + PG8_SA(b, h) + aoff + m * 2048 + k * 1024); } while (0)
; #define PG8_LDB(dst, b, h) do { _Pragma("unroll") for (int n = 0; n < 2; ++n) _Pragma("unroll") for (int k = 0; k < 2; ++k) dst[n][k] = *(const PG8_LAS bf16x8*)(lds + PG8_SB(b, h) + boff + n * 2048 + k * 1024); } while (0)
; #define PG8_MMA(ai, bj, At, Bt) do { __builtin_amdgcn_s_setprio(1); _Pragma("unroll") for (int m = 0; m < 4; ++m) _Pragma("unroll") for (int n = 0; n < 2; ++n) _Pragma("unroll") for (int k = 0; k < 2; ++k) \
;         acc[ai][bj][m][n] = __builtin_amdgcn_mfma_f32_16x16x32_bf16(Bt[n][k], At[m][k], acc[ai][bj][m][n], 0, 0, 0); __builtin_amdgcn_s_setprio(0); } while (0)
; #define PG8_WAIT_V(n) asm volatile("s_waitcnt vmcnt(" #n ")" ::: "memory")
; #define PG8_WAIT_L(n) asm volatile("s_waitcnt lgkmcnt(" #n ")" ::: "memory")
; template <class Epi, class Sched, bool ALIGN_EPI = false, bool SP2 = false>
; __device__ __forceinline__ void gemm_phase(PG8_LAS unsigned char* lds, const Gemm g, const Sched& S, const Epi& E) {
;     ...
;             const bool last = (t == nt - 2);
;             const char* a1 = cA + (size_t)(t + 1) * kstep;
;             const char* a2 = last ? nA : cA + (size_t)(t + 2) * kstep; const char* b2 = last ? nB : cB + (size_t)(t + 2) * kstep;
;             const char* a3 = a2 + kstep; const char* b3 = b2 + kstep;
;             if (last && has_next) S.a_ready(nxt);
;             if constexpr (SP2) {
;             PG8_LDB(B0, 0, 0); PG8_LDB(B1, 0, 1); PG8_SCHED; PG8_LDA(At, 0, 0); PG8_STAGE(PG8_SA(1, 1), a1 + hstep, voffA);
;             PG8_WAIT_V(8); PG8_WAIT_L(0); PG8_BAR; PG8_MMA(0, 0, At, B0); PG8_MMA(0, 1, At, B1); PG8_BAR; PG8_SCHED;
;             PG8_LDA(At, 0, 1); PG8_STAGE(PG8_SB(0, 0), b2, voffB); PG8_STAGE(PG8_SB(0, 1), b2 + hstep, voffB); PG8_STAGE(PG8_SA(0, 0), a2, voffA);
;             PG8_WAIT_V(8); PG8_WAIT_L(0); PG8_BAR; PG8_MMA(1, 0, At, B0); PG8_MMA(1, 1, At, B1); PG8_BAR; PG8_SCHED;
.LBB0_1746:
	ds_read_b128 v[140:143], v134
	ds_read_b128 v[144:147], v134 offset:1024
	ds_read_b128 v[148:151], v134 offset:2048
	ds_read_b128 v[152:155], v134 offset:3072
	ds_read_b128 v[156:159], v135
	ds_read_b128 v[160:163], v135 offset:1024
	ds_read_b128 v[164:167], v135 offset:2048
	ds_read_b128 v[168:171], v135 offset:3072
	s_add_i32 s36, s38, 2
	s_mov_b32 s37, s11
	s_or_b32 s10, s38, 1
	s_lshl_b64 s[40:41], s[36:37], 7
	s_cmp_lg_u32 s38, s42
	s_cselect_b32 s38, s40, 0
	s_cselect_b32 s37, s41, 0
	s_add_u32 s40, s6, s38
	s_addc_u32 s41, s7, s37
	s_add_u32 s38, s2, s38
	s_addc_u32 s39, s3, s37
	s_lshl_b64 s[52:53], s[10:11], 7
	s_add_u32 s52, s8, s52
	s_addc_u32 s53, s9, s53
	s_mov_b32 m0, s43
	v_lshl_add_u64 v[192:193], s[52:53], 0, v[128:129]
	ds_read_b128 v[172:175], v136
	ds_read_b128 v[176:179], v136 offset:1024
	ds_read_b128 v[180:183], v136 offset:2048
	ds_read_b128 v[184:187], v136 offset:3072
	ds_read_b128 v[188:191], v136 offset:4096
	ds_read_b128 v[196:199], v136 offset:5120
	ds_read_b128 v[202:205], v136 offset:6144
	ds_read_b128 v[206:209], v136 offset:7168
	global_load_lds_dwordx4 v[192:193], off
	v_lshl_add_u64 v[192:193], s[52:53], 0, v[130:131]
	s_mov_b32 m0, s44
	s_nop 0
	global_load_lds_dwordx4 v[192:193], off
	s_waitcnt vmcnt(8)
	s_waitcnt lgkmcnt(0)
	s_setprio 1
	s_barrier
	v_mfma_f32_16x16x32_bf16 v[124:127], v[140:143], v[172:175], v[124:127]
	v_mfma_f32_16x16x32_bf16 v[124:127], v[144:147], v[176:179], v[124:127]
	v_mfma_f32_16x16x32_bf16 v[116:119], v[144:147], v[184:187], v[116:119]
	v_mfma_f32_16x16x32_bf16 v[116:119], v[140:143], v[180:183], v[116:119]
	v_mfma_f32_16x16x32_bf16 v[104:107], v[140:143], v[188:191], v[104:107]
	v_mfma_f32_16x16x32_bf16 v[104:107], v[144:147], v[196:199], v[104:107]
	v_mfma_f32_16x16x32_bf16 v[88:91], v[144:147], v[206:209], v[88:91]
	v_mfma_f32_16x16x32_bf16 v[88:91], v[140:143], v[202:205], v[88:91]
	v_mfma_f32_16x16x32_bf16 v[80:83], v[148:151], v[202:205], v[80:83]
	v_mfma_f32_16x16x32_bf16 v[80:83], v[152:155], v[206:209], v[80:83]
	v_mfma_f32_16x16x32_bf16 v[120:123], v[152:155], v[176:179], v[120:123]
	v_mfma_f32_16x16x32_bf16 v[120:123], v[148:151], v[172:175], v[120:123]
	v_mfma_f32_16x16x32_bf16 v[112:115], v[148:151], v[180:183], v[112:115]
	v_mfma_f32_16x16x32_bf16 v[112:115], v[152:155], v[184:187], v[112:115]
	v_mfma_f32_16x16x32_bf16 v[96:99], v[152:155], v[196:199], v[96:99]
	v_mfma_f32_16x16x32_bf16 v[96:99], v[148:151], v[188:191], v[96:99]
	v_mfma_f32_16x16x32_bf16 v[76:79], v[156:159], v[188:191], v[76:79]
	v_mfma_f32_16x16x32_bf16 v[76:79], v[160:163], v[196:199], v[76:79]
	v_mfma_f32_16x16x32_bf16 v[108:111], v[160:163], v[176:179], v[108:111]
	v_mfma_f32_16x16x32_bf16 v[108:111], v[156:159], v[172:175], v[108:111]
	v_mfma_f32_16x16x32_bf16 v[92:95], v[156:159], v[180:183], v[92:95]
	v_mfma_f32_16x16x32_bf16 v[92:95], v[160:163], v[184:187], v[92:95]
	v_mfma_f32_16x16x32_bf16 v[68:71], v[160:163], v[206:209], v[68:71]
	v_mfma_f32_16x16x32_bf16 v[68:71], v[156:159], v[202:205], v[68:71]
	v_mfma_f32_16x16x32_bf16 v[64:67], v[164:167], v[202:205], v[64:67]
	v_mfma_f32_16x16x32_bf16 v[64:67], v[168:171], v[206:209], v[64:67]
	v_mfma_f32_16x16x32_bf16 v[100:103], v[168:171], v[176:179], v[100:103]
	v_mfma_f32_16x16x32_bf16 v[100:103], v[164:167], v[172:175], v[100:103]
	v_mfma_f32_16x16x32_bf16 v[84:87], v[164:167], v[180:183], v[84:87]
	v_mfma_f32_16x16x32_bf16 v[84:87], v[168:171], v[184:187], v[84:87]
	v_mfma_f32_16x16x32_bf16 v[72:75], v[168:171], v[196:199], v[72:75]
	v_mfma_f32_16x16x32_bf16 v[72:75], v[164:167], v[188:191], v[72:75]
	s_barrier
	s_setprio 0
	s_mov_b32 m0, s31
	v_lshl_add_u64 v[192:193], s[38:39], 0, v[128:129]
	s_add_u32 s52, s38, 0x2b0000
	ds_read_b128 v[172:175], v136 offset:16384
	ds_read_b128 v[176:179], v136 offset:17408
	ds_read_b128 v[180:183], v136 offset:18432
	ds_read_b128 v[184:187], v136 offset:19456
	ds_read_b128 v[188:191], v136 offset:20480
	ds_read_b128 v[196:199], v136 offset:21504
	ds_read_b128 v[202:205], v136 offset:22528
	ds_read_b128 v[206:209], v136 offset:23552
	global_load_lds_dwordx4 v[192:193], off
	v_lshl_add_u64 v[194:195], s[38:39], 0, v[130:131]
	s_mov_b32 m0, s45
	s_addc_u32 s53, s39, 0
	global_load_lds_dwordx4 v[194:195], off
	v_lshl_add_u64 v[210:211], s[52:53], 0, v[128:129]
	s_mov_b32 m0, s46
	v_lshl_add_u64 v[212:213], s[40:41], 0, v[130:131]
	global_load_lds_dwordx4 v[210:211], off
	v_lshl_add_u64 v[210:211], s[52:53], 0, v[130:131]
	s_mov_b32 m0, s47
	s_nop 0
	global_load_lds_dwordx4 v[210:211], off
	v_lshl_add_u64 v[210:211], s[40:41], 0, v[128:129]
	s_mov_b32 m0, s26
	s_nop 0
	global_load_lds_dwordx4 v[210:211], off
	s_mov_b32 m0, s27
	s_nop 0
	global_load_lds_dwordx4 v[212:213], off
	s_waitcnt vmcnt(8)
	s_waitcnt lgkmcnt(0)
	s_setprio 1
	s_barrier
; #define PG8_STAGE(bufoff, gbase, voff) do { _Pragma("unroll") for (int _i = 0; _i < 2; ++_i) \
;         __builtin_amdgcn_global_load_lds((const unsigned*)((const char*)(gbase) + (voff)[_i]), (PG8_LAS unsigned*)(lds + (bufoff) + ldsw + _i * 8192), 16, 0, 0); } while (0)
; #define PG8_LDA(dst, b, h) do { _Pragma("unroll") for (int m = 0; m < 4; ++m) _Pragma("unroll") for (int k = 0; k < 2; ++k) dst[m][k] = *(const PG8_LAS bf16x8*)(lds + PG8_SA(b, h) + aoff + m * 2048 + k * 1024); } while (0)
; #define PG8_LDB(dst, b, h) do { _Pragma("unroll") for (int n = 0; n < 2; ++n) _Pragma("unroll") for (int k = 0; k < 2; ++k) dst[n][k] = *(const PG8_LAS bf16x8*)(lds + PG8_SB(b, h) + boff + n * 2048 + k * 1024); } while (0)
; #define PG8_MMA(ai, bj, At, Bt) do { __builtin_amdgcn_s_setprio(1); _Pragma("unroll") for (int m = 0; m < 4; ++m) _Pragma("unroll") for (int n = 0; n < 2; ++n) _Pragma("unroll") for (int k = 0; k < 2; ++k) \
;         acc[ai][bj][m][n] = __builtin_amdgcn_mfma_f32_16x16x32_bf16(Bt[n][k], At[m][k], acc[ai][bj][m][n], 0, 0, 0); __builtin_amdgcn_s_setprio(0); } while (0)
; #define PG8_WAIT_V(n) asm volatile("s_waitcnt vmcnt(" #n ")" ::: "memory")
; #define PG8_WAIT_L(n) asm volatile("s_waitcnt lgkmcnt(" #n ")" ::: "memory")
; #define PG8_BAR __builtin_amdgcn_s_barrier()
; #define PG8_SCHED __builtin_amdgcn_sched_barrier(0)
; template <class Epi, class Sched, bool ALIGN_EPI = false, bool SP2 = false>
; __device__ __forceinline__ void gemm_phase(PG8_LAS unsigned char* lds, const Gemm g, const Sched& S, const Epi& E) {
;     ...
;             PG8_WAIT_V(8); PG8_WAIT_L(0); PG8_BAR; PG8_MMA(1, 0, At, B0); PG8_MMA(1, 1, At, B1); PG8_BAR; PG8_SCHED;
;             PG8_LDB(B0, 1, 0); PG8_LDB(B1, 1, 1); PG8_SCHED; PG8_LDA(At, 1, 0); PG8_STAGE(PG8_SA(0, 1), a2 + hstep, voffA);
;             PG8_WAIT_V(8); PG8_WAIT_L(0); PG8_BAR; PG8_MMA(0, 0, At, B0); PG8_MMA(0, 1, At, B1); PG8_BAR; PG8_SCHED;
	v_mfma_f32_16x16x32_bf16 v[60:63], v[140:143], v[172:175], v[60:63]
	v_mfma_f32_16x16x32_bf16 v[60:63], v[144:147], v[176:179], v[60:63]
	v_mfma_f32_16x16x32_bf16 v[52:55], v[144:147], v[184:187], v[52:55]
	v_mfma_f32_16x16x32_bf16 v[52:55], v[140:143], v[180:183], v[52:55]
	v_mfma_f32_16x16x32_bf16 v[40:43], v[140:143], v[188:191], v[40:43]
	v_mfma_f32_16x16x32_bf16 v[40:43], v[144:147], v[196:199], v[40:43]
	v_mfma_f32_16x16x32_bf16 v[24:27], v[144:147], v[206:209], v[24:27]
	v_mfma_f32_16x16x32_bf16 v[24:27], v[140:143], v[202:205], v[24:27]
	v_mfma_f32_16x16x32_bf16 v[16:19], v[148:151], v[202:205], v[16:19]
	v_mfma_f32_16x16x32_bf16 v[16:19], v[152:155], v[206:209], v[16:19]
	v_mfma_f32_16x16x32_bf16 v[56:59], v[152:155], v[176:179], v[56:59]
	v_mfma_f32_16x16x32_bf16 v[56:59], v[148:151], v[172:175], v[56:59]
	v_mfma_f32_16x16x32_bf16 v[48:51], v[148:151], v[180:183], v[48:51]
	v_mfma_f32_16x16x32_bf16 v[48:51], v[152:155], v[184:187], v[48:51]
	v_mfma_f32_16x16x32_bf16 v[32:35], v[152:155], v[196:199], v[32:35]
	v_mfma_f32_16x16x32_bf16 v[32:35], v[148:151], v[188:191], v[32:35]
	v_mfma_f32_16x16x32_bf16 v[12:15], v[156:159], v[188:191], v[12:15]
	v_mfma_f32_16x16x32_bf16 v[12:15], v[160:163], v[196:199], v[12:15]
	v_mfma_f32_16x16x32_bf16 v[44:47], v[160:163], v[176:179], v[44:47]
	v_mfma_f32_16x16x32_bf16 v[44:47], v[156:159], v[172:175], v[44:47]
	v_mfma_f32_16x16x32_bf16 v[28:31], v[156:159], v[180:183], v[28:31]
	v_mfma_f32_16x16x32_bf16 v[28:31], v[160:163], v[184:187], v[28:31]
	v_mfma_f32_16x16x32_bf16 v[4:7], v[160:163], v[206:209], v[4:7]
	v_mfma_f32_16x16x32_bf16 v[4:7], v[156:159], v[202:205], v[4:7]
	v_mfma_f32_16x16x32_bf16 v[0:3], v[164:167], v[202:205], v[0:3]
	v_mfma_f32_16x16x32_bf16 v[0:3], v[168:171], v[206:209], v[0:3]
	v_mfma_f32_16x16x32_bf16 v[36:39], v[168:171], v[176:179], v[36:39]
	v_mfma_f32_16x16x32_bf16 v[36:39], v[164:167], v[172:175], v[36:39]
	v_mfma_f32_16x16x32_bf16 v[20:23], v[164:167], v[180:183], v[20:23]
	v_mfma_f32_16x16x32_bf16 v[20:23], v[168:171], v[184:187], v[20:23]
	v_mfma_f32_16x16x32_bf16 v[8:11], v[168:171], v[196:199], v[8:11]
	v_mfma_f32_16x16x32_bf16 v[8:11], v[164:167], v[188:191], v[8:11]
	s_barrier
	s_setprio 0
	ds_read_b128 v[140:143], v137
	ds_read_b128 v[144:147], v137 offset:1024
	ds_read_b128 v[148:151], v137 offset:2048
	ds_read_b128 v[152:155], v137 offset:3072
	ds_read_b128 v[156:159], v138
	ds_read_b128 v[160:163], v138 offset:1024
	ds_read_b128 v[164:167], v138 offset:2048
	ds_read_b128 v[168:171], v138 offset:3072
	s_add_u32 s40, s40, 0x2b0000
	s_addc_u32 s41, s41, 0
	s_mov_b32 m0, s28
	v_lshl_add_u64 v[214:215], s[40:41], 0, v[128:129]
	ds_read_b128 v[172:175], v136 offset:32768
	ds_read_b128 v[176:179], v136 offset:33792
	ds_read_b128 v[180:183], v136 offset:34816
	ds_read_b128 v[184:187], v136 offset:35840
	ds_read_b128 v[188:191], v136 offset:36864
	ds_read_b128 v[196:199], v136 offset:37888
	ds_read_b128 v[202:205], v136 offset:38912
	ds_read_b128 v[206:209], v136 offset:39936
	global_load_lds_dwordx4 v[214:215], off
	v_lshl_add_u64 v[214:215], s[40:41], 0, v[130:131]
	s_mov_b32 m0, s30
	s_nop 0
	global_load_lds_dwordx4 v[214:215], off
	s_waitcnt vmcnt(8)
	s_waitcnt lgkmcnt(0)
	s_setprio 1
	s_barrier
	v_mfma_f32_16x16x32_bf16 v[124:127], v[140:143], v[172:175], v[124:127]
	v_mfma_f32_16x16x32_bf16 v[124:127], v[144:147], v[176:179], v[124:127]
	v_mfma_f32_16x16x32_bf16 v[116:119], v[144:147], v[184:187], v[116:119]
	v_mfma_f32_16x16x32_bf16 v[116:119], v[140:143], v[180:183], v[116:119]
	v_mfma_f32_16x16x32_bf16 v[104:107], v[140:143], v[188:191], v[104:107]
	v_mfma_f32_16x16x32_bf16 v[104:107], v[144:147], v[196:199], v[104:107]
	v_mfma_f32_16x16x32_bf16 v[88:91], v[144:147], v[206:209], v[88:91]
	v_mfma_f32_16x16x32_bf16 v[88:91], v[140:143], v[202:205], v[88:91]
	v_mfma_f32_16x16x32_bf16 v[80:83], v[148:151], v[202:205], v[80:83]
	v_mfma_f32_16x16x32_bf16 v[80:83], v[152:155], v[206:209], v[80:83]
	v_mfma_f32_16x16x32_bf16 v[120:123], v[152:155], v[176:179], v[120:123]
	v_mfma_f32_16x16x32_bf16 v[120:123], v[148:151], v[172:175], v[120:123]
	v_mfma_f32_16x16x32_bf16 v[112:115], v[148:151], v[180:183], v[112:115]
	v_mfma_f32_16x16x32_bf16 v[112:115], v[152:155], v[184:187], v[112:115]
	v_mfma_f32_16x16x32_bf16 v[96:99], v[152:155], v[196:199], v[96:99]
	v_mfma_f32_16x16x32_bf16 v[96:99], v[148:151], v[188:191], v[96:99]
	v_mfma_f32_16x16x32_bf16 v[76:79], v[156:159], v[188:191], v[76:79]
	v_mfma_f32_16x16x32_bf16 v[76:79], v[160:163], v[196:199], v[76:79]
	v_mfma_f32_16x16x32_bf16 v[108:111], v[160:163], v[176:179], v[108:111]
	v_mfma_f32_16x16x32_bf16 v[108:111], v[156:159], v[172:175], v[108:111]
	v_mfma_f32_16x16x32_bf16 v[92:95], v[156:159], v[180:183], v[92:95]
	v_mfma_f32_16x16x32_bf16 v[92:95], v[160:163], v[184:187], v[92:95]
	v_mfma_f32_16x16x32_bf16 v[68:71], v[160:163], v[206:209], v[68:71]
	v_mfma_f32_16x16x32_bf16 v[68:71], v[156:159], v[202:205], v[68:71]
	v_mfma_f32_16x16x32_bf16 v[64:67], v[164:167], v[202:205], v[64:67]
	v_mfma_f32_16x16x32_bf16 v[64:67], v[168:171], v[206:209], v[64:67]
	v_mfma_f32_16x16x32_bf16 v[100:103], v[168:171], v[176:179], v[100:103]
	v_mfma_f32_16x16x32_bf16 v[100:103], v[164:167], v[172:175], v[100:103]
	v_mfma_f32_16x16x32_bf16 v[84:87], v[164:167], v[180:183], v[84:87]
	v_mfma_f32_16x16x32_bf16 v[84:87], v[168:171], v[184:187], v[84:87]
	v_mfma_f32_16x16x32_bf16 v[72:75], v[168:171], v[196:199], v[72:75]
	v_mfma_f32_16x16x32_bf16 v[72:75], v[164:167], v[188:191], v[72:75]
	s_barrier
; #define PG8_STAGE(bufoff, gbase, voff) do { _Pragma("unroll") for (int _i = 0; _i < 2; ++_i) \
;         __builtin_amdgcn_global_load_lds((const unsigned*)((const char*)(gbase) + (voff)[_i]), (PG8_LAS unsigned*)(lds + (bufoff) + ldsw + _i * 8192), 16, 0, 0); } while (0)
; #define PG8_LDA(dst, b, h) do { _Pragma("unroll") for (int m = 0; m < 4; ++m) _Pragma("unroll") for (int k = 0; k < 2; ++k) dst[m][k] = *(const PG8_LAS bf16x8*)(lds + PG8_SA(b, h) + aoff + m * 2048 + k * 1024); } while (0)
; #define PG8_MMA(ai, bj, At, Bt) do { __builtin_amdgcn_s_setprio(1); _Pragma("unroll") for (int m = 0; m < 4; ++m) _Pragma("unroll") for (int n = 0; n < 2; ++n) _Pragma("unroll") for (int k = 0; k < 2; ++k) \
;         acc[ai][bj][m][n] = __builtin_amdgcn_mfma_f32_16x16x32_bf16(Bt[n][k], At[m][k], acc[ai][bj][m][n], 0, 0, 0); __builtin_amdgcn_s_setprio(0); } while (0)
; #define PG8_WAIT_V(n) asm volatile("s_waitcnt vmcnt(" #n ")" ::: "memory")
; #define PG8_WAIT_L(n) asm volatile("s_waitcnt lgkmcnt(" #n ")" ::: "memory")
; #define PG8_BAR __builtin_amdgcn_s_barrier()
; #define PG8_SCHED __builtin_amdgcn_sched_barrier(0)
; template <class Epi, class Sched, bool ALIGN_EPI = false, bool SP2 = false>
; __device__ __forceinline__ void gemm_phase(PG8_LAS unsigned char* lds, const Gemm g, const Sched& S, const Epi& E) {
;     ...
;         for (int t = 0; t < nt; t += 2) {
;     ...
;             PG8_LDA(At, 1, 1); PG8_STAGE(PG8_SB(1, 0), b3, voffB); PG8_STAGE(PG8_SB(1, 1), b3 + hstep, voffB); PG8_STAGE(PG8_SA(1, 0), a3, voffA);
;             PG8_WAIT_V(8); PG8_WAIT_L(0); PG8_BAR; PG8_MMA(1, 0, At, B0); PG8_MMA(1, 1, At, B1); PG8_BAR; PG8_SCHED;
;     ...
;         if constexpr (ALIGN_EPI) { if (wr == 0) PG8_BAR; }
	s_setprio 0
	s_mov_b32 m0, s48
	v_lshl_add_u64 v[192:193], v[192:193], 0, s[12:13]
	s_add_u32 s38, s38, 0x2b0080
	ds_read_b128 v[172:175], v136 offset:49152
	ds_read_b128 v[176:179], v136 offset:50176
	ds_read_b128 v[180:183], v136 offset:51200
	ds_read_b128 v[184:187], v136 offset:52224
	ds_read_b128 v[188:191], v136 offset:53248
	ds_read_b128 v[196:199], v136 offset:54272
	ds_read_b128 v[202:205], v136 offset:55296
	ds_read_b128 v[206:209], v136 offset:56320
	global_load_lds_dwordx4 v[192:193], off
	v_lshl_add_u64 v[192:193], v[194:195], 0, s[12:13]
	s_mov_b32 m0, s49
	s_addc_u32 s39, s39, 0
	global_load_lds_dwordx4 v[192:193], off
	v_lshl_add_u64 v[192:193], s[38:39], 0, v[128:129]
	s_mov_b32 m0, s50
	s_nop 0
	global_load_lds_dwordx4 v[192:193], off
	v_lshl_add_u64 v[192:193], s[38:39], 0, v[130:131]
	s_mov_b32 m0, s51
	s_nop 0
	global_load_lds_dwordx4 v[192:193], off
	v_lshl_add_u64 v[192:193], v[210:211], 0, s[12:13]
	s_mov_b32 m0, s34
	s_nop 0
	global_load_lds_dwordx4 v[192:193], off
	v_lshl_add_u64 v[192:193], v[212:213], 0, s[12:13]
	s_mov_b32 m0, s35
	s_nop 0
	global_load_lds_dwordx4 v[192:193], off
	s_waitcnt vmcnt(8)
	s_waitcnt lgkmcnt(0)
	s_setprio 1
	s_barrier
	v_mfma_f32_16x16x32_bf16 v[60:63], v[140:143], v[172:175], v[60:63]
	v_mfma_f32_16x16x32_bf16 v[60:63], v[144:147], v[176:179], v[60:63]
	v_mfma_f32_16x16x32_bf16 v[52:55], v[144:147], v[184:187], v[52:55]
	v_mfma_f32_16x16x32_bf16 v[52:55], v[140:143], v[180:183], v[52:55]
	v_mfma_f32_16x16x32_bf16 v[40:43], v[140:143], v[188:191], v[40:43]
	v_mfma_f32_16x16x32_bf16 v[40:43], v[144:147], v[196:199], v[40:43]
	v_mfma_f32_16x16x32_bf16 v[24:27], v[144:147], v[206:209], v[24:27]
	v_mfma_f32_16x16x32_bf16 v[24:27], v[140:143], v[202:205], v[24:27]
	v_mfma_f32_16x16x32_bf16 v[16:19], v[148:151], v[202:205], v[16:19]
	v_mfma_f32_16x16x32_bf16 v[16:19], v[152:155], v[206:209], v[16:19]
	v_mfma_f32_16x16x32_bf16 v[56:59], v[152:155], v[176:179], v[56:59]
	v_mfma_f32_16x16x32_bf16 v[56:59], v[148:151], v[172:175], v[56:59]
	v_mfma_f32_16x16x32_bf16 v[48:51], v[148:151], v[180:183], v[48:51]
	v_mfma_f32_16x16x32_bf16 v[48:51], v[152:155], v[184:187], v[48:51]
	v_mfma_f32_16x16x32_bf16 v[32:35], v[152:155], v[196:199], v[32:35]
	v_mfma_f32_16x16x32_bf16 v[32:35], v[148:151], v[188:191], v[32:35]
	v_mfma_f32_16x16x32_bf16 v[12:15], v[156:159], v[188:191], v[12:15]
	v_mfma_f32_16x16x32_bf16 v[12:15], v[160:163], v[196:199], v[12:15]
	v_mfma_f32_16x16x32_bf16 v[44:47], v[160:163], v[176:179], v[44:47]
	v_mfma_f32_16x16x32_bf16 v[44:47], v[156:159], v[172:175], v[44:47]
	v_mfma_f32_16x16x32_bf16 v[28:31], v[156:159], v[180:183], v[28:31]
	v_mfma_f32_16x16x32_bf16 v[28:31], v[160:163], v[184:187], v[28:31]
	v_mfma_f32_16x16x32_bf16 v[4:7], v[160:163], v[206:209], v[4:7]
	v_mfma_f32_16x16x32_bf16 v[4:7], v[156:159], v[202:205], v[4:7]
	v_mfma_f32_16x16x32_bf16 v[0:3], v[164:167], v[202:205], v[0:3]
	v_mfma_f32_16x16x32_bf16 v[0:3], v[168:171], v[206:209], v[0:3]
	v_mfma_f32_16x16x32_bf16 v[36:39], v[168:171], v[176:179], v[36:39]
	v_mfma_f32_16x16x32_bf16 v[36:39], v[164:167], v[172:175], v[36:39]
	v_mfma_f32_16x16x32_bf16 v[20:23], v[164:167], v[180:183], v[20:23]
	v_mfma_f32_16x16x32_bf16 v[20:23], v[168:171], v[184:187], v[20:23]
	v_mfma_f32_16x16x32_bf16 v[8:11], v[168:171], v[196:199], v[8:11]
	v_mfma_f32_16x16x32_bf16 v[8:11], v[164:167], v[188:191], v[8:11]
	s_barrier
	s_setprio 0
	s_cmp_ge_u32 s36, s5
	s_mov_b32 s38, s36
	s_cbranch_scc0 .LBB0_1746
	s_cmpk_lt_u32 s16, 0x100
	s_cbranch_scc0 .LBB0_1749
	s_barrier
